# speedup vs baseline: 1.0073x; 1.0073x over previous
; #define WAIT_V(n) asm volatile("s_waitcnt vmcnt(" #n ")" ::: "memory")
; #define BAR __builtin_amdgcn_s_barrier()
;     ...
;     { int _r, _c; stage_rc(tix * 16, _r, _c); boff0 = (unsigned)(_r * K + _c) * 2u; stage_rc(tix * 16 + 8192, _r, _c); boff1 = (unsigned)(_r * K + _c) * 2u; }
;     int wgid = is_slice ? 0 : tile;
;     { int q = nwg / NXCD, r = nwg % NXCD, xcd = wgid % NXCD, off = wgid / NXCD;
;       wgid = (xcd < r ? xcd * (q + 1) : r * (q + 1) + (xcd - r) * q) + off; }
;     const int nig = WGM * nN, gid = wgid / nig, fm = gid * WGM, gsz = min(nM - fm, WGM);
;     int pm = fm + ((wgid % nig) % gsz), pn = (wgid % nig) / gsz;
;     if (is_slice) { const int u = tile - nwg; pn = u % nN; slice = u / nN; pm = nM; nt = (K / BK) / nslice; kt0 = slice * nt; }
;     const int brow = pm * BM, bcol = pn * BM;
;     f32x4 acc[2][2][4][2] = {};
;     bf16x8 At[4][2], B0[2][2], B1[2][2];
;     STAGE(SB(0, 0), Bt, bcol, 0); STAGE(SA(0, 0), A, brow, 0);
;     STAGE(SB(0, 1), Bt, bcol + HALF, 0); STAGE(SA(0, 1), A, brow + HALF, 0);
;     if (wr == 1) BAR;
;     WAIT_V(4); BAR;
;     STAGE(SB(1, 0), Bt, bcol, 1); STAGE(SA(1, 0), A, brow, 1); STAGE(SB(1, 1), Bt, bcol + HALF, 1);
;     WAIT_V(6); BAR;
.LBB0_97:
	s_or_b32 s34, s48, 1
	s_mov_b32 s35, s49
	s_lshl_b64 s[42:43], s[34:35], 6
	s_add_u32 s34, s42, s6
	s_addc_u32 s35, s43, s4
	s_lshl_b64 s[34:35], s[34:35], 1
	s_add_u32 s44, s24, s34
	s_addc_u32 s45, s25, s35
	s_add_i32 s34, s15, 0x18000
	s_add_i32 s35, s15, 0x1a000
	s_add_u32 s4, s42, s5
	s_addc_u32 s5, s43, s7
	s_lshl_b64 s[4:5], s[4:5], 1
	v_mov_b32_e32 v141, v1
	s_waitcnt vmcnt(4)
	s_barrier
	s_mov_b32 m0, s34
	v_lshl_add_u64 v[4:5], s[44:45], 0, v[0:1]
	s_add_u32 s4, s22, s4
	global_load_lds_dwordx4 v[4:5], off
	v_lshl_add_u64 v[4:5], s[44:45], 0, v[140:141]
	s_mov_b32 m0, s35
	s_addc_u32 s5, s23, s5
	s_add_i32 s37, s15, 0x8000
	global_load_lds_dwordx4 v[4:5], off
	s_mov_b32 m0, s37
	v_lshl_add_u64 v[4:5], s[4:5], 0, v[0:1]
	s_waitcnt lgkmcnt(0)
	s_add_i32 s38, s15, 0xa000
	global_load_lds_dwordx4 v[4:5], off
	v_lshl_add_u64 v[4:5], s[4:5], 0, v[140:141]
	s_add_u32 s4, s42, s39
	s_addc_u32 s5, s43, s40
	s_lshl_b64 s[4:5], s[4:5], 1
	s_add_u32 s4, s24, s4
	s_mov_b32 m0, s38
	s_addc_u32 s5, s25, s5
	s_add_i32 s41, s15, 0x1c000
	global_load_lds_dwordx4 v[4:5], off
	s_mov_b32 m0, s41
	v_lshl_add_u64 v[4:5], s[4:5], 0, v[0:1]
	s_add_i32 s42, s15, 0x1e000
	global_load_lds_dwordx4 v[4:5], off
	v_lshl_add_u64 v[4:5], s[4:5], 0, v[140:141]
	s_mov_b32 m0, s42
	v_and_b32_e32 v3, 15, v2
	global_load_lds_dwordx4 v[4:5], off
	v_and_b32_e32 v6, 48, v2
	v_lshlrev_b32_e32 v2, 2, v2
	v_lshlrev_b32_e32 v4, 6, v3
	v_and_b32_e32 v2, 32, v2
	v_bitop3_b32 v142, v4, v2, v6 bitop3:0x36
	v_or_b32_e32 v2, s33, v3
	v_lshlrev_b32_e32 v4, 6, v2
	v_lshlrev_b32_e32 v2, 2, v2
	v_and_b32_e32 v4, 0x3c0, v4
	v_and_b32_e32 v2, 32, v2
	v_readlane_b32 s4, v245, 36
	s_add_i32 s43, s14, -2
	s_mul_i32 s40, s29, 0x2c00
	v_bitop3_b32 v4, v4, v2, v6 bitop3:0x36
	v_or_b32_e32 v2, s4, v3
	s_mul_hi_i32 s39, s29, 0x2c00
	s_add_u32 s55, s22, s40
	v_lshlrev_b32_e32 v5, 6, v2
	v_lshlrev_b32_e32 v2, 2, v2
	s_addc_u32 s57, s23, s39
	v_and_b32_e32 v5, 0x3c0, v5
	v_and_b32_e32 v2, 32, v2
	v_readlane_b32 s4, v245, 37
	s_ashr_i32 s7, s6, 31
	v_bitop3_b32 v5, v5, v2, v6 bitop3:0x36
	v_or_b32_e32 v2, s4, v3
	s_lshl_b64 s[4:5], s[48:49], 7
	s_lshl_b64 s[6:7], s[6:7], 1
	s_add_u32 s6, s24, s6
	v_lshlrev_b32_e32 v7, 6, v2
	v_lshlrev_b32_e32 v2, 2, v2
	s_addc_u32 s7, s25, s7
	s_mul_i32 s44, s20, 0x2c00
	v_and_b32_e32 v7, 0x3c0, v7
	v_and_b32_e32 v2, 32, v2
	s_mul_hi_i32 s45, s20, 0x2c00
	s_add_u32 s44, s22, s44
	v_bitop3_b32 v7, v7, v2, v6 bitop3:0x36
	v_or_b32_e32 v2, s85, v3
	s_addc_u32 s45, s23, s45
	s_mul_i32 s50, s10, 0x2c00
	v_readlane_b32 s59, v244, 19
	v_lshlrev_b32_e32 v3, 6, v2
	v_lshlrev_b32_e32 v2, 2, v2
	s_mul_hi_i32 s51, s10, 0x2c00
	s_add_u32 s50, s24, s50
	v_add_u32_e32 v133, s59, v4
	v_readlane_b32 s59, v244, 20
	s_waitcnt vmcnt(6)
	v_and_b32_e32 v3, 0x3c0, v3
	v_and_b32_e32 v2, 32, v2
	s_addc_u32 s51, s25, s51
	v_add_u32_e32 v134, s59, v5
	v_readlane_b32 s59, v244, 21
	v_bitop3_b32 v3, v3, v2, v6 bitop3:0x36
	s_add_u32 s55, s55, 0x80
	v_mov_b32_e32 v2, 0
	v_add_u32_e32 v137, s59, v7
	v_readlane_b32 s59, v244, 22
	s_addc_u32 s57, s57, 0
	s_mov_b32 s58, 0
	v_add_u32_e32 v139, s59, v3
	v_mov_b32_e32 v3, v2
	v_mov_b32_e32 v4, v2
	v_mov_b32_e32 v5, v2
	v_mov_b32_e32 v6, v2
	v_mov_b32_e32 v7, v2
	v_mov_b32_e32 v8, v2
	v_mov_b32_e32 v9, v2
	v_mov_b32_e32 v10, v2
	v_mov_b32_e32 v11, v2
	v_mov_b32_e32 v12, v2
	v_mov_b32_e32 v13, v2
	v_mov_b32_e32 v14, v2
	v_mov_b32_e32 v15, v2
	v_mov_b32_e32 v16, v2
	v_mov_b32_e32 v17, v2
	v_mov_b32_e32 v18, v2
	v_mov_b32_e32 v19, v2
	v_mov_b32_e32 v20, v2
	v_mov_b32_e32 v21, v2
	v_mov_b32_e32 v22, v2
	v_mov_b32_e32 v23, v2
	v_mov_b32_e32 v24, v2
	v_mov_b32_e32 v25, v2
	v_mov_b32_e32 v26, v2
	v_mov_b32_e32 v27, v2
	v_mov_b32_e32 v28, v2
	v_mov_b32_e32 v29, v2
	v_mov_b32_e32 v30, v2
	v_mov_b32_e32 v31, v2
	v_mov_b32_e32 v32, v2
	v_mov_b32_e32 v33, v2
	v_mov_b32_e32 v34, v2
	v_mov_b32_e32 v35, v2
	v_mov_b32_e32 v36, v2
	v_mov_b32_e32 v37, v2
	v_mov_b32_e32 v38, v2
	v_mov_b32_e32 v39, v2
	v_mov_b32_e32 v40, v2
	v_mov_b32_e32 v41, v2
	v_mov_b32_e32 v42, v2
	v_mov_b32_e32 v43, v2
	v_mov_b32_e32 v44, v2
	v_mov_b32_e32 v45, v2
	v_mov_b32_e32 v46, v2
	v_mov_b32_e32 v47, v2
	v_mov_b32_e32 v48, v2
	v_mov_b32_e32 v49, v2
	v_mov_b32_e32 v50, v2
	v_mov_b32_e32 v51, v2
	v_mov_b32_e32 v52, v2
	v_mov_b32_e32 v53, v2
	v_mov_b32_e32 v54, v2
	v_mov_b32_e32 v55, v2
	v_mov_b32_e32 v56, v2
	v_mov_b32_e32 v57, v2
	v_mov_b32_e32 v58, v2
	v_mov_b32_e32 v59, v2
	v_mov_b32_e32 v60, v2
	v_mov_b32_e32 v61, v2
	v_mov_b32_e32 v62, v2
	v_mov_b32_e32 v63, v2
	v_mov_b32_e32 v64, v2
	v_mov_b32_e32 v65, v2
	v_mov_b32_e32 v66, v2
	v_mov_b32_e32 v67, v2
	v_mov_b32_e32 v68, v2
	v_mov_b32_e32 v69, v2
	v_mov_b32_e32 v70, v2
	v_mov_b32_e32 v71, v2
	v_mov_b32_e32 v72, v2
	v_mov_b32_e32 v73, v2
	v_mov_b32_e32 v74, v2
	v_mov_b32_e32 v75, v2
	v_mov_b32_e32 v76, v2
	v_mov_b32_e32 v77, v2
	v_mov_b32_e32 v78, v2
	v_mov_b32_e32 v79, v2
	v_mov_b32_e32 v80, v2
	v_mov_b32_e32 v81, v2
	v_mov_b32_e32 v82, v2
	v_mov_b32_e32 v83, v2
	v_mov_b32_e32 v84, v2
	v_mov_b32_e32 v85, v2
	v_mov_b32_e32 v86, v2
	v_mov_b32_e32 v87, v2
	v_mov_b32_e32 v88, v2
	v_mov_b32_e32 v89, v2
	v_mov_b32_e32 v90, v2
	v_mov_b32_e32 v91, v2
	v_mov_b32_e32 v92, v2
	v_mov_b32_e32 v93, v2
	v_mov_b32_e32 v94, v2
	v_mov_b32_e32 v95, v2
	v_mov_b32_e32 v96, v2
	v_mov_b32_e32 v97, v2
	v_mov_b32_e32 v98, v2
	v_mov_b32_e32 v99, v2
	v_mov_b32_e32 v100, v2
	v_mov_b32_e32 v101, v2
	v_mov_b32_e32 v102, v2
	v_mov_b32_e32 v103, v2
	v_mov_b32_e32 v104, v2
	v_mov_b32_e32 v105, v2
	v_mov_b32_e32 v106, v2
	v_mov_b32_e32 v107, v2
	v_mov_b32_e32 v108, v2
	v_mov_b32_e32 v109, v2
	v_mov_b32_e32 v110, v2
	v_mov_b32_e32 v111, v2
	v_mov_b32_e32 v112, v2
	v_mov_b32_e32 v113, v2
	v_mov_b32_e32 v114, v2
	v_mov_b32_e32 v115, v2
	v_mov_b32_e32 v116, v2
	v_mov_b32_e32 v117, v2
	v_mov_b32_e32 v118, v2
	v_mov_b32_e32 v119, v2
	v_mov_b32_e32 v120, v2
	v_mov_b32_e32 v121, v2
	v_mov_b32_e32 v122, v2
	v_mov_b32_e32 v123, v2
	v_mov_b32_e32 v124, v2
	v_mov_b32_e32 v125, v2
	v_mov_b32_e32 v126, v2
	v_mov_b32_e32 v127, v2
	v_mov_b32_e32 v128, v2
	v_mov_b32_e32 v129, v2
	v_readlane_b32 vcc_lo, v245, 30
	s_nop 0
	s_cmpk_lt_u32 vcc_lo, 0x1000
	s_cbranch_scc1 .Lgp_98
	s_setprio 1

; #define LDA(dst, b, h) for (int m = 0; m < 4; ++m) for (int k = 0; k < 2; ++k) \
;     dst[m][k] = *reinterpret_cast<const bf16x8*>((char*)SA(b, h) + lds_byte(wr * 64 + m * 16 + fr, k * 32 + fq * 8))
; #define LDB(dst, b, h) for (int n = 0; n < 2; ++n) for (int k = 0; k < 2; ++k) \
;     dst[n][k] = *reinterpret_cast<const bf16x8*>((char*)SB(b, h) + lds_byte(wc * 32 + n * 16 + fr, k * 32 + fq * 8))
; #define MMA(ai, bj, At, Bt_) do { __builtin_amdgcn_s_setprio(1); \
;     for (int m = 0; m < 4; ++m) for (int n = 0; n < 2; ++n) for (int k = 0; k < 2; ++k) \
;       acc[ai][bj][m][n] = __builtin_amdgcn_mfma_f32_16x16x32_bf16(At[m][k], Bt_[n][k], acc[ai][bj][m][n], 0, 0, 0); \
;     __builtin_amdgcn_s_setprio(0); } while (0)
; #define WAIT_L(n) asm volatile("s_waitcnt lgkmcnt(" #n ")" ::: "memory")
; #define BAR __builtin_amdgcn_s_barrier()
; #define SCHED __builtin_amdgcn_sched_barrier(0)
;     ...
;       LDB(B0, 0, 0); SCHED; LDA(At, 0, 0); STAGE(SA(1, 1), A, brow + HALF, t + 1);
;       WAIT_L(8); BAR; WAIT_L(0); MMA(0, 0, At, B0); BAR; SCHED;
;       LDB(B1, 0, 1); STAGE(SB(0, 0), Bt, bcol, t + 2);
;       BAR; WAIT_L(0); MMA(0, 1, At, B1); BAR;
;       LDA(At, 0, 1); STAGE(SA(0, 0), A, brow, t + 2);
;       BAR; WAIT_L(0); MMA(1, 0, At, B0); BAR; SCHED;
.LBB0_98:
	v_add_u32_e32 v143, s2, v142
	ds_read_b128 v[146:149], v143
	ds_read_b128 v[150:153], v143 offset:1024
	ds_read_b128 v[154:157], v143 offset:2048
	ds_read_b128 v[158:161], v143 offset:3072
	s_add_u32 s66, s55, s4
	s_addc_u32 s67, s57, s5
	s_add_i32 s63, s15, 0xc000
	ds_read_b128 v[162:165], v133
	ds_read_b128 v[184:187], v133 offset:1024
	ds_read_b128 v[188:191], v134
	ds_read_b128 v[192:195], v134 offset:1024
	ds_read_b128 v[196:199], v137
	ds_read_b128 v[200:203], v137 offset:1024
	ds_read_b128 v[204:207], v139
	ds_read_b128 v[208:211], v139 offset:1024
	s_mov_b32 m0, s63
	v_lshl_add_u64 v[144:145], s[66:67], 0, v[0:1]
	s_add_i32 s59, s15, 0xe000
	global_load_lds_dwordx4 v[144:145], off
	v_lshl_add_u64 v[144:145], s[66:67], 0, v[140:141]
	s_mov_b32 m0, s59
	s_nop 0
	global_load_lds_dwordx4 v[144:145], off
	s_waitcnt lgkmcnt(8)
	s_barrier
	s_waitcnt lgkmcnt(0)
	s_waitcnt lgkmcnt(0)
	v_mfma_f32_16x16x32_bf16 v[126:129], v[162:165], v[146:149], v[126:129]
	v_mfma_f32_16x16x32_bf16 v[122:125], v[162:165], v[154:157], v[122:125]
	v_mfma_f32_16x16x32_bf16 v[118:121], v[188:191], v[146:149], v[118:121]
	v_mfma_f32_16x16x32_bf16 v[114:117], v[188:191], v[154:157], v[114:117]
	v_mfma_f32_16x16x32_bf16 v[110:113], v[196:199], v[146:149], v[110:113]
	v_mfma_f32_16x16x32_bf16 v[106:109], v[196:199], v[154:157], v[106:109]
	v_mfma_f32_16x16x32_bf16 v[102:105], v[204:207], v[146:149], v[102:105]
	v_mfma_f32_16x16x32_bf16 v[98:101], v[204:207], v[154:157], v[98:101]
	v_mfma_f32_16x16x32_bf16 v[126:129], v[184:187], v[150:153], v[126:129]
	v_mfma_f32_16x16x32_bf16 v[122:125], v[184:187], v[158:161], v[122:125]
	v_mfma_f32_16x16x32_bf16 v[118:121], v[192:195], v[150:153], v[118:121]
	v_mfma_f32_16x16x32_bf16 v[114:117], v[192:195], v[158:161], v[114:117]
	v_mfma_f32_16x16x32_bf16 v[110:113], v[200:203], v[150:153], v[110:113]
	v_mfma_f32_16x16x32_bf16 v[106:109], v[200:203], v[158:161], v[106:109]
	v_mfma_f32_16x16x32_bf16 v[102:105], v[208:211], v[150:153], v[102:105]
	v_mfma_f32_16x16x32_bf16 v[98:101], v[208:211], v[158:161], v[98:101]
	s_barrier
	s_add_i32 s58, s58, 2
	s_add_u32 s65, s50, s4
	s_addc_u32 s70, s51, s5
	s_add_u32 s66, s65, 0x100
	v_add_u32_e32 v144, s76, v142
	s_addc_u32 s67, s70, 0
	s_mov_b32 m0, s16
	ds_read_b128 v[212:215], v144
	ds_read_b128 v[216:219], v144 offset:1024
	ds_read_b128 v[220:223], v144 offset:2048
	ds_read_b128 v[224:227], v144 offset:3072
	s_nop 0
	v_lshl_add_u64 v[166:167], s[66:67], 0, v[0:1]
	global_load_lds_dwordx4 v[166:167], off
	v_lshl_add_u64 v[166:167], s[66:67], 0, v[140:141]
	s_mov_b32 m0, s17
	s_nop 0
	global_load_lds_dwordx4 v[166:167], off
	s_barrier
	s_waitcnt lgkmcnt(0)
	s_waitcnt lgkmcnt(0)
	v_mfma_f32_16x16x32_bf16 v[94:97], v[162:165], v[212:215], v[94:97]
	v_mfma_f32_16x16x32_bf16 v[90:93], v[162:165], v[220:223], v[90:93]
	v_mfma_f32_16x16x32_bf16 v[86:89], v[188:191], v[212:215], v[86:89]
	v_mfma_f32_16x16x32_bf16 v[82:85], v[188:191], v[220:223], v[82:85]
	v_mfma_f32_16x16x32_bf16 v[78:81], v[196:199], v[212:215], v[78:81]
	v_mfma_f32_16x16x32_bf16 v[74:77], v[196:199], v[220:223], v[74:77]
	v_mfma_f32_16x16x32_bf16 v[70:73], v[204:207], v[212:215], v[70:73]
	v_mfma_f32_16x16x32_bf16 v[66:69], v[204:207], v[220:223], v[66:69]
	v_mfma_f32_16x16x32_bf16 v[94:97], v[184:187], v[216:219], v[94:97]
	v_mfma_f32_16x16x32_bf16 v[90:93], v[184:187], v[224:227], v[90:93]
	v_mfma_f32_16x16x32_bf16 v[86:89], v[192:195], v[216:219], v[86:89]
	v_mfma_f32_16x16x32_bf16 v[82:85], v[192:195], v[224:227], v[82:85]
	v_mfma_f32_16x16x32_bf16 v[78:81], v[200:203], v[216:219], v[78:81]
	v_mfma_f32_16x16x32_bf16 v[74:77], v[200:203], v[224:227], v[74:77]
	v_mfma_f32_16x16x32_bf16 v[70:73], v[208:211], v[216:219], v[70:73]
	v_mfma_f32_16x16x32_bf16 v[66:69], v[208:211], v[224:227], v[66:69]
	s_add_u32 s71, s44, s4
	s_addc_u32 s72, s45, s5
	s_add_u32 s66, s71, 0x100
	s_addc_u32 s67, s72, 0
	s_mov_b32 m0, s15
	s_barrier
	ds_read_b128 v[162:165], v133 offset:16384
	ds_read_b128 v[184:187], v133 offset:17408
	ds_read_b128 v[188:191], v134 offset:16384
	ds_read_b128 v[192:195], v134 offset:17408
	ds_read_b128 v[196:199], v137 offset:16384
	ds_read_b128 v[200:203], v137 offset:17408
	ds_read_b128 v[204:207], v139 offset:16384
	ds_read_b128 v[208:211], v139 offset:17408
	s_nop 0
	v_lshl_add_u64 v[166:167], s[66:67], 0, v[0:1]
	global_load_lds_dwordx4 v[166:167], off
	v_lshl_add_u64 v[166:167], s[66:67], 0, v[140:141]
	s_mov_b32 m0, s18
	s_nop 0
	global_load_lds_dwordx4 v[166:167], off
	s_barrier
	s_waitcnt lgkmcnt(0)
	s_waitcnt lgkmcnt(0)
	v_mfma_f32_16x16x32_bf16 v[62:65], v[162:165], v[146:149], v[62:65]
	v_mfma_f32_16x16x32_bf16 v[58:61], v[162:165], v[154:157], v[58:61]
	v_mfma_f32_16x16x32_bf16 v[54:57], v[188:191], v[146:149], v[54:57]
	v_mfma_f32_16x16x32_bf16 v[50:53], v[188:191], v[154:157], v[50:53]
	v_mfma_f32_16x16x32_bf16 v[46:49], v[196:199], v[146:149], v[46:49]
	v_mfma_f32_16x16x32_bf16 v[42:45], v[196:199], v[154:157], v[42:45]
	v_mfma_f32_16x16x32_bf16 v[38:41], v[204:207], v[146:149], v[38:41]
	v_mfma_f32_16x16x32_bf16 v[34:37], v[204:207], v[154:157], v[34:37]
	v_mfma_f32_16x16x32_bf16 v[62:65], v[184:187], v[150:153], v[62:65]
	v_mfma_f32_16x16x32_bf16 v[58:61], v[184:187], v[158:161], v[58:61]
	v_mfma_f32_16x16x32_bf16 v[54:57], v[192:195], v[150:153], v[54:57]
	v_mfma_f32_16x16x32_bf16 v[50:53], v[192:195], v[158:161], v[50:53]
	v_mfma_f32_16x16x32_bf16 v[46:49], v[200:203], v[150:153], v[46:49]
	v_mfma_f32_16x16x32_bf16 v[42:45], v[200:203], v[158:161], v[42:45]
	v_mfma_f32_16x16x32_bf16 v[38:41], v[208:211], v[150:153], v[38:41]
	v_mfma_f32_16x16x32_bf16 v[34:37], v[208:211], v[158:161], v[34:37]
	s_barrier
; #define LDA(dst, b, h) for (int m = 0; m < 4; ++m) for (int k = 0; k < 2; ++k) \
;     dst[m][k] = *reinterpret_cast<const bf16x8*>((char*)SA(b, h) + lds_byte(wr * 64 + m * 16 + fr, k * 32 + fq * 8))
; #define LDB(dst, b, h) for (int n = 0; n < 2; ++n) for (int k = 0; k < 2; ++k) \
;     dst[n][k] = *reinterpret_cast<const bf16x8*>((char*)SB(b, h) + lds_byte(wc * 32 + n * 16 + fr, k * 32 + fq * 8))
; #define MMA(ai, bj, At, Bt_) do { __builtin_amdgcn_s_setprio(1); \
;     for (int m = 0; m < 4; ++m) for (int n = 0; n < 2; ++n) for (int k = 0; k < 2; ++k) \
;       acc[ai][bj][m][n] = __builtin_amdgcn_mfma_f32_16x16x32_bf16(At[m][k], Bt_[n][k], acc[ai][bj][m][n], 0, 0, 0); \
;     __builtin_amdgcn_s_setprio(0); } while (0)
; #define WAIT_V(n) asm volatile("s_waitcnt vmcnt(" #n ")" ::: "memory")
; #define WAIT_L(n) asm volatile("s_waitcnt lgkmcnt(" #n ")" ::: "memory")
; #define BAR __builtin_amdgcn_s_barrier()
; #define SCHED __builtin_amdgcn_sched_barrier(0)
;     ...
;       BAR; WAIT_L(0); MMA(1, 0, At, B0); BAR; SCHED;
;       STAGE(SB(0, 1), Bt, bcol + HALF, t + 2);
;       WAIT_V(6); BAR; MMA(1, 1, At, B1); BAR;
;       LDB(B0, 1, 0); SCHED; LDA(At, 1, 0); STAGE(SA(0, 1), A, brow + HALF, t + 2);
;       WAIT_L(8); BAR; WAIT_L(0); MMA(0, 0, At, B0); BAR; SCHED;
;       LDB(B1, 1, 1); STAGE(SB(1, 0), Bt, bcol, t + 3);
;       BAR; WAIT_L(0); MMA(0, 1, At, B1); BAR;
	s_add_u32 s73, s6, s4
	s_addc_u32 s82, s7, s5
	s_add_u32 s66, s73, 0x160100
	s_addc_u32 s67, s82, 0
	s_mov_b32 m0, s19
	s_nop 0
	v_lshl_add_u64 v[146:147], s[66:67], 0, v[0:1]
	global_load_lds_dwordx4 v[146:147], off
	v_lshl_add_u64 v[146:147], s[66:67], 0, v[140:141]
	s_mov_b32 m0, s21
	s_nop 0
	global_load_lds_dwordx4 v[146:147], off
	s_waitcnt vmcnt(6)
	s_barrier
	v_mfma_f32_16x16x32_bf16 v[30:33], v[162:165], v[212:215], v[30:33]
	v_mfma_f32_16x16x32_bf16 v[26:29], v[162:165], v[220:223], v[26:29]
	v_mfma_f32_16x16x32_bf16 v[22:25], v[188:191], v[212:215], v[22:25]
	v_mfma_f32_16x16x32_bf16 v[18:21], v[188:191], v[220:223], v[18:21]
	v_mfma_f32_16x16x32_bf16 v[14:17], v[196:199], v[212:215], v[14:17]
	v_mfma_f32_16x16x32_bf16 v[10:13], v[196:199], v[220:223], v[10:13]
	v_mfma_f32_16x16x32_bf16 v[6:9], v[204:207], v[212:215], v[6:9]
	v_mfma_f32_16x16x32_bf16 v[2:5], v[204:207], v[220:223], v[2:5]
	v_mfma_f32_16x16x32_bf16 v[30:33], v[184:187], v[216:219], v[30:33]
	v_mfma_f32_16x16x32_bf16 v[26:29], v[184:187], v[224:227], v[26:29]
	v_mfma_f32_16x16x32_bf16 v[22:25], v[192:195], v[216:219], v[22:25]
	v_mfma_f32_16x16x32_bf16 v[18:21], v[192:195], v[224:227], v[18:21]
	v_mfma_f32_16x16x32_bf16 v[14:17], v[200:203], v[216:219], v[14:17]
	v_mfma_f32_16x16x32_bf16 v[10:13], v[200:203], v[224:227], v[10:13]
	v_mfma_f32_16x16x32_bf16 v[6:9], v[208:211], v[216:219], v[6:9]
	v_mfma_f32_16x16x32_bf16 v[2:5], v[208:211], v[224:227], v[2:5]
	v_add_u32_e32 v145, s77, v142
	s_barrier
	ds_read_b128 v[148:151], v145
	ds_read_b128 v[152:155], v145 offset:1024
	ds_read_b128 v[156:159], v145 offset:2048
	ds_read_b128 v[160:163], v145 offset:3072
	s_add_u32 s66, s71, 0x160100
	s_addc_u32 s67, s72, 0
	s_mov_b32 m0, s30
	ds_read_b128 v[164:167], v133 offset:32768
	ds_read_b128 v[184:187], v133 offset:33792
	ds_read_b128 v[188:191], v134 offset:32768
	ds_read_b128 v[192:195], v134 offset:33792
	ds_read_b128 v[196:199], v137 offset:32768
	ds_read_b128 v[200:203], v137 offset:33792
	ds_read_b128 v[204:207], v139 offset:32768
	ds_read_b128 v[208:211], v139 offset:33792
	s_nop 0
	v_lshl_add_u64 v[146:147], s[66:67], 0, v[0:1]
	global_load_lds_dwordx4 v[146:147], off
	v_lshl_add_u64 v[146:147], s[66:67], 0, v[140:141]
	s_mov_b32 m0, s31
	s_nop 0
	global_load_lds_dwordx4 v[146:147], off
	s_waitcnt lgkmcnt(8)
	s_barrier
	s_waitcnt lgkmcnt(0)
	s_waitcnt lgkmcnt(0)
	v_mfma_f32_16x16x32_bf16 v[126:129], v[164:167], v[148:151], v[126:129]
	v_mfma_f32_16x16x32_bf16 v[122:125], v[164:167], v[156:159], v[122:125]
	v_mfma_f32_16x16x32_bf16 v[118:121], v[188:191], v[148:151], v[118:121]
	v_mfma_f32_16x16x32_bf16 v[114:117], v[188:191], v[156:159], v[114:117]
	v_mfma_f32_16x16x32_bf16 v[110:113], v[196:199], v[148:151], v[110:113]
	v_mfma_f32_16x16x32_bf16 v[106:109], v[196:199], v[156:159], v[106:109]
	v_mfma_f32_16x16x32_bf16 v[102:105], v[204:207], v[148:151], v[102:105]
	v_mfma_f32_16x16x32_bf16 v[98:101], v[204:207], v[156:159], v[98:101]
	v_mfma_f32_16x16x32_bf16 v[126:129], v[184:187], v[152:155], v[126:129]
	v_mfma_f32_16x16x32_bf16 v[122:125], v[184:187], v[160:163], v[122:125]
	v_mfma_f32_16x16x32_bf16 v[118:121], v[192:195], v[152:155], v[118:121]
	v_mfma_f32_16x16x32_bf16 v[114:117], v[192:195], v[160:163], v[114:117]
	v_mfma_f32_16x16x32_bf16 v[110:113], v[200:203], v[152:155], v[110:113]
	v_mfma_f32_16x16x32_bf16 v[106:109], v[200:203], v[160:163], v[106:109]
	v_mfma_f32_16x16x32_bf16 v[102:105], v[208:211], v[152:155], v[102:105]
	v_mfma_f32_16x16x32_bf16 v[98:101], v[208:211], v[160:163], v[98:101]
	s_barrier
	s_add_u32 s66, s65, 0x180
	v_add_u32_e32 v146, s78, v142
	s_addc_u32 s67, s70, 0
	s_mov_b32 m0, s34
	ds_read_b128 v[212:215], v146
	ds_read_b128 v[216:219], v146 offset:1024
	ds_read_b128 v[220:223], v146 offset:2048
	ds_read_b128 v[224:227], v146 offset:3072
	s_nop 0
	v_lshl_add_u64 v[228:229], s[66:67], 0, v[0:1]
	global_load_lds_dwordx4 v[228:229], off
	v_lshl_add_u64 v[228:229], s[66:67], 0, v[140:141]
	s_mov_b32 m0, s35
	s_nop 0
	global_load_lds_dwordx4 v[228:229], off
	s_barrier
	s_waitcnt lgkmcnt(0)
	s_waitcnt lgkmcnt(0)
	v_mfma_f32_16x16x32_bf16 v[94:97], v[164:167], v[212:215], v[94:97]
	v_mfma_f32_16x16x32_bf16 v[90:93], v[164:167], v[220:223], v[90:93]
	v_mfma_f32_16x16x32_bf16 v[86:89], v[188:191], v[212:215], v[86:89]
	v_mfma_f32_16x16x32_bf16 v[82:85], v[188:191], v[220:223], v[82:85]
	v_mfma_f32_16x16x32_bf16 v[78:81], v[196:199], v[212:215], v[78:81]
	v_mfma_f32_16x16x32_bf16 v[74:77], v[196:199], v[220:223], v[74:77]
	v_mfma_f32_16x16x32_bf16 v[70:73], v[204:207], v[212:215], v[70:73]
	v_mfma_f32_16x16x32_bf16 v[66:69], v[204:207], v[220:223], v[66:69]
	v_mfma_f32_16x16x32_bf16 v[94:97], v[184:187], v[216:219], v[94:97]
	v_mfma_f32_16x16x32_bf16 v[90:93], v[184:187], v[224:227], v[90:93]
	v_mfma_f32_16x16x32_bf16 v[86:89], v[192:195], v[216:219], v[86:89]
	v_mfma_f32_16x16x32_bf16 v[82:85], v[192:195], v[224:227], v[82:85]
	v_mfma_f32_16x16x32_bf16 v[78:81], v[200:203], v[216:219], v[78:81]
	v_mfma_f32_16x16x32_bf16 v[74:77], v[200:203], v[224:227], v[74:77]
	v_mfma_f32_16x16x32_bf16 v[70:73], v[208:211], v[216:219], v[70:73]
	v_mfma_f32_16x16x32_bf16 v[66:69], v[208:211], v[224:227], v[66:69]
	s_add_u32 s66, s71, 0x180
	s_addc_u32 s67, s72, 0
	s_mov_b32 m0, s37
	s_barrier
	ds_read_b128 v[164:167], v133 offset:49152
	ds_read_b128 v[184:187], v133 offset:50176
	ds_read_b128 v[188:191], v134 offset:49152
	ds_read_b128 v[192:195], v134 offset:50176
	ds_read_b128 v[196:199], v137 offset:49152
	ds_read_b128 v[200:203], v137 offset:50176
	ds_read_b128 v[204:207], v139 offset:49152
	ds_read_b128 v[208:211], v139 offset:50176
	s_nop 0
	v_lshl_add_u64 v[228:229], s[66:67], 0, v[0:1]
	global_load_lds_dwordx4 v[228:229], off
	v_lshl_add_u64 v[228:229], s[66:67], 0, v[140:141]
	s_mov_b32 m0, s38
	s_nop 0
	global_load_lds_dwordx4 v[228:229], off
	s_barrier
; #define LDA(dst, b, h) for (int m = 0; m < 4; ++m) for (int k = 0; k < 2; ++k) \
;     dst[m][k] = *reinterpret_cast<const bf16x8*>((char*)SA(b, h) + lds_byte(wr * 64 + m * 16 + fr, k * 32 + fq * 8))
; #define LDB(dst, b, h) for (int n = 0; n < 2; ++n) for (int k = 0; k < 2; ++k) \
;     dst[n][k] = *reinterpret_cast<const bf16x8*>((char*)SB(b, h) + lds_byte(wc * 32 + n * 16 + fr, k * 32 + fq * 8))
; #define MMA(ai, bj, At, Bt_) do { __builtin_amdgcn_s_setprio(1); \
;     for (int m = 0; m < 4; ++m) for (int n = 0; n < 2; ++n) for (int k = 0; k < 2; ++k) \
;       acc[ai][bj][m][n] = __builtin_amdgcn_mfma_f32_16x16x32_bf16(At[m][k], Bt_[n][k], acc[ai][bj][m][n], 0, 0, 0); \
;     __builtin_amdgcn_s_setprio(0); } while (0)
; #define WAIT_V(n) asm volatile("s_waitcnt vmcnt(" #n ")" ::: "memory")
; #define WAIT_L(n) asm volatile("s_waitcnt lgkmcnt(" #n ")" ::: "memory")
; #define BAR __builtin_amdgcn_s_barrier()
; #define SCHED __builtin_amdgcn_sched_barrier(0)
;     ...
;       BAR; WAIT_L(0); MMA(0, 1, At, B1); BAR;
;       LDA(At, 1, 1); STAGE(SA(1, 0), A, brow, t + 3);
;       BAR; WAIT_L(0); MMA(1, 0, At, B0); BAR; SCHED;
;       STAGE(SB(1, 1), Bt, bcol + HALF, t + 3);
;       WAIT_V(6); BAR; MMA(1, 1, At, B1); BAR;
;     }
;     { LDB(B0, 0, 0); LDA(At, 0, 0); STAGE(SA(1, 1), A, brow + HALF, nt - 1);
;       BAR; WAIT_L(0); MMA(0, 0, At, B0); BAR;
;       LDB(B1, 0, 1); BAR; WAIT_L(0); MMA(0, 1, At, B1); BAR;
	s_waitcnt lgkmcnt(0)
	s_waitcnt lgkmcnt(0)
	v_mfma_f32_16x16x32_bf16 v[62:65], v[164:167], v[148:151], v[62:65]
	v_mfma_f32_16x16x32_bf16 v[58:61], v[164:167], v[156:159], v[58:61]
	v_mfma_f32_16x16x32_bf16 v[54:57], v[188:191], v[148:151], v[54:57]
	v_mfma_f32_16x16x32_bf16 v[50:53], v[188:191], v[156:159], v[50:53]
	v_mfma_f32_16x16x32_bf16 v[46:49], v[196:199], v[148:151], v[46:49]
	v_mfma_f32_16x16x32_bf16 v[42:45], v[196:199], v[156:159], v[42:45]
	v_mfma_f32_16x16x32_bf16 v[38:41], v[204:207], v[148:151], v[38:41]
	v_mfma_f32_16x16x32_bf16 v[34:37], v[204:207], v[156:159], v[34:37]
	v_mfma_f32_16x16x32_bf16 v[62:65], v[184:187], v[152:155], v[62:65]
	v_mfma_f32_16x16x32_bf16 v[58:61], v[184:187], v[160:163], v[58:61]
	v_mfma_f32_16x16x32_bf16 v[54:57], v[192:195], v[152:155], v[54:57]
	v_mfma_f32_16x16x32_bf16 v[50:53], v[192:195], v[160:163], v[50:53]
	v_mfma_f32_16x16x32_bf16 v[46:49], v[200:203], v[152:155], v[46:49]
	v_mfma_f32_16x16x32_bf16 v[42:45], v[200:203], v[160:163], v[42:45]
	v_mfma_f32_16x16x32_bf16 v[38:41], v[208:211], v[152:155], v[38:41]
	v_mfma_f32_16x16x32_bf16 v[34:37], v[208:211], v[160:163], v[34:37]
	s_barrier
	s_add_u32 s66, s73, 0x160180
	s_addc_u32 s67, s82, 0
	s_mov_b32 m0, s41
	s_nop 0
	v_lshl_add_u64 v[148:149], s[66:67], 0, v[0:1]
	global_load_lds_dwordx4 v[148:149], off
	v_lshl_add_u64 v[148:149], s[66:67], 0, v[140:141]
	s_mov_b32 m0, s42
	s_nop 0
	global_load_lds_dwordx4 v[148:149], off
	s_waitcnt vmcnt(6)
	s_barrier
	v_mfma_f32_16x16x32_bf16 v[30:33], v[164:167], v[212:215], v[30:33]
	v_mfma_f32_16x16x32_bf16 v[26:29], v[164:167], v[220:223], v[26:29]
	v_mfma_f32_16x16x32_bf16 v[22:25], v[188:191], v[212:215], v[22:25]
	v_mfma_f32_16x16x32_bf16 v[18:21], v[188:191], v[220:223], v[18:21]
	v_mfma_f32_16x16x32_bf16 v[14:17], v[196:199], v[212:215], v[14:17]
	v_mfma_f32_16x16x32_bf16 v[10:13], v[196:199], v[220:223], v[10:13]
	v_mfma_f32_16x16x32_bf16 v[6:9], v[204:207], v[212:215], v[6:9]
	v_mfma_f32_16x16x32_bf16 v[2:5], v[204:207], v[220:223], v[2:5]
	v_mfma_f32_16x16x32_bf16 v[30:33], v[184:187], v[216:219], v[30:33]
	v_mfma_f32_16x16x32_bf16 v[26:29], v[184:187], v[224:227], v[26:29]
	v_mfma_f32_16x16x32_bf16 v[22:25], v[192:195], v[216:219], v[22:25]
	v_mfma_f32_16x16x32_bf16 v[18:21], v[192:195], v[224:227], v[18:21]
	v_mfma_f32_16x16x32_bf16 v[14:17], v[200:203], v[216:219], v[14:17]
	v_mfma_f32_16x16x32_bf16 v[10:13], v[200:203], v[224:227], v[10:13]
	v_mfma_f32_16x16x32_bf16 v[6:9], v[208:211], v[216:219], v[6:9]
	v_mfma_f32_16x16x32_bf16 v[2:5], v[208:211], v[224:227], v[2:5]
	s_add_u32 s6, s6, 0x100
	s_addc_u32 s7, s7, 0
	s_add_u32 s44, s44, 0x100
	s_addc_u32 s45, s45, 0
	s_add_u32 s50, s50, 0x100
	s_addc_u32 s51, s51, 0
	s_add_u32 s55, s55, 0x100
	s_addc_u32 s57, s57, 0
	s_cmp_ge_u32 s58, s43
	s_barrier
	s_cbranch_scc0 .LBB0_98
	s_setprio 0
	s_add_i32 s4, s48, s14
	s_add_i32 s48, s4, -1
	s_lshl_b64 s[4:5], s[48:49], 7
	s_add_u32 s4, s22, s4
	s_addc_u32 s5, s23, s5
	s_add_u32 s4, s4, s40
	s_addc_u32 s5, s5, s39
	s_mov_b32 m0, s63
	ds_read_b128 v[148:151], v143
	ds_read_b128 v[152:155], v143 offset:1024
	ds_read_b128 v[156:159], v143 offset:2048
	ds_read_b128 v[160:163], v143 offset:3072
	ds_read_b128 v[164:167], v133
	ds_read_b128 v[184:187], v133 offset:1024
	ds_read_b128 v[188:191], v134
	ds_read_b128 v[192:195], v134 offset:1024
	ds_read_b128 v[196:199], v137
	ds_read_b128 v[200:203], v137 offset:1024
	ds_read_b128 v[204:207], v139
	ds_read_b128 v[208:211], v139 offset:1024
	s_nop 0
	v_lshl_add_u64 v[142:143], s[4:5], 0, v[0:1]
	global_load_lds_dwordx4 v[142:143], off
	v_lshl_add_u64 v[140:141], s[4:5], 0, v[140:141]
	s_mov_b32 m0, s59
	s_nop 0
	global_load_lds_dwordx4 v[140:141], off
	s_barrier
	s_waitcnt lgkmcnt(0)
	s_setprio 1
	s_waitcnt lgkmcnt(0)
	v_mfma_f32_16x16x32_bf16 v[126:129], v[164:167], v[148:151], v[126:129]
	v_mfma_f32_16x16x32_bf16 v[122:125], v[164:167], v[156:159], v[122:125]
	v_mfma_f32_16x16x32_bf16 v[118:121], v[188:191], v[148:151], v[118:121]
	v_mfma_f32_16x16x32_bf16 v[110:113], v[196:199], v[148:151], v[110:113]
	v_mfma_f32_16x16x32_bf16 v[106:109], v[196:199], v[156:159], v[106:109]
	v_mfma_f32_16x16x32_bf16 v[102:105], v[204:207], v[148:151], v[102:105]
	v_mfma_f32_16x16x32_bf16 v[98:101], v[204:207], v[156:159], v[98:101]
	v_mfma_f32_16x16x32_bf16 v[126:129], v[184:187], v[152:155], v[126:129]
	v_mfma_f32_16x16x32_bf16 v[122:125], v[184:187], v[160:163], v[122:125]
	v_mfma_f32_16x16x32_bf16 v[118:121], v[192:195], v[152:155], v[118:121]
	v_mfma_f32_16x16x32_bf16 v[114:117], v[188:191], v[156:159], v[114:117]
	v_mfma_f32_16x16x32_bf16 v[110:113], v[200:203], v[152:155], v[110:113]
	v_mfma_f32_16x16x32_bf16 v[106:109], v[200:203], v[160:163], v[106:109]
	v_mfma_f32_16x16x32_bf16 v[102:105], v[208:211], v[152:155], v[102:105]
	v_mfma_f32_16x16x32_bf16 v[98:101], v[208:211], v[160:163], v[98:101]
	v_mfma_f32_16x16x32_bf16 v[140:143], v[192:195], v[160:163], v[114:117]
	s_setprio 0
	s_barrier
	s_nop 0
	ds_read_b128 v[114:117], v144
	ds_read_b128 v[212:215], v144 offset:1024
	ds_read_b128 v[216:219], v144 offset:2048
	ds_read_b128 v[220:223], v144 offset:3072
	s_barrier
; #define LDA(dst, b, h) for (int m = 0; m < 4; ++m) for (int k = 0; k < 2; ++k) \
;     dst[m][k] = *reinterpret_cast<const bf16x8*>((char*)SA(b, h) + lds_byte(wr * 64 + m * 16 + fr, k * 32 + fq * 8))
; #define LDB(dst, b, h) for (int n = 0; n < 2; ++n) for (int k = 0; k < 2; ++k) \
;     dst[n][k] = *reinterpret_cast<const bf16x8*>((char*)SB(b, h) + lds_byte(wc * 32 + n * 16 + fr, k * 32 + fq * 8))
; #define MMA(ai, bj, At, Bt_) do { __builtin_amdgcn_s_setprio(1); \
;     for (int m = 0; m < 4; ++m) for (int n = 0; n < 2; ++n) for (int k = 0; k < 2; ++k) \
;       acc[ai][bj][m][n] = __builtin_amdgcn_mfma_f32_16x16x32_bf16(At[m][k], Bt_[n][k], acc[ai][bj][m][n], 0, 0, 0); \
;     __builtin_amdgcn_s_setprio(0); } while (0)
; #define WAIT_V(n) asm volatile("s_waitcnt vmcnt(" #n ")" ::: "memory")
; #define WAIT_L(n) asm volatile("s_waitcnt lgkmcnt(" #n ")" ::: "memory")
; #define BAR __builtin_amdgcn_s_barrier()
;     ...
;       BAR; WAIT_L(0); MMA(0, 0, At, B0); BAR;
;       LDB(B1, 0, 1); BAR; WAIT_L(0); MMA(0, 1, At, B1); BAR;
;       LDA(At, 0, 1); WAIT_V(4); BAR; WAIT_L(0); MMA(1, 0, At, B0); MMA(1, 1, At, B1); BAR; }
;     { LDB(B0, 1, 0); LDA(At, 1, 0); WAIT_V(2); BAR; WAIT_L(0); MMA(0, 0, At, B0); BAR;
	s_waitcnt lgkmcnt(0)
	s_setprio 1
	s_waitcnt lgkmcnt(0)
	v_mfma_f32_16x16x32_bf16 v[90:93], v[164:167], v[216:219], v[90:93]
	v_mfma_f32_16x16x32_bf16 v[86:89], v[188:191], v[114:117], v[86:89]
	v_mfma_f32_16x16x32_bf16 v[94:97], v[164:167], v[114:117], v[94:97]
	v_mfma_f32_16x16x32_bf16 v[90:93], v[184:187], v[220:223], v[90:93]
	v_mfma_f32_16x16x32_bf16 v[86:89], v[192:195], v[212:215], v[86:89]
	v_mfma_f32_16x16x32_bf16 v[82:85], v[188:191], v[216:219], v[82:85]
	v_mfma_f32_16x16x32_bf16 v[78:81], v[196:199], v[114:117], v[78:81]
	v_mfma_f32_16x16x32_bf16 v[74:77], v[196:199], v[216:219], v[74:77]
	v_mfma_f32_16x16x32_bf16 v[70:73], v[204:207], v[114:117], v[70:73]
	v_mfma_f32_16x16x32_bf16 v[66:69], v[204:207], v[216:219], v[66:69]
	v_mfma_f32_16x16x32_bf16 v[224:227], v[184:187], v[212:215], v[94:97]
	v_mfma_f32_16x16x32_bf16 v[164:167], v[192:195], v[220:223], v[82:85]
	v_mfma_f32_16x16x32_bf16 v[184:187], v[200:203], v[212:215], v[78:81]
	v_mfma_f32_16x16x32_bf16 v[188:191], v[200:203], v[220:223], v[74:77]
	v_mfma_f32_16x16x32_bf16 v[192:195], v[208:211], v[212:215], v[70:73]
	v_mfma_f32_16x16x32_bf16 v[196:199], v[208:211], v[220:223], v[66:69]
	s_setprio 0
	s_barrier
	s_nop 0
	ds_read_b128 v[66:69], v133 offset:16384
	ds_read_b128 v[70:73], v133 offset:17408
	ds_read_b128 v[74:77], v134 offset:16384
	ds_read_b128 v[78:81], v134 offset:17408
	ds_read_b128 v[82:85], v137 offset:16384
	ds_read_b128 v[94:97], v137 offset:17408
	ds_read_b128 v[200:203], v139 offset:16384
	ds_read_b128 v[204:207], v139 offset:17408
	s_waitcnt vmcnt(4)
	s_barrier
	s_waitcnt lgkmcnt(0)
	s_setprio 1
	s_waitcnt lgkmcnt(0)
	v_mfma_f32_16x16x32_bf16 v[62:65], v[66:69], v[148:151], v[62:65]
	v_mfma_f32_16x16x32_bf16 v[58:61], v[66:69], v[156:159], v[58:61]
	v_mfma_f32_16x16x32_bf16 v[54:57], v[74:77], v[148:151], v[54:57]
	v_mfma_f32_16x16x32_bf16 v[50:53], v[74:77], v[156:159], v[50:53]
	v_mfma_f32_16x16x32_bf16 v[46:49], v[82:85], v[148:151], v[46:49]
	v_mfma_f32_16x16x32_bf16 v[42:45], v[82:85], v[156:159], v[42:45]
	v_mfma_f32_16x16x32_bf16 v[38:41], v[200:203], v[148:151], v[38:41]
	v_mfma_f32_16x16x32_bf16 v[34:37], v[200:203], v[156:159], v[34:37]
	v_mfma_f32_16x16x32_bf16 v[62:65], v[70:73], v[152:155], v[62:65]
	v_mfma_f32_16x16x32_bf16 v[58:61], v[70:73], v[160:163], v[58:61]
	v_mfma_f32_16x16x32_bf16 v[54:57], v[78:81], v[152:155], v[54:57]
	v_mfma_f32_16x16x32_bf16 v[50:53], v[78:81], v[160:163], v[50:53]
	v_mfma_f32_16x16x32_bf16 v[46:49], v[94:97], v[152:155], v[46:49]
	v_mfma_f32_16x16x32_bf16 v[42:45], v[94:97], v[160:163], v[42:45]
	v_mfma_f32_16x16x32_bf16 v[38:41], v[204:207], v[152:155], v[38:41]
	v_mfma_f32_16x16x32_bf16 v[34:37], v[204:207], v[160:163], v[34:37]
	s_setprio 0
	s_setprio 1
	v_mfma_f32_16x16x32_bf16 v[30:33], v[66:69], v[114:117], v[30:33]
	v_mfma_f32_16x16x32_bf16 v[26:29], v[66:69], v[216:219], v[26:29]
	v_mfma_f32_16x16x32_bf16 v[22:25], v[74:77], v[114:117], v[22:25]
	v_mfma_f32_16x16x32_bf16 v[18:21], v[74:77], v[216:219], v[18:21]
	v_mfma_f32_16x16x32_bf16 v[14:17], v[82:85], v[114:117], v[14:17]
	v_mfma_f32_16x16x32_bf16 v[10:13], v[82:85], v[216:219], v[10:13]
	v_mfma_f32_16x16x32_bf16 v[6:9], v[200:203], v[114:117], v[6:9]
	v_mfma_f32_16x16x32_bf16 v[2:5], v[200:203], v[216:219], v[2:5]
	v_mfma_f32_16x16x32_bf16 v[148:151], v[70:73], v[212:215], v[30:33]
	v_mfma_f32_16x16x32_bf16 v[152:155], v[70:73], v[220:223], v[26:29]
	v_mfma_f32_16x16x32_bf16 v[156:159], v[78:81], v[212:215], v[22:25]
	v_mfma_f32_16x16x32_bf16 v[160:163], v[78:81], v[220:223], v[18:21]
	v_mfma_f32_16x16x32_bf16 v[208:211], v[94:97], v[212:215], v[14:17]
	v_mfma_f32_16x16x32_bf16 v[228:231], v[94:97], v[220:223], v[10:13]
	v_mfma_f32_16x16x32_bf16 v[212:215], v[204:207], v[212:215], v[6:9]
	v_mfma_f32_16x16x32_bf16 v[200:203], v[204:207], v[220:223], v[2:5]
	s_setprio 0
	s_barrier
	ds_read_b128 v[14:17], v145
	ds_read_b128 v[30:33], v145 offset:1024
	ds_read_b128 v[204:207], v145 offset:2048
	ds_read_b128 v[216:219], v145 offset:3072
	ds_read_b128 v[2:5], v133 offset:32768
	ds_read_b128 v[6:9], v133 offset:33792
	ds_read_b128 v[10:13], v134 offset:32768
	ds_read_b128 v[18:21], v134 offset:33792
	ds_read_b128 v[22:25], v137 offset:32768
	ds_read_b128 v[26:29], v137 offset:33792
	ds_read_b128 v[220:223], v139 offset:32768
	ds_read_b128 v[232:235], v139 offset:33792
	s_waitcnt vmcnt(2)
	s_barrier
; #define LDA(dst, b, h) for (int m = 0; m < 4; ++m) for (int k = 0; k < 2; ++k) \
;     dst[m][k] = *reinterpret_cast<const bf16x8*>((char*)SA(b, h) + lds_byte(wr * 64 + m * 16 + fr, k * 32 + fq * 8))
; #define LDB(dst, b, h) for (int n = 0; n < 2; ++n) for (int k = 0; k < 2; ++k) \
;     dst[n][k] = *reinterpret_cast<const bf16x8*>((char*)SB(b, h) + lds_byte(wc * 32 + n * 16 + fr, k * 32 + fq * 8))
; #define MMA(ai, bj, At, Bt_) do { __builtin_amdgcn_s_setprio(1); \
;     for (int m = 0; m < 4; ++m) for (int n = 0; n < 2; ++n) for (int k = 0; k < 2; ++k) \
;       acc[ai][bj][m][n] = __builtin_amdgcn_mfma_f32_16x16x32_bf16(At[m][k], Bt_[n][k], acc[ai][bj][m][n], 0, 0, 0); \
;     __builtin_amdgcn_s_setprio(0); } while (0)
; #define WAIT_V(n) asm volatile("s_waitcnt vmcnt(" #n ")" ::: "memory")
; #define WAIT_L(n) asm volatile("s_waitcnt lgkmcnt(" #n ")" ::: "memory")
; #define BAR __builtin_amdgcn_s_barrier()
;     ...
;     { LDB(B0, 1, 0); LDA(At, 1, 0); WAIT_V(2); BAR; WAIT_L(0); MMA(0, 0, At, B0); BAR;
;       LDB(B1, 1, 1); WAIT_V(0); BAR; WAIT_L(0); MMA(0, 1, At, B1); BAR;
;       LDA(At, 1, 1); BAR; WAIT_L(0); MMA(1, 0, At, B0); MMA(1, 1, At, B1); BAR; }
;     if (wr == 0) BAR;
	s_waitcnt lgkmcnt(0)
	s_setprio 1
	s_waitcnt lgkmcnt(0)
	v_mfma_f32_16x16x32_bf16 v[66:69], v[2:5], v[14:17], v[126:129]
	v_mfma_f32_16x16x32_bf16 v[114:117], v[6:9], v[30:33], v[66:69]
	v_mfma_f32_16x16x32_bf16 v[66:69], v[2:5], v[204:207], v[122:125]
	v_mfma_f32_16x16x32_bf16 v[126:129], v[6:9], v[216:219], v[66:69]
	v_mfma_f32_16x16x32_bf16 v[66:69], v[10:13], v[14:17], v[118:121]
	v_mfma_f32_16x16x32_bf16 v[82:85], v[18:21], v[30:33], v[66:69]
	v_mfma_f32_16x16x32_bf16 v[66:69], v[10:13], v[204:207], v[140:143]
	v_mfma_f32_16x16x32_bf16 v[94:97], v[18:21], v[216:219], v[66:69]
	v_mfma_f32_16x16x32_bf16 v[66:69], v[22:25], v[14:17], v[110:113]
	v_mfma_f32_16x16x32_bf16 v[74:77], v[26:29], v[30:33], v[66:69]
	v_mfma_f32_16x16x32_bf16 v[66:69], v[22:25], v[204:207], v[106:109]
	v_mfma_f32_16x16x32_bf16 v[78:81], v[26:29], v[216:219], v[66:69]
	v_mfma_f32_16x16x32_bf16 v[66:69], v[220:223], v[14:17], v[102:105]
	v_mfma_f32_16x16x32_bf16 v[70:73], v[220:223], v[204:207], v[98:101]
	v_mfma_f32_16x16x32_bf16 v[66:69], v[232:235], v[30:33], v[66:69]
	v_mfma_f32_16x16x32_bf16 v[70:73], v[232:235], v[216:219], v[70:73]
	s_setprio 0
	s_barrier
	ds_read_b128 v[140:143], v146
	ds_read_b128 v[236:239], v146 offset:1024
	ds_read_b128 v[240:243], v146 offset:2048
	ds_read_b128 v[144:147], v146 offset:3072
	s_waitcnt vmcnt(0)
	s_barrier
	s_waitcnt lgkmcnt(0)
	s_setprio 1
	s_waitcnt lgkmcnt(0)
	v_mfma_f32_16x16x32_bf16 v[98:101], v[2:5], v[140:143], v[224:227]
	v_mfma_f32_16x16x32_bf16 v[2:5], v[2:5], v[240:243], v[90:93]
	v_mfma_f32_16x16x32_bf16 v[118:121], v[6:9], v[144:147], v[2:5]
	v_mfma_f32_16x16x32_bf16 v[2:5], v[10:13], v[140:143], v[86:89]
	v_mfma_f32_16x16x32_bf16 v[102:105], v[18:21], v[236:239], v[2:5]
	v_mfma_f32_16x16x32_bf16 v[2:5], v[10:13], v[240:243], v[164:167]
	v_mfma_f32_16x16x32_bf16 v[122:125], v[18:21], v[144:147], v[2:5]
	v_mfma_f32_16x16x32_bf16 v[2:5], v[22:25], v[140:143], v[184:187]
	v_mfma_f32_16x16x32_bf16 v[90:93], v[26:29], v[236:239], v[2:5]
	v_mfma_f32_16x16x32_bf16 v[2:5], v[22:25], v[240:243], v[188:191]
	v_mfma_f32_16x16x32_bf16 v[110:113], v[26:29], v[144:147], v[2:5]
	v_mfma_f32_16x16x32_bf16 v[2:5], v[220:223], v[140:143], v[192:195]
	v_mfma_f32_16x16x32_bf16 v[86:89], v[232:235], v[236:239], v[2:5]
	v_mfma_f32_16x16x32_bf16 v[2:5], v[220:223], v[240:243], v[196:199]
	v_mfma_f32_16x16x32_bf16 v[98:101], v[6:9], v[236:239], v[98:101]
	v_mfma_f32_16x16x32_bf16 v[106:109], v[232:235], v[144:147], v[2:5]
	s_setprio 0
	s_barrier
	ds_read_b128 v[164:167], v133 offset:49152
	ds_read_b128 v[184:187], v133 offset:50176
	ds_read_b128 v[188:191], v134 offset:49152
	ds_read_b128 v[192:195], v134 offset:50176
	ds_read_b128 v[196:199], v137 offset:49152
	ds_read_b128 v[220:223], v137 offset:50176
	ds_read_b128 v[224:227], v139 offset:49152
	ds_read_b128 v[232:235], v139 offset:50176
	s_barrier
	s_waitcnt lgkmcnt(0)
	s_setprio 1
	s_waitcnt lgkmcnt(0)
	v_mfma_f32_16x16x32_bf16 v[6:9], v[164:167], v[204:207], v[58:61]
	v_mfma_f32_16x16x32_bf16 v[10:13], v[188:191], v[204:207], v[50:53]
	v_mfma_f32_16x16x32_bf16 v[2:5], v[164:167], v[14:17], v[62:65]
	v_mfma_f32_16x16x32_bf16 v[18:21], v[184:187], v[216:219], v[6:9]
	v_mfma_f32_16x16x32_bf16 v[6:9], v[188:191], v[14:17], v[54:57]
	v_mfma_f32_16x16x32_bf16 v[22:25], v[192:195], v[216:219], v[10:13]
	v_mfma_f32_16x16x32_bf16 v[10:13], v[196:199], v[14:17], v[46:49]
	v_mfma_f32_16x16x32_bf16 v[14:17], v[224:227], v[14:17], v[38:41]
	v_mfma_f32_16x16x32_bf16 v[2:5], v[184:187], v[30:33], v[2:5]
	v_mfma_f32_16x16x32_bf16 v[6:9], v[192:195], v[30:33], v[6:9]
	v_mfma_f32_16x16x32_bf16 v[10:13], v[220:223], v[30:33], v[10:13]
	v_mfma_f32_16x16x32_bf16 v[26:29], v[196:199], v[204:207], v[42:45]
	v_mfma_f32_16x16x32_bf16 v[14:17], v[232:235], v[30:33], v[14:17]
	v_mfma_f32_16x16x32_bf16 v[30:33], v[224:227], v[204:207], v[34:37]
	v_mfma_f32_16x16x32_bf16 v[26:29], v[220:223], v[216:219], v[26:29]
	v_mfma_f32_16x16x32_bf16 v[30:33], v[232:235], v[216:219], v[30:33]
	s_setprio 0
	s_setprio 1
	v_mfma_f32_16x16x32_bf16 v[38:41], v[164:167], v[240:243], v[152:155]
	v_mfma_f32_16x16x32_bf16 v[42:45], v[188:191], v[240:243], v[160:163]
	v_mfma_f32_16x16x32_bf16 v[46:49], v[196:199], v[240:243], v[228:231]
	v_mfma_f32_16x16x32_bf16 v[34:37], v[164:167], v[140:143], v[148:151]
	v_mfma_f32_16x16x32_bf16 v[50:53], v[184:187], v[144:147], v[38:41]
	v_mfma_f32_16x16x32_bf16 v[38:41], v[188:191], v[140:143], v[156:159]
	v_mfma_f32_16x16x32_bf16 v[54:57], v[192:195], v[144:147], v[42:45]
	v_mfma_f32_16x16x32_bf16 v[42:45], v[196:199], v[140:143], v[208:211]
	v_mfma_f32_16x16x32_bf16 v[58:61], v[220:223], v[144:147], v[46:49]
	v_mfma_f32_16x16x32_bf16 v[46:49], v[224:227], v[140:143], v[212:215]
	v_mfma_f32_16x16x32_bf16 v[62:65], v[224:227], v[240:243], v[200:203]
	v_mfma_f32_16x16x32_bf16 v[34:37], v[184:187], v[236:239], v[34:37]
	v_mfma_f32_16x16x32_bf16 v[38:41], v[192:195], v[236:239], v[38:41]
	v_mfma_f32_16x16x32_bf16 v[42:45], v[220:223], v[236:239], v[42:45]
	v_mfma_f32_16x16x32_bf16 v[46:49], v[232:235], v[236:239], v[46:49]
	v_mfma_f32_16x16x32_bf16 v[62:65], v[232:235], v[144:147], v[62:65]
	s_setprio 0
	v_readlane_b32 s4, v245, 33
	v_readlane_b32 s5, v245, 34
	s_and_b64 vcc, exec, s[4:5]
	s_barrier
	s_cbranch_vccz .LBB0_101
	s_barrier

; #define WAIT_V(n) asm volatile("s_waitcnt vmcnt(" #n ")" ::: "memory")
; #define BAR __builtin_amdgcn_s_barrier()
;     ...
;     { int _r, _c; stage_rc(tix * 16, _r, _c); boff0 = (unsigned)(_r * K + _c) * 2u; stage_rc(tix * 16 + 8192, _r, _c); boff1 = (unsigned)(_r * K + _c) * 2u; }
;     int wgid = is_slice ? 0 : tile;
;     { int q = nwg / NXCD, r = nwg % NXCD, xcd = wgid % NXCD, off = wgid / NXCD;
;       wgid = (xcd < r ? xcd * (q + 1) : r * (q + 1) + (xcd - r) * q) + off; }
;     const int nig = WGM * nN, gid = wgid / nig, fm = gid * WGM, gsz = min(nM - fm, WGM);
;     int pm = fm + ((wgid % nig) % gsz), pn = (wgid % nig) / gsz;
;     if (is_slice) { const int u = tile - nwg; pn = u % nN; slice = u / nN; pm = nM; nt = (K / BK) / nslice; kt0 = slice * nt; }
;     const int brow = pm * BM, bcol = pn * BM;
;     f32x4 acc[2][2][4][2] = {};
;     bf16x8 At[4][2], B0[2][2], B1[2][2];
;     STAGE(SB(0, 0), Bt, bcol, 0); STAGE(SA(0, 0), A, brow, 0);
;     STAGE(SB(0, 1), Bt, bcol + HALF, 0); STAGE(SA(0, 1), A, brow + HALF, 0);
;     if (wr == 1) BAR;
;     WAIT_V(4); BAR;
;     STAGE(SB(1, 0), Bt, bcol, 1); STAGE(SA(1, 0), A, brow, 1); STAGE(SB(1, 1), Bt, bcol + HALF, 1);
;     WAIT_V(6); BAR;
.LBB0_154:
	s_add_u32 s34, s12, 0x80
	s_addc_u32 s35, s13, 0
	s_add_i32 s12, s24, 0x18000
	v_mov_b32_e32 v141, v1
	s_waitcnt vmcnt(4)
	s_barrier
	s_mov_b32 m0, s12
	v_lshl_add_u64 v[4:5], s[34:35], 0, v[0:1]
	s_add_i32 s13, s24, 0x1a000
	global_load_lds_dwordx4 v[4:5], off
	v_lshl_add_u64 v[4:5], s[34:35], 0, v[140:141]
	s_add_u32 s34, s14, 0x80
	s_mov_b32 m0, s13
	s_addc_u32 s35, s15, 0
	s_add_i32 s14, s24, 0x8000
	global_load_lds_dwordx4 v[4:5], off
	s_mov_b32 m0, s14
	v_lshl_add_u64 v[4:5], s[34:35], 0, v[0:1]
	s_add_i32 s15, s24, 0xa000
	global_load_lds_dwordx4 v[4:5], off
	v_lshl_add_u64 v[4:5], s[34:35], 0, v[140:141]
	s_add_u32 s34, s16, 0x80
	s_mov_b32 m0, s15
	s_addc_u32 s35, s17, 0
	s_add_i32 s16, s24, 0x1c000
	global_load_lds_dwordx4 v[4:5], off
	s_mov_b32 m0, s16
	v_lshl_add_u64 v[4:5], s[34:35], 0, v[0:1]
	s_add_i32 s17, s24, 0x1e000
	global_load_lds_dwordx4 v[4:5], off
	v_lshl_add_u64 v[4:5], s[34:35], 0, v[140:141]
	s_mov_b32 m0, s17
	v_and_b32_e32 v3, 15, v2
	global_load_lds_dwordx4 v[4:5], off
	v_and_b32_e32 v6, 48, v2
	v_lshlrev_b32_e32 v2, 2, v2
	v_lshlrev_b32_e32 v4, 6, v3
	v_and_b32_e32 v2, 32, v2
	v_bitop3_b32 v142, v4, v2, v6 bitop3:0x36
	v_or_b32_e32 v2, s33, v3
	v_lshlrev_b32_e32 v4, 6, v2
	v_lshlrev_b32_e32 v2, 2, v2
	v_and_b32_e32 v4, 0x3c0, v4
	v_and_b32_e32 v2, 32, v2
	v_readlane_b32 s34, v245, 36
	v_bitop3_b32 v4, v4, v2, v6 bitop3:0x36
	s_lshl_b32 s30, s30, 11
	v_or_b32_e32 v2, s34, v3
	v_lshlrev_b32_e32 v5, 6, v2
	v_lshlrev_b32_e32 v2, 2, v2
	v_and_b32_e32 v5, 0x3c0, v5
	v_and_b32_e32 v2, 32, v2
	v_readlane_b32 s34, v245, 37
	v_bitop3_b32 v5, v5, v2, v6 bitop3:0x36
	s_lshl_b32 s31, s31, 8
	v_or_b32_e32 v2, s34, v3
	v_lshlrev_b32_e32 v7, 6, v2
	v_lshlrev_b32_e32 v2, 2, v2
	s_add_i32 s30, s30, s31
	v_and_b32_e32 v7, 0x3c0, v7
	v_and_b32_e32 v2, 32, v2
	s_ashr_i32 s31, s30, 31
	v_bitop3_b32 v7, v7, v2, v6 bitop3:0x36
	v_or_b32_e32 v2, s85, v3
	s_lshl_b64 s[30:31], s[30:31], 12
	s_waitcnt lgkmcnt(0)
	v_readlane_b32 s38, v244, 19
	v_lshlrev_b32_e32 v3, 6, v2
	v_lshlrev_b32_e32 v2, 2, v2
	s_add_u32 s30, s74, s30
	v_add_u32_e32 v133, s38, v4
	v_readlane_b32 s38, v244, 20
	s_waitcnt vmcnt(6)
	v_and_b32_e32 v3, 0x3c0, v3
	v_and_b32_e32 v2, 32, v2
	s_addc_u32 s31, s75, s31
	v_add_u32_e32 v134, s38, v5
	v_readlane_b32 s38, v244, 21
	v_bitop3_b32 v3, v3, v2, v6 bitop3:0x36
	s_add_u32 s34, s18, s10
	v_mov_b32_e32 v2, 0
	v_add_u32_e32 v137, s38, v7
	v_readlane_b32 s38, v244, 22
	s_addc_u32 s35, s19, s11
	s_mov_b32 s37, -2
	s_mov_b64 s[10:11], 0
	v_add_u32_e32 v139, s38, v3
	v_mov_b32_e32 v3, v2
	v_mov_b32_e32 v4, v2
	v_mov_b32_e32 v5, v2
	v_mov_b32_e32 v6, v2
	v_mov_b32_e32 v7, v2
	v_mov_b32_e32 v8, v2
	v_mov_b32_e32 v9, v2
	v_mov_b32_e32 v10, v2
	v_mov_b32_e32 v11, v2
	v_mov_b32_e32 v12, v2
	v_mov_b32_e32 v13, v2
	v_mov_b32_e32 v14, v2
	v_mov_b32_e32 v15, v2
	v_mov_b32_e32 v16, v2
	v_mov_b32_e32 v17, v2
	v_mov_b32_e32 v18, v2
	v_mov_b32_e32 v19, v2
	v_mov_b32_e32 v20, v2
	v_mov_b32_e32 v21, v2
	v_mov_b32_e32 v22, v2
	v_mov_b32_e32 v23, v2
	v_mov_b32_e32 v24, v2
	v_mov_b32_e32 v25, v2
	v_mov_b32_e32 v26, v2
	v_mov_b32_e32 v27, v2
	v_mov_b32_e32 v28, v2
	v_mov_b32_e32 v29, v2
	v_mov_b32_e32 v30, v2
	v_mov_b32_e32 v31, v2
	v_mov_b32_e32 v32, v2
	v_mov_b32_e32 v33, v2
	v_mov_b32_e32 v34, v2
	v_mov_b32_e32 v35, v2
	v_mov_b32_e32 v36, v2
	v_mov_b32_e32 v37, v2
	v_mov_b32_e32 v38, v2
	v_mov_b32_e32 v39, v2
	v_mov_b32_e32 v40, v2
	v_mov_b32_e32 v41, v2
	v_mov_b32_e32 v42, v2
	v_mov_b32_e32 v43, v2
	v_mov_b32_e32 v44, v2
	v_mov_b32_e32 v45, v2
	v_mov_b32_e32 v46, v2
	v_mov_b32_e32 v47, v2
	v_mov_b32_e32 v48, v2
	v_mov_b32_e32 v49, v2
	v_mov_b32_e32 v50, v2
	v_mov_b32_e32 v51, v2
	v_mov_b32_e32 v52, v2
	v_mov_b32_e32 v53, v2
	v_mov_b32_e32 v54, v2
	v_mov_b32_e32 v55, v2
	v_mov_b32_e32 v56, v2
	v_mov_b32_e32 v57, v2
	v_mov_b32_e32 v58, v2
	v_mov_b32_e32 v59, v2
	v_mov_b32_e32 v60, v2
	v_mov_b32_e32 v61, v2
	v_mov_b32_e32 v62, v2
	v_mov_b32_e32 v63, v2
	v_mov_b32_e32 v64, v2
	v_mov_b32_e32 v65, v2
	v_mov_b32_e32 v66, v2
	v_mov_b32_e32 v67, v2
	v_mov_b32_e32 v68, v2
	v_mov_b32_e32 v69, v2
	v_mov_b32_e32 v70, v2
	v_mov_b32_e32 v71, v2
	v_mov_b32_e32 v72, v2
	v_mov_b32_e32 v73, v2
	v_mov_b32_e32 v74, v2
	v_mov_b32_e32 v75, v2
	v_mov_b32_e32 v76, v2
	v_mov_b32_e32 v77, v2
	v_mov_b32_e32 v78, v2
	v_mov_b32_e32 v79, v2
	v_mov_b32_e32 v80, v2
	v_mov_b32_e32 v81, v2
	v_mov_b32_e32 v82, v2
	v_mov_b32_e32 v83, v2
	v_mov_b32_e32 v84, v2
	v_mov_b32_e32 v85, v2
	v_mov_b32_e32 v86, v2
	v_mov_b32_e32 v87, v2
	v_mov_b32_e32 v88, v2
	v_mov_b32_e32 v89, v2
	v_mov_b32_e32 v90, v2
	v_mov_b32_e32 v91, v2
	v_mov_b32_e32 v92, v2
	v_mov_b32_e32 v93, v2
	v_mov_b32_e32 v94, v2
	v_mov_b32_e32 v95, v2
	v_mov_b32_e32 v96, v2
	v_mov_b32_e32 v97, v2
	v_mov_b32_e32 v98, v2
	v_mov_b32_e32 v99, v2
	v_mov_b32_e32 v100, v2
	v_mov_b32_e32 v101, v2
	v_mov_b32_e32 v102, v2
	v_mov_b32_e32 v103, v2
	v_mov_b32_e32 v104, v2
	v_mov_b32_e32 v105, v2
	v_mov_b32_e32 v106, v2
	v_mov_b32_e32 v107, v2
	v_mov_b32_e32 v108, v2
	v_mov_b32_e32 v109, v2
	v_mov_b32_e32 v110, v2
	v_mov_b32_e32 v111, v2
	v_mov_b32_e32 v112, v2
	v_mov_b32_e32 v113, v2
	v_mov_b32_e32 v114, v2
	v_mov_b32_e32 v115, v2
	v_mov_b32_e32 v116, v2
	v_mov_b32_e32 v117, v2
	v_mov_b32_e32 v118, v2
	v_mov_b32_e32 v119, v2
	v_mov_b32_e32 v120, v2
	v_mov_b32_e32 v121, v2
	v_mov_b32_e32 v122, v2
	v_mov_b32_e32 v123, v2
	v_mov_b32_e32 v124, v2
	v_mov_b32_e32 v125, v2
	v_mov_b32_e32 v126, v2
	v_mov_b32_e32 v127, v2
	v_mov_b32_e32 v128, v2
	v_mov_b32_e32 v129, v2
	v_readlane_b32 vcc_lo, v245, 30
	s_nop 0
	s_cmpk_lt_u32 vcc_lo, 0x1000
	s_cbranch_scc1 .Lgp_155
	s_setprio 1

; #define LDA(dst, b, h) for (int m = 0; m < 4; ++m) for (int k = 0; k < 2; ++k) \
;     dst[m][k] = *reinterpret_cast<const bf16x8*>((char*)SA(b, h) + lds_byte(wr * 64 + m * 16 + fr, k * 32 + fq * 8))
; #define LDB(dst, b, h) for (int n = 0; n < 2; ++n) for (int k = 0; k < 2; ++k) \
;     dst[n][k] = *reinterpret_cast<const bf16x8*>((char*)SB(b, h) + lds_byte(wc * 32 + n * 16 + fr, k * 32 + fq * 8))
; #define MMA(ai, bj, At, Bt_) do { __builtin_amdgcn_s_setprio(1); \
;     for (int m = 0; m < 4; ++m) for (int n = 0; n < 2; ++n) for (int k = 0; k < 2; ++k) \
;       acc[ai][bj][m][n] = __builtin_amdgcn_mfma_f32_16x16x32_bf16(At[m][k], Bt_[n][k], acc[ai][bj][m][n], 0, 0, 0); \
;     __builtin_amdgcn_s_setprio(0); } while (0)
; #define WAIT_L(n) asm volatile("s_waitcnt lgkmcnt(" #n ")" ::: "memory")
; #define BAR __builtin_amdgcn_s_barrier()
; #define SCHED __builtin_amdgcn_sched_barrier(0)
;     ...
;       LDB(B0, 0, 0); SCHED; LDA(At, 0, 0); STAGE(SA(1, 1), A, brow + HALF, t + 1);
;       WAIT_L(8); BAR; WAIT_L(0); MMA(0, 0, At, B0); BAR; SCHED;
;       LDB(B1, 0, 1); STAGE(SB(0, 0), Bt, bcol, t + 2);
;       BAR; WAIT_L(0); MMA(0, 1, At, B1); BAR;
;       LDA(At, 0, 1); STAGE(SA(0, 0), A, brow, t + 2);
;       BAR; WAIT_L(0); MMA(1, 0, At, B0); BAR; SCHED;
.LBB0_155:
	v_add_u32_e32 v143, s2, v142
	ds_read_b128 v[146:149], v143
	ds_read_b128 v[150:153], v143 offset:1024
	ds_read_b128 v[154:157], v143 offset:2048
	ds_read_b128 v[158:161], v143 offset:3072
	s_add_u32 s40, s30, s10
	s_addc_u32 s41, s31, s11
	s_add_u32 s42, s40, 0x80080
	s_addc_u32 s43, s41, 0
	s_add_i32 s39, s24, 0xc000
	ds_read_b128 v[162:165], v133
	ds_read_b128 v[184:187], v133 offset:1024
	ds_read_b128 v[188:191], v134
	ds_read_b128 v[192:195], v134 offset:1024
	ds_read_b128 v[196:199], v137
	ds_read_b128 v[200:203], v137 offset:1024
	ds_read_b128 v[204:207], v139
	ds_read_b128 v[208:211], v139 offset:1024
	s_mov_b32 m0, s39
	v_lshl_add_u64 v[144:145], s[42:43], 0, v[0:1]
	s_add_i32 s38, s24, 0xe000
	global_load_lds_dwordx4 v[144:145], off
	v_lshl_add_u64 v[144:145], s[42:43], 0, v[140:141]
	s_mov_b32 m0, s38
	s_nop 0
	global_load_lds_dwordx4 v[144:145], off
	s_waitcnt lgkmcnt(8)
	s_barrier
	s_waitcnt lgkmcnt(0)
	s_waitcnt lgkmcnt(0)
	v_mfma_f32_16x16x32_bf16 v[126:129], v[162:165], v[146:149], v[126:129]
	v_mfma_f32_16x16x32_bf16 v[122:125], v[162:165], v[154:157], v[122:125]
	v_mfma_f32_16x16x32_bf16 v[118:121], v[188:191], v[146:149], v[118:121]
	v_mfma_f32_16x16x32_bf16 v[114:117], v[188:191], v[154:157], v[114:117]
	v_mfma_f32_16x16x32_bf16 v[110:113], v[196:199], v[146:149], v[110:113]
	v_mfma_f32_16x16x32_bf16 v[106:109], v[196:199], v[154:157], v[106:109]
	v_mfma_f32_16x16x32_bf16 v[102:105], v[204:207], v[146:149], v[102:105]
	v_mfma_f32_16x16x32_bf16 v[98:101], v[204:207], v[154:157], v[98:101]
	v_mfma_f32_16x16x32_bf16 v[126:129], v[184:187], v[150:153], v[126:129]
	v_mfma_f32_16x16x32_bf16 v[122:125], v[184:187], v[158:161], v[122:125]
	v_mfma_f32_16x16x32_bf16 v[118:121], v[192:195], v[150:153], v[118:121]
	v_mfma_f32_16x16x32_bf16 v[114:117], v[192:195], v[158:161], v[114:117]
	v_mfma_f32_16x16x32_bf16 v[110:113], v[200:203], v[150:153], v[110:113]
	v_mfma_f32_16x16x32_bf16 v[106:109], v[200:203], v[158:161], v[106:109]
	v_mfma_f32_16x16x32_bf16 v[102:105], v[208:211], v[150:153], v[102:105]
	v_mfma_f32_16x16x32_bf16 v[98:101], v[208:211], v[158:161], v[98:101]
	s_barrier
	s_add_u32 s42, s34, s10
	s_addc_u32 s43, s35, s11
	s_add_u32 s44, s42, 0x100
	v_add_u32_e32 v144, s76, v142
	s_addc_u32 s45, s43, 0
	s_mov_b32 m0, s25
	ds_read_b128 v[212:215], v144
	ds_read_b128 v[216:219], v144 offset:1024
	ds_read_b128 v[220:223], v144 offset:2048
	ds_read_b128 v[224:227], v144 offset:3072
	s_nop 0
	v_lshl_add_u64 v[166:167], s[44:45], 0, v[0:1]
	global_load_lds_dwordx4 v[166:167], off
	v_lshl_add_u64 v[166:167], s[44:45], 0, v[140:141]
	s_mov_b32 m0, s26
	s_nop 0
	global_load_lds_dwordx4 v[166:167], off
	s_barrier
	s_waitcnt lgkmcnt(0)
	s_waitcnt lgkmcnt(0)
	v_mfma_f32_16x16x32_bf16 v[94:97], v[162:165], v[212:215], v[94:97]
	v_mfma_f32_16x16x32_bf16 v[90:93], v[162:165], v[220:223], v[90:93]
	v_mfma_f32_16x16x32_bf16 v[86:89], v[188:191], v[212:215], v[86:89]
	v_mfma_f32_16x16x32_bf16 v[82:85], v[188:191], v[220:223], v[82:85]
	v_mfma_f32_16x16x32_bf16 v[78:81], v[196:199], v[212:215], v[78:81]
	v_mfma_f32_16x16x32_bf16 v[74:77], v[196:199], v[220:223], v[74:77]
	v_mfma_f32_16x16x32_bf16 v[70:73], v[204:207], v[212:215], v[70:73]
	v_mfma_f32_16x16x32_bf16 v[66:69], v[204:207], v[220:223], v[66:69]
	v_mfma_f32_16x16x32_bf16 v[94:97], v[184:187], v[216:219], v[94:97]
	v_mfma_f32_16x16x32_bf16 v[90:93], v[184:187], v[224:227], v[90:93]
	v_mfma_f32_16x16x32_bf16 v[86:89], v[192:195], v[216:219], v[86:89]
	v_mfma_f32_16x16x32_bf16 v[82:85], v[192:195], v[224:227], v[82:85]
	v_mfma_f32_16x16x32_bf16 v[78:81], v[200:203], v[216:219], v[78:81]
	v_mfma_f32_16x16x32_bf16 v[74:77], v[200:203], v[224:227], v[74:77]
	v_mfma_f32_16x16x32_bf16 v[70:73], v[208:211], v[216:219], v[70:73]
	v_mfma_f32_16x16x32_bf16 v[66:69], v[208:211], v[224:227], v[66:69]
	s_add_u32 s44, s40, 0x100
	s_addc_u32 s45, s41, 0
	s_mov_b32 m0, s24
	s_barrier
	ds_read_b128 v[162:165], v133 offset:16384
	ds_read_b128 v[184:187], v133 offset:17408
	ds_read_b128 v[188:191], v134 offset:16384
	ds_read_b128 v[192:195], v134 offset:17408
	ds_read_b128 v[196:199], v137 offset:16384
	ds_read_b128 v[200:203], v137 offset:17408
	ds_read_b128 v[204:207], v139 offset:16384
	ds_read_b128 v[208:211], v139 offset:17408
	s_nop 0
	v_lshl_add_u64 v[166:167], s[44:45], 0, v[0:1]
	global_load_lds_dwordx4 v[166:167], off
	v_lshl_add_u64 v[166:167], s[44:45], 0, v[140:141]
	s_mov_b32 m0, s9
	s_nop 0
	global_load_lds_dwordx4 v[166:167], off
	s_barrier
	s_waitcnt lgkmcnt(0)
	s_waitcnt lgkmcnt(0)
	v_mfma_f32_16x16x32_bf16 v[62:65], v[162:165], v[146:149], v[62:65]
	v_mfma_f32_16x16x32_bf16 v[58:61], v[162:165], v[154:157], v[58:61]
	v_mfma_f32_16x16x32_bf16 v[54:57], v[188:191], v[146:149], v[54:57]
	v_mfma_f32_16x16x32_bf16 v[50:53], v[188:191], v[154:157], v[50:53]
	v_mfma_f32_16x16x32_bf16 v[46:49], v[196:199], v[146:149], v[46:49]
	v_mfma_f32_16x16x32_bf16 v[42:45], v[196:199], v[154:157], v[42:45]
	v_mfma_f32_16x16x32_bf16 v[38:41], v[204:207], v[146:149], v[38:41]
	v_mfma_f32_16x16x32_bf16 v[34:37], v[204:207], v[154:157], v[34:37]
	v_mfma_f32_16x16x32_bf16 v[62:65], v[184:187], v[150:153], v[62:65]
	v_mfma_f32_16x16x32_bf16 v[58:61], v[184:187], v[158:161], v[58:61]
	v_mfma_f32_16x16x32_bf16 v[54:57], v[192:195], v[150:153], v[54:57]
	v_mfma_f32_16x16x32_bf16 v[50:53], v[192:195], v[158:161], v[50:53]
	v_mfma_f32_16x16x32_bf16 v[46:49], v[200:203], v[150:153], v[46:49]
	v_mfma_f32_16x16x32_bf16 v[42:45], v[200:203], v[158:161], v[42:45]
	v_mfma_f32_16x16x32_bf16 v[38:41], v[208:211], v[150:153], v[38:41]
	v_mfma_f32_16x16x32_bf16 v[34:37], v[208:211], v[158:161], v[34:37]
	s_barrier
; #define LDA(dst, b, h) for (int m = 0; m < 4; ++m) for (int k = 0; k < 2; ++k) \
;     dst[m][k] = *reinterpret_cast<const bf16x8*>((char*)SA(b, h) + lds_byte(wr * 64 + m * 16 + fr, k * 32 + fq * 8))
; #define LDB(dst, b, h) for (int n = 0; n < 2; ++n) for (int k = 0; k < 2; ++k) \
;     dst[n][k] = *reinterpret_cast<const bf16x8*>((char*)SB(b, h) + lds_byte(wc * 32 + n * 16 + fr, k * 32 + fq * 8))
; #define MMA(ai, bj, At, Bt_) do { __builtin_amdgcn_s_setprio(1); \
;     for (int m = 0; m < 4; ++m) for (int n = 0; n < 2; ++n) for (int k = 0; k < 2; ++k) \
;       acc[ai][bj][m][n] = __builtin_amdgcn_mfma_f32_16x16x32_bf16(At[m][k], Bt_[n][k], acc[ai][bj][m][n], 0, 0, 0); \
;     __builtin_amdgcn_s_setprio(0); } while (0)
; #define WAIT_V(n) asm volatile("s_waitcnt vmcnt(" #n ")" ::: "memory")
; #define WAIT_L(n) asm volatile("s_waitcnt lgkmcnt(" #n ")" ::: "memory")
; #define BAR __builtin_amdgcn_s_barrier()
; #define SCHED __builtin_amdgcn_sched_barrier(0)
;     ...
;       BAR; WAIT_L(0); MMA(1, 0, At, B0); BAR; SCHED;
;       STAGE(SB(0, 1), Bt, bcol + HALF, t + 2);
;       WAIT_V(6); BAR; MMA(1, 1, At, B1); BAR;
;       LDB(B0, 1, 0); SCHED; LDA(At, 1, 0); STAGE(SA(0, 1), A, brow + HALF, t + 2);
;       WAIT_L(8); BAR; WAIT_L(0); MMA(0, 0, At, B0); BAR; SCHED;
;       LDB(B1, 1, 1); STAGE(SB(1, 0), Bt, bcol, t + 3);
;       BAR; WAIT_L(0); MMA(0, 1, At, B1); BAR;
	s_add_u32 s44, s42, 0x80100
	s_addc_u32 s45, s43, 0
	s_mov_b32 m0, s27
	s_nop 0
	v_lshl_add_u64 v[146:147], s[44:45], 0, v[0:1]
	global_load_lds_dwordx4 v[146:147], off
	v_lshl_add_u64 v[146:147], s[44:45], 0, v[140:141]
	s_mov_b32 m0, s28
	s_nop 0
	global_load_lds_dwordx4 v[146:147], off
	s_waitcnt vmcnt(6)
	s_barrier
	v_mfma_f32_16x16x32_bf16 v[30:33], v[162:165], v[212:215], v[30:33]
	v_mfma_f32_16x16x32_bf16 v[26:29], v[162:165], v[220:223], v[26:29]
	v_mfma_f32_16x16x32_bf16 v[22:25], v[188:191], v[212:215], v[22:25]
	v_mfma_f32_16x16x32_bf16 v[18:21], v[188:191], v[220:223], v[18:21]
	v_mfma_f32_16x16x32_bf16 v[14:17], v[196:199], v[212:215], v[14:17]
	v_mfma_f32_16x16x32_bf16 v[10:13], v[196:199], v[220:223], v[10:13]
	v_mfma_f32_16x16x32_bf16 v[6:9], v[204:207], v[212:215], v[6:9]
	v_mfma_f32_16x16x32_bf16 v[2:5], v[204:207], v[220:223], v[2:5]
	v_mfma_f32_16x16x32_bf16 v[30:33], v[184:187], v[216:219], v[30:33]
	v_mfma_f32_16x16x32_bf16 v[26:29], v[184:187], v[224:227], v[26:29]
	v_mfma_f32_16x16x32_bf16 v[22:25], v[192:195], v[216:219], v[22:25]
	v_mfma_f32_16x16x32_bf16 v[18:21], v[192:195], v[224:227], v[18:21]
	v_mfma_f32_16x16x32_bf16 v[14:17], v[200:203], v[216:219], v[14:17]
	v_mfma_f32_16x16x32_bf16 v[10:13], v[200:203], v[224:227], v[10:13]
	v_mfma_f32_16x16x32_bf16 v[6:9], v[208:211], v[216:219], v[6:9]
	v_mfma_f32_16x16x32_bf16 v[2:5], v[208:211], v[224:227], v[2:5]
	v_add_u32_e32 v145, s77, v142
	s_barrier
	ds_read_b128 v[148:151], v145
	ds_read_b128 v[152:155], v145 offset:1024
	ds_read_b128 v[156:159], v145 offset:2048
	ds_read_b128 v[160:163], v145 offset:3072
	s_add_u32 s44, s40, 0x80100
	s_addc_u32 s45, s41, 0
	s_mov_b32 m0, s7
	ds_read_b128 v[164:167], v133 offset:32768
	ds_read_b128 v[184:187], v133 offset:33792
	ds_read_b128 v[188:191], v134 offset:32768
	ds_read_b128 v[192:195], v134 offset:33792
	ds_read_b128 v[196:199], v137 offset:32768
	ds_read_b128 v[200:203], v137 offset:33792
	ds_read_b128 v[204:207], v139 offset:32768
	ds_read_b128 v[208:211], v139 offset:33792
	s_nop 0
	v_lshl_add_u64 v[146:147], s[44:45], 0, v[0:1]
	global_load_lds_dwordx4 v[146:147], off
	v_lshl_add_u64 v[146:147], s[44:45], 0, v[140:141]
	s_mov_b32 m0, s29
	s_nop 0
	global_load_lds_dwordx4 v[146:147], off
	s_waitcnt lgkmcnt(8)
	s_barrier
	s_waitcnt lgkmcnt(0)
	s_waitcnt lgkmcnt(0)
	v_mfma_f32_16x16x32_bf16 v[126:129], v[164:167], v[148:151], v[126:129]
	v_mfma_f32_16x16x32_bf16 v[122:125], v[164:167], v[156:159], v[122:125]
	v_mfma_f32_16x16x32_bf16 v[118:121], v[188:191], v[148:151], v[118:121]
	v_mfma_f32_16x16x32_bf16 v[114:117], v[188:191], v[156:159], v[114:117]
	v_mfma_f32_16x16x32_bf16 v[110:113], v[196:199], v[148:151], v[110:113]
	v_mfma_f32_16x16x32_bf16 v[106:109], v[196:199], v[156:159], v[106:109]
	v_mfma_f32_16x16x32_bf16 v[102:105], v[204:207], v[148:151], v[102:105]
	v_mfma_f32_16x16x32_bf16 v[98:101], v[204:207], v[156:159], v[98:101]
	v_mfma_f32_16x16x32_bf16 v[126:129], v[184:187], v[152:155], v[126:129]
	v_mfma_f32_16x16x32_bf16 v[122:125], v[184:187], v[160:163], v[122:125]
	v_mfma_f32_16x16x32_bf16 v[118:121], v[192:195], v[152:155], v[118:121]
	v_mfma_f32_16x16x32_bf16 v[114:117], v[192:195], v[160:163], v[114:117]
	v_mfma_f32_16x16x32_bf16 v[110:113], v[200:203], v[152:155], v[110:113]
	v_mfma_f32_16x16x32_bf16 v[106:109], v[200:203], v[160:163], v[106:109]
	v_mfma_f32_16x16x32_bf16 v[102:105], v[208:211], v[152:155], v[102:105]
	v_mfma_f32_16x16x32_bf16 v[98:101], v[208:211], v[160:163], v[98:101]
	s_barrier
	s_add_u32 s44, s42, 0x180
	v_add_u32_e32 v146, s78, v142
	s_addc_u32 s45, s43, 0
	s_mov_b32 m0, s12
	ds_read_b128 v[212:215], v146
	ds_read_b128 v[216:219], v146 offset:1024
	ds_read_b128 v[220:223], v146 offset:2048
	ds_read_b128 v[224:227], v146 offset:3072
	s_nop 0
	v_lshl_add_u64 v[228:229], s[44:45], 0, v[0:1]
	global_load_lds_dwordx4 v[228:229], off
	v_lshl_add_u64 v[228:229], s[44:45], 0, v[140:141]
	s_mov_b32 m0, s13
	s_nop 0
	global_load_lds_dwordx4 v[228:229], off
	s_barrier
	s_waitcnt lgkmcnt(0)
	s_waitcnt lgkmcnt(0)
	v_mfma_f32_16x16x32_bf16 v[94:97], v[164:167], v[212:215], v[94:97]
	v_mfma_f32_16x16x32_bf16 v[90:93], v[164:167], v[220:223], v[90:93]
	v_mfma_f32_16x16x32_bf16 v[86:89], v[188:191], v[212:215], v[86:89]
	v_mfma_f32_16x16x32_bf16 v[82:85], v[188:191], v[220:223], v[82:85]
	v_mfma_f32_16x16x32_bf16 v[78:81], v[196:199], v[212:215], v[78:81]
	v_mfma_f32_16x16x32_bf16 v[74:77], v[196:199], v[220:223], v[74:77]
	v_mfma_f32_16x16x32_bf16 v[70:73], v[204:207], v[212:215], v[70:73]
	v_mfma_f32_16x16x32_bf16 v[66:69], v[204:207], v[220:223], v[66:69]
	v_mfma_f32_16x16x32_bf16 v[94:97], v[184:187], v[216:219], v[94:97]
	v_mfma_f32_16x16x32_bf16 v[90:93], v[184:187], v[224:227], v[90:93]
	v_mfma_f32_16x16x32_bf16 v[86:89], v[192:195], v[216:219], v[86:89]
	v_mfma_f32_16x16x32_bf16 v[82:85], v[192:195], v[224:227], v[82:85]
	v_mfma_f32_16x16x32_bf16 v[78:81], v[200:203], v[216:219], v[78:81]
	v_mfma_f32_16x16x32_bf16 v[74:77], v[200:203], v[224:227], v[74:77]
	v_mfma_f32_16x16x32_bf16 v[70:73], v[208:211], v[216:219], v[70:73]
	v_mfma_f32_16x16x32_bf16 v[66:69], v[208:211], v[224:227], v[66:69]
	s_add_u32 s40, s40, 0x180
	s_addc_u32 s41, s41, 0
	s_mov_b32 m0, s14
	s_barrier
	ds_read_b128 v[164:167], v133 offset:49152
	ds_read_b128 v[184:187], v133 offset:50176
	ds_read_b128 v[188:191], v134 offset:49152
	ds_read_b128 v[192:195], v134 offset:50176
	ds_read_b128 v[196:199], v137 offset:49152
	ds_read_b128 v[200:203], v137 offset:50176
	ds_read_b128 v[204:207], v139 offset:49152
	ds_read_b128 v[208:211], v139 offset:50176
	s_nop 0
	v_lshl_add_u64 v[228:229], s[40:41], 0, v[0:1]
	global_load_lds_dwordx4 v[228:229], off
	v_lshl_add_u64 v[228:229], s[40:41], 0, v[140:141]
	s_mov_b32 m0, s15
	s_nop 0
	global_load_lds_dwordx4 v[228:229], off
	s_barrier
; #define LDA(dst, b, h) for (int m = 0; m < 4; ++m) for (int k = 0; k < 2; ++k) \
;     dst[m][k] = *reinterpret_cast<const bf16x8*>((char*)SA(b, h) + lds_byte(wr * 64 + m * 16 + fr, k * 32 + fq * 8))
; #define LDB(dst, b, h) for (int n = 0; n < 2; ++n) for (int k = 0; k < 2; ++k) \
;     dst[n][k] = *reinterpret_cast<const bf16x8*>((char*)SB(b, h) + lds_byte(wc * 32 + n * 16 + fr, k * 32 + fq * 8))
; #define MMA(ai, bj, At, Bt_) do { __builtin_amdgcn_s_setprio(1); \
;     for (int m = 0; m < 4; ++m) for (int n = 0; n < 2; ++n) for (int k = 0; k < 2; ++k) \
;       acc[ai][bj][m][n] = __builtin_amdgcn_mfma_f32_16x16x32_bf16(At[m][k], Bt_[n][k], acc[ai][bj][m][n], 0, 0, 0); \
;     __builtin_amdgcn_s_setprio(0); } while (0)
; #define WAIT_V(n) asm volatile("s_waitcnt vmcnt(" #n ")" ::: "memory")
; #define WAIT_L(n) asm volatile("s_waitcnt lgkmcnt(" #n ")" ::: "memory")
; #define BAR __builtin_amdgcn_s_barrier()
; #define SCHED __builtin_amdgcn_sched_barrier(0)
;     ...
;       BAR; WAIT_L(0); MMA(0, 1, At, B1); BAR;
;       LDA(At, 1, 1); STAGE(SA(1, 0), A, brow, t + 3);
;       BAR; WAIT_L(0); MMA(1, 0, At, B0); BAR; SCHED;
;       STAGE(SB(1, 1), Bt, bcol + HALF, t + 3);
;       WAIT_V(6); BAR; MMA(1, 1, At, B1); BAR;
;     }
;     { LDB(B0, 0, 0); LDA(At, 0, 0); STAGE(SA(1, 1), A, brow + HALF, nt - 1);
;       BAR; WAIT_L(0); MMA(0, 0, At, B0); BAR;
;       LDB(B1, 0, 1); BAR; WAIT_L(0); MMA(0, 1, At, B1); BAR;
;       LDA(At, 0, 1); WAIT_V(4); BAR; WAIT_L(0); MMA(1, 0, At, B0); MMA(1, 1, At, B1); BAR; }
	s_waitcnt lgkmcnt(0)
	s_waitcnt lgkmcnt(0)
	v_mfma_f32_16x16x32_bf16 v[62:65], v[164:167], v[148:151], v[62:65]
	v_mfma_f32_16x16x32_bf16 v[58:61], v[164:167], v[156:159], v[58:61]
	v_mfma_f32_16x16x32_bf16 v[54:57], v[188:191], v[148:151], v[54:57]
	v_mfma_f32_16x16x32_bf16 v[50:53], v[188:191], v[156:159], v[50:53]
	v_mfma_f32_16x16x32_bf16 v[46:49], v[196:199], v[148:151], v[46:49]
	v_mfma_f32_16x16x32_bf16 v[42:45], v[196:199], v[156:159], v[42:45]
	v_mfma_f32_16x16x32_bf16 v[38:41], v[204:207], v[148:151], v[38:41]
	v_mfma_f32_16x16x32_bf16 v[34:37], v[204:207], v[156:159], v[34:37]
	v_mfma_f32_16x16x32_bf16 v[62:65], v[184:187], v[152:155], v[62:65]
	v_mfma_f32_16x16x32_bf16 v[58:61], v[184:187], v[160:163], v[58:61]
	v_mfma_f32_16x16x32_bf16 v[54:57], v[192:195], v[152:155], v[54:57]
	v_mfma_f32_16x16x32_bf16 v[50:53], v[192:195], v[160:163], v[50:53]
	v_mfma_f32_16x16x32_bf16 v[46:49], v[200:203], v[152:155], v[46:49]
	v_mfma_f32_16x16x32_bf16 v[42:45], v[200:203], v[160:163], v[42:45]
	v_mfma_f32_16x16x32_bf16 v[38:41], v[208:211], v[152:155], v[38:41]
	v_mfma_f32_16x16x32_bf16 v[34:37], v[208:211], v[160:163], v[34:37]
	s_barrier
	s_add_u32 s40, s42, 0x80180
	s_addc_u32 s41, s43, 0
	s_mov_b32 m0, s16
	s_nop 0
	v_lshl_add_u64 v[148:149], s[40:41], 0, v[0:1]
	global_load_lds_dwordx4 v[148:149], off
	v_lshl_add_u64 v[148:149], s[40:41], 0, v[140:141]
	s_mov_b32 m0, s17
	s_nop 0
	global_load_lds_dwordx4 v[148:149], off
	s_waitcnt vmcnt(6)
	s_barrier
	v_mfma_f32_16x16x32_bf16 v[30:33], v[164:167], v[212:215], v[30:33]
	v_mfma_f32_16x16x32_bf16 v[26:29], v[164:167], v[220:223], v[26:29]
	v_mfma_f32_16x16x32_bf16 v[22:25], v[188:191], v[212:215], v[22:25]
	v_mfma_f32_16x16x32_bf16 v[18:21], v[188:191], v[220:223], v[18:21]
	v_mfma_f32_16x16x32_bf16 v[14:17], v[196:199], v[212:215], v[14:17]
	v_mfma_f32_16x16x32_bf16 v[10:13], v[196:199], v[220:223], v[10:13]
	v_mfma_f32_16x16x32_bf16 v[6:9], v[204:207], v[212:215], v[6:9]
	v_mfma_f32_16x16x32_bf16 v[2:5], v[204:207], v[220:223], v[2:5]
	v_mfma_f32_16x16x32_bf16 v[30:33], v[184:187], v[216:219], v[30:33]
	v_mfma_f32_16x16x32_bf16 v[26:29], v[184:187], v[224:227], v[26:29]
	v_mfma_f32_16x16x32_bf16 v[22:25], v[192:195], v[216:219], v[22:25]
	v_mfma_f32_16x16x32_bf16 v[18:21], v[192:195], v[224:227], v[18:21]
	v_mfma_f32_16x16x32_bf16 v[14:17], v[200:203], v[216:219], v[14:17]
	v_mfma_f32_16x16x32_bf16 v[10:13], v[200:203], v[224:227], v[10:13]
	v_mfma_f32_16x16x32_bf16 v[6:9], v[208:211], v[216:219], v[6:9]
	v_mfma_f32_16x16x32_bf16 v[2:5], v[208:211], v[224:227], v[2:5]
	s_add_i32 s37, s37, 2
	s_add_u32 s10, s10, 0x100
	s_addc_u32 s11, s11, 0
	s_cmp_gt_u32 s37, 27
	s_barrier
	s_cbranch_scc0 .LBB0_155
	s_setprio 0
	s_add_u32 s4, s4, 0xf80
	s_addc_u32 s5, s5, 0
	s_mov_b32 m0, s39
	ds_read_b128 v[148:151], v143
	ds_read_b128 v[152:155], v143 offset:1024
	ds_read_b128 v[156:159], v143 offset:2048
	ds_read_b128 v[160:163], v143 offset:3072
	ds_read_b128 v[164:167], v133
	ds_read_b128 v[184:187], v133 offset:1024
	ds_read_b128 v[188:191], v134
	ds_read_b128 v[192:195], v134 offset:1024
	ds_read_b128 v[196:199], v137
	ds_read_b128 v[200:203], v137 offset:1024
	ds_read_b128 v[204:207], v139
	ds_read_b128 v[208:211], v139 offset:1024
	s_nop 0
	v_lshl_add_u64 v[142:143], s[4:5], 0, v[0:1]
	global_load_lds_dwordx4 v[142:143], off
	v_lshl_add_u64 v[140:141], s[4:5], 0, v[140:141]
	s_mov_b32 m0, s38
	s_nop 0
	global_load_lds_dwordx4 v[140:141], off
	s_barrier
	s_waitcnt lgkmcnt(0)
	s_setprio 1
	s_waitcnt lgkmcnt(0)
	v_mfma_f32_16x16x32_bf16 v[126:129], v[164:167], v[148:151], v[126:129]
	v_mfma_f32_16x16x32_bf16 v[118:121], v[188:191], v[148:151], v[118:121]
	v_mfma_f32_16x16x32_bf16 v[110:113], v[196:199], v[148:151], v[110:113]
	v_mfma_f32_16x16x32_bf16 v[102:105], v[204:207], v[148:151], v[102:105]
	v_mfma_f32_16x16x32_bf16 v[126:129], v[184:187], v[152:155], v[126:129]
	v_mfma_f32_16x16x32_bf16 v[122:125], v[164:167], v[156:159], v[122:125]
	v_mfma_f32_16x16x32_bf16 v[118:121], v[192:195], v[152:155], v[118:121]
	v_mfma_f32_16x16x32_bf16 v[114:117], v[188:191], v[156:159], v[114:117]
	v_mfma_f32_16x16x32_bf16 v[110:113], v[200:203], v[152:155], v[110:113]
	v_mfma_f32_16x16x32_bf16 v[106:109], v[196:199], v[156:159], v[106:109]
	v_mfma_f32_16x16x32_bf16 v[102:105], v[208:211], v[152:155], v[102:105]
	v_mfma_f32_16x16x32_bf16 v[98:101], v[204:207], v[156:159], v[98:101]
	v_mfma_f32_16x16x32_bf16 v[140:143], v[184:187], v[160:163], v[122:125]
	v_mfma_f32_16x16x32_bf16 v[212:215], v[192:195], v[160:163], v[114:117]
	v_mfma_f32_16x16x32_bf16 v[216:219], v[200:203], v[160:163], v[106:109]
	v_mfma_f32_16x16x32_bf16 v[220:223], v[208:211], v[160:163], v[98:101]
	s_setprio 0
	s_barrier
	s_nop 1
	ds_read_b128 v[98:101], v144
	ds_read_b128 v[106:109], v144 offset:1024
	ds_read_b128 v[114:117], v144 offset:2048
	ds_read_b128 v[122:125], v144 offset:3072
	s_barrier
	s_waitcnt lgkmcnt(0)
	s_setprio 1
	s_waitcnt lgkmcnt(0)
	v_mfma_f32_16x16x32_bf16 v[94:97], v[164:167], v[98:101], v[94:97]
	v_mfma_f32_16x16x32_bf16 v[86:89], v[188:191], v[98:101], v[86:89]
	v_mfma_f32_16x16x32_bf16 v[78:81], v[196:199], v[98:101], v[78:81]
	v_mfma_f32_16x16x32_bf16 v[70:73], v[204:207], v[98:101], v[70:73]
	v_mfma_f32_16x16x32_bf16 v[94:97], v[184:187], v[106:109], v[94:97]
	v_mfma_f32_16x16x32_bf16 v[90:93], v[164:167], v[114:117], v[90:93]
	v_mfma_f32_16x16x32_bf16 v[86:89], v[192:195], v[106:109], v[86:89]
	v_mfma_f32_16x16x32_bf16 v[82:85], v[188:191], v[114:117], v[82:85]
	v_mfma_f32_16x16x32_bf16 v[78:81], v[200:203], v[106:109], v[78:81]
	v_mfma_f32_16x16x32_bf16 v[74:77], v[196:199], v[114:117], v[74:77]
	v_mfma_f32_16x16x32_bf16 v[70:73], v[208:211], v[106:109], v[70:73]
	v_mfma_f32_16x16x32_bf16 v[66:69], v[204:207], v[114:117], v[66:69]
	v_mfma_f32_16x16x32_bf16 v[164:167], v[184:187], v[122:125], v[90:93]
	v_mfma_f32_16x16x32_bf16 v[184:187], v[192:195], v[122:125], v[82:85]
	v_mfma_f32_16x16x32_bf16 v[188:191], v[200:203], v[122:125], v[74:77]
	v_mfma_f32_16x16x32_bf16 v[192:195], v[208:211], v[122:125], v[66:69]
	s_setprio 0
	s_barrier
; #define LDA(dst, b, h) for (int m = 0; m < 4; ++m) for (int k = 0; k < 2; ++k) \
;     dst[m][k] = *reinterpret_cast<const bf16x8*>((char*)SA(b, h) + lds_byte(wr * 64 + m * 16 + fr, k * 32 + fq * 8))
; #define LDB(dst, b, h) for (int n = 0; n < 2; ++n) for (int k = 0; k < 2; ++k) \
;     dst[n][k] = *reinterpret_cast<const bf16x8*>((char*)SB(b, h) + lds_byte(wc * 32 + n * 16 + fr, k * 32 + fq * 8))
; #define MMA(ai, bj, At, Bt_) do { __builtin_amdgcn_s_setprio(1); \
;     for (int m = 0; m < 4; ++m) for (int n = 0; n < 2; ++n) for (int k = 0; k < 2; ++k) \
;       acc[ai][bj][m][n] = __builtin_amdgcn_mfma_f32_16x16x32_bf16(At[m][k], Bt_[n][k], acc[ai][bj][m][n], 0, 0, 0); \
;     __builtin_amdgcn_s_setprio(0); } while (0)
; #define WAIT_V(n) asm volatile("s_waitcnt vmcnt(" #n ")" ::: "memory")
; #define WAIT_L(n) asm volatile("s_waitcnt lgkmcnt(" #n ")" ::: "memory")
; #define BAR __builtin_amdgcn_s_barrier()
;     ...
;       LDB(B1, 0, 1); BAR; WAIT_L(0); MMA(0, 1, At, B1); BAR;
;       LDA(At, 0, 1); WAIT_V(4); BAR; WAIT_L(0); MMA(1, 0, At, B0); MMA(1, 1, At, B1); BAR; }
;     { LDB(B0, 1, 0); LDA(At, 1, 0); WAIT_V(2); BAR; WAIT_L(0); MMA(0, 0, At, B0); BAR;
;       LDB(B1, 1, 1); WAIT_V(0); BAR; WAIT_L(0); MMA(0, 1, At, B1); BAR;
	s_nop 1
	ds_read_b128 v[66:69], v133 offset:16384
	ds_read_b128 v[74:77], v133 offset:17408
	ds_read_b128 v[82:85], v134 offset:16384
	ds_read_b128 v[90:93], v134 offset:17408
	ds_read_b128 v[196:199], v137 offset:16384
	ds_read_b128 v[200:203], v137 offset:17408
	ds_read_b128 v[204:207], v139 offset:16384
	ds_read_b128 v[208:211], v139 offset:17408
	s_waitcnt vmcnt(4)
	s_barrier
	s_waitcnt lgkmcnt(0)
	s_setprio 1
	s_waitcnt lgkmcnt(0)
	v_mfma_f32_16x16x32_bf16 v[62:65], v[66:69], v[148:151], v[62:65]
	v_mfma_f32_16x16x32_bf16 v[54:57], v[82:85], v[148:151], v[54:57]
	v_mfma_f32_16x16x32_bf16 v[46:49], v[196:199], v[148:151], v[46:49]
	v_mfma_f32_16x16x32_bf16 v[38:41], v[204:207], v[148:151], v[38:41]
	v_mfma_f32_16x16x32_bf16 v[62:65], v[74:77], v[152:155], v[62:65]
	v_mfma_f32_16x16x32_bf16 v[58:61], v[66:69], v[156:159], v[58:61]
	v_mfma_f32_16x16x32_bf16 v[54:57], v[90:93], v[152:155], v[54:57]
	v_mfma_f32_16x16x32_bf16 v[50:53], v[82:85], v[156:159], v[50:53]
	v_mfma_f32_16x16x32_bf16 v[46:49], v[200:203], v[152:155], v[46:49]
	v_mfma_f32_16x16x32_bf16 v[42:45], v[196:199], v[156:159], v[42:45]
	v_mfma_f32_16x16x32_bf16 v[38:41], v[208:211], v[152:155], v[38:41]
	v_mfma_f32_16x16x32_bf16 v[34:37], v[204:207], v[156:159], v[34:37]
	v_mfma_f32_16x16x32_bf16 v[224:227], v[74:77], v[160:163], v[58:61]
	v_mfma_f32_16x16x32_bf16 v[228:231], v[90:93], v[160:163], v[50:53]
	v_mfma_f32_16x16x32_bf16 v[232:235], v[200:203], v[160:163], v[42:45]
	v_mfma_f32_16x16x32_bf16 v[148:151], v[208:211], v[160:163], v[34:37]
	s_setprio 0
	s_setprio 1
	v_mfma_f32_16x16x32_bf16 v[30:33], v[66:69], v[98:101], v[30:33]
	v_mfma_f32_16x16x32_bf16 v[22:25], v[82:85], v[98:101], v[22:25]
	v_mfma_f32_16x16x32_bf16 v[14:17], v[196:199], v[98:101], v[14:17]
	v_mfma_f32_16x16x32_bf16 v[6:9], v[204:207], v[98:101], v[6:9]
	v_mfma_f32_16x16x32_bf16 v[30:33], v[74:77], v[106:109], v[30:33]
	v_mfma_f32_16x16x32_bf16 v[26:29], v[66:69], v[114:117], v[26:29]
	v_mfma_f32_16x16x32_bf16 v[22:25], v[90:93], v[106:109], v[22:25]
	v_mfma_f32_16x16x32_bf16 v[18:21], v[82:85], v[114:117], v[18:21]
	v_mfma_f32_16x16x32_bf16 v[14:17], v[200:203], v[106:109], v[14:17]
	v_mfma_f32_16x16x32_bf16 v[10:13], v[196:199], v[114:117], v[10:13]
	v_mfma_f32_16x16x32_bf16 v[6:9], v[208:211], v[106:109], v[6:9]
	v_mfma_f32_16x16x32_bf16 v[2:5], v[204:207], v[114:117], v[2:5]
	v_mfma_f32_16x16x32_bf16 v[152:155], v[74:77], v[122:125], v[26:29]
	v_mfma_f32_16x16x32_bf16 v[156:159], v[90:93], v[122:125], v[18:21]
	v_mfma_f32_16x16x32_bf16 v[160:163], v[200:203], v[122:125], v[10:13]
	v_mfma_f32_16x16x32_bf16 v[196:199], v[208:211], v[122:125], v[2:5]
	s_setprio 0
	s_barrier
	s_nop 1
	ds_read_b128 v[2:5], v145
	ds_read_b128 v[10:13], v145 offset:1024
	ds_read_b128 v[200:203], v145 offset:2048
	ds_read_b128 v[204:207], v145 offset:3072
	ds_read_b128 v[18:21], v133 offset:32768
	ds_read_b128 v[26:29], v133 offset:33792
	ds_read_b128 v[34:37], v134 offset:32768
	ds_read_b128 v[42:45], v134 offset:33792
	ds_read_b128 v[50:53], v137 offset:32768
	ds_read_b128 v[58:61], v137 offset:33792
	ds_read_b128 v[208:211], v139 offset:32768
	ds_read_b128 v[236:239], v139 offset:33792
	s_waitcnt vmcnt(2)
	s_barrier
	s_waitcnt lgkmcnt(0)
	s_setprio 1
	s_waitcnt lgkmcnt(0)
	v_mfma_f32_16x16x32_bf16 v[66:69], v[18:21], v[2:5], v[126:129]
	v_mfma_f32_16x16x32_bf16 v[122:125], v[26:29], v[10:13], v[66:69]
	v_mfma_f32_16x16x32_bf16 v[66:69], v[18:21], v[200:203], v[140:143]
	v_mfma_f32_16x16x32_bf16 v[114:117], v[26:29], v[204:207], v[66:69]
	v_mfma_f32_16x16x32_bf16 v[66:69], v[34:37], v[2:5], v[118:121]
	v_mfma_f32_16x16x32_bf16 v[106:109], v[42:45], v[10:13], v[66:69]
	v_mfma_f32_16x16x32_bf16 v[66:69], v[34:37], v[200:203], v[212:215]
	v_mfma_f32_16x16x32_bf16 v[98:101], v[42:45], v[204:207], v[66:69]
	v_mfma_f32_16x16x32_bf16 v[66:69], v[50:53], v[2:5], v[110:113]
	v_mfma_f32_16x16x32_bf16 v[90:93], v[58:61], v[10:13], v[66:69]
	v_mfma_f32_16x16x32_bf16 v[66:69], v[50:53], v[200:203], v[216:219]
	v_mfma_f32_16x16x32_bf16 v[82:85], v[58:61], v[204:207], v[66:69]
	v_mfma_f32_16x16x32_bf16 v[66:69], v[208:211], v[2:5], v[102:105]
	v_mfma_f32_16x16x32_bf16 v[74:77], v[236:239], v[10:13], v[66:69]
	v_mfma_f32_16x16x32_bf16 v[66:69], v[208:211], v[200:203], v[220:223]
	v_mfma_f32_16x16x32_bf16 v[66:69], v[236:239], v[204:207], v[66:69]
	s_setprio 0
	s_barrier
; #define LDA(dst, b, h) for (int m = 0; m < 4; ++m) for (int k = 0; k < 2; ++k) \
;     dst[m][k] = *reinterpret_cast<const bf16x8*>((char*)SA(b, h) + lds_byte(wr * 64 + m * 16 + fr, k * 32 + fq * 8))
; #define LDB(dst, b, h) for (int n = 0; n < 2; ++n) for (int k = 0; k < 2; ++k) \
;     dst[n][k] = *reinterpret_cast<const bf16x8*>((char*)SB(b, h) + lds_byte(wc * 32 + n * 16 + fr, k * 32 + fq * 8))
; #define MMA(ai, bj, At, Bt_) do { __builtin_amdgcn_s_setprio(1); \
;     for (int m = 0; m < 4; ++m) for (int n = 0; n < 2; ++n) for (int k = 0; k < 2; ++k) \
;       acc[ai][bj][m][n] = __builtin_amdgcn_mfma_f32_16x16x32_bf16(At[m][k], Bt_[n][k], acc[ai][bj][m][n], 0, 0, 0); \
;     __builtin_amdgcn_s_setprio(0); } while (0)
; #define WAIT_V(n) asm volatile("s_waitcnt vmcnt(" #n ")" ::: "memory")
; #define WAIT_L(n) asm volatile("s_waitcnt lgkmcnt(" #n ")" ::: "memory")
; #define BAR __builtin_amdgcn_s_barrier()
;     ...
;     { LDB(B0, 1, 0); LDA(At, 1, 0); WAIT_V(2); BAR; WAIT_L(0); MMA(0, 0, At, B0); BAR;
;       LDB(B1, 1, 1); WAIT_V(0); BAR; WAIT_L(0); MMA(0, 1, At, B1); BAR;
;       LDA(At, 1, 1); BAR; WAIT_L(0); MMA(1, 0, At, B0); MMA(1, 1, At, B1); BAR; }
;     if (wr == 0) BAR;
	ds_read_b128 v[140:143], v146
	ds_read_b128 v[212:215], v146 offset:1024
	ds_read_b128 v[216:219], v146 offset:2048
	ds_read_b128 v[144:147], v146 offset:3072
	s_waitcnt vmcnt(0)
	s_barrier
	s_waitcnt lgkmcnt(0)
	s_setprio 1
	s_waitcnt lgkmcnt(0)
	v_mfma_f32_16x16x32_bf16 v[94:97], v[18:21], v[140:143], v[94:97]
	v_mfma_f32_16x16x32_bf16 v[18:21], v[18:21], v[216:219], v[164:167]
	v_mfma_f32_16x16x32_bf16 v[118:121], v[26:29], v[144:147], v[18:21]
	v_mfma_f32_16x16x32_bf16 v[18:21], v[34:37], v[140:143], v[86:89]
	v_mfma_f32_16x16x32_bf16 v[110:113], v[42:45], v[212:215], v[18:21]
	v_mfma_f32_16x16x32_bf16 v[18:21], v[34:37], v[216:219], v[184:187]
	v_mfma_f32_16x16x32_bf16 v[102:105], v[42:45], v[144:147], v[18:21]
	v_mfma_f32_16x16x32_bf16 v[18:21], v[50:53], v[140:143], v[78:81]
	v_mfma_f32_16x16x32_bf16 v[126:129], v[26:29], v[212:215], v[94:97]
	v_mfma_f32_16x16x32_bf16 v[94:97], v[58:61], v[212:215], v[18:21]
	v_mfma_f32_16x16x32_bf16 v[18:21], v[50:53], v[216:219], v[188:191]
	v_mfma_f32_16x16x32_bf16 v[86:89], v[58:61], v[144:147], v[18:21]
	v_mfma_f32_16x16x32_bf16 v[18:21], v[208:211], v[140:143], v[70:73]
	v_mfma_f32_16x16x32_bf16 v[78:81], v[236:239], v[212:215], v[18:21]
	v_mfma_f32_16x16x32_bf16 v[18:21], v[208:211], v[216:219], v[192:195]
	v_mfma_f32_16x16x32_bf16 v[70:73], v[236:239], v[144:147], v[18:21]
	s_setprio 0
	s_barrier
	ds_read_b128 v[164:167], v133 offset:49152
	ds_read_b128 v[184:187], v133 offset:50176
	ds_read_b128 v[188:191], v134 offset:49152
	ds_read_b128 v[192:195], v134 offset:50176
	ds_read_b128 v[208:211], v137 offset:49152
	ds_read_b128 v[220:223], v137 offset:50176
	ds_read_b128 v[236:239], v139 offset:49152
	ds_read_b128 v[240:243], v139 offset:50176
	s_barrier
	s_waitcnt lgkmcnt(0)
	s_setprio 1
	s_waitcnt lgkmcnt(0)
	v_mfma_f32_16x16x32_bf16 v[18:21], v[164:167], v[2:5], v[62:65]
	v_mfma_f32_16x16x32_bf16 v[58:61], v[184:187], v[10:13], v[18:21]
	v_mfma_f32_16x16x32_bf16 v[18:21], v[164:167], v[200:203], v[224:227]
	v_mfma_f32_16x16x32_bf16 v[50:53], v[184:187], v[204:207], v[18:21]
	v_mfma_f32_16x16x32_bf16 v[18:21], v[188:191], v[2:5], v[54:57]
	v_mfma_f32_16x16x32_bf16 v[42:45], v[192:195], v[10:13], v[18:21]
	v_mfma_f32_16x16x32_bf16 v[18:21], v[188:191], v[200:203], v[228:231]
	v_mfma_f32_16x16x32_bf16 v[34:37], v[192:195], v[204:207], v[18:21]
	v_mfma_f32_16x16x32_bf16 v[18:21], v[208:211], v[2:5], v[46:49]
	v_mfma_f32_16x16x32_bf16 v[2:5], v[236:239], v[2:5], v[38:41]
	v_mfma_f32_16x16x32_bf16 v[26:29], v[220:223], v[10:13], v[18:21]
	v_mfma_f32_16x16x32_bf16 v[18:21], v[208:211], v[200:203], v[232:235]
	v_mfma_f32_16x16x32_bf16 v[10:13], v[240:243], v[10:13], v[2:5]
	v_mfma_f32_16x16x32_bf16 v[2:5], v[236:239], v[200:203], v[148:151]
	v_mfma_f32_16x16x32_bf16 v[18:21], v[220:223], v[204:207], v[18:21]
	v_mfma_f32_16x16x32_bf16 v[2:5], v[240:243], v[204:207], v[2:5]
	s_setprio 0
	s_setprio 1
	v_mfma_f32_16x16x32_bf16 v[30:33], v[164:167], v[140:143], v[30:33]
	v_mfma_f32_16x16x32_bf16 v[62:65], v[184:187], v[212:215], v[30:33]
	v_mfma_f32_16x16x32_bf16 v[30:33], v[164:167], v[216:219], v[152:155]
	v_mfma_f32_16x16x32_bf16 v[22:25], v[188:191], v[140:143], v[22:25]
	v_mfma_f32_16x16x32_bf16 v[14:17], v[208:211], v[140:143], v[14:17]
	v_mfma_f32_16x16x32_bf16 v[54:57], v[184:187], v[144:147], v[30:33]
	v_mfma_f32_16x16x32_bf16 v[46:49], v[192:195], v[212:215], v[22:25]
	v_mfma_f32_16x16x32_bf16 v[22:25], v[188:191], v[216:219], v[156:159]
	v_mfma_f32_16x16x32_bf16 v[30:33], v[220:223], v[212:215], v[14:17]
	v_mfma_f32_16x16x32_bf16 v[14:17], v[208:211], v[216:219], v[160:163]
	v_mfma_f32_16x16x32_bf16 v[6:9], v[236:239], v[140:143], v[6:9]
	v_mfma_f32_16x16x32_bf16 v[38:41], v[192:195], v[144:147], v[22:25]
	v_mfma_f32_16x16x32_bf16 v[22:25], v[220:223], v[144:147], v[14:17]
	v_mfma_f32_16x16x32_bf16 v[14:17], v[240:243], v[212:215], v[6:9]
	v_mfma_f32_16x16x32_bf16 v[6:9], v[236:239], v[216:219], v[196:199]
	v_mfma_f32_16x16x32_bf16 v[6:9], v[240:243], v[144:147], v[6:9]
	s_setprio 0
	v_readlane_b32 s4, v245, 33
	v_readlane_b32 s5, v245, 34
	s_and_b64 vcc, exec, s[4:5]
	s_barrier
	s_cbranch_vccz .LBB0_158
	s_barrier

; #define WAIT_V(n) asm volatile("s_waitcnt vmcnt(" #n ")" ::: "memory")
; #define BAR __builtin_amdgcn_s_barrier()
;     ...
;     STAGE(SB(0, 0), Bt, bcol, 0); STAGE(SA(0, 0), A, brow, 0);
;     STAGE(SB(0, 1), Bt, bcol + HALF, 0); STAGE(SA(0, 1), A, brow + HALF, 0);
;     if (wr == 1) BAR;
;     WAIT_V(4); BAR;
;     STAGE(SB(1, 0), Bt, bcol, 1); STAGE(SA(1, 0), A, brow, 1); STAGE(SB(1, 1), Bt, bcol + HALF, 1);
;     WAIT_V(6); BAR;
;     for (int t = 0; t < nt - 2; t += 2) {
.LBB0_201:
	s_or_b32 s40, s48, 1
	s_mov_b32 s41, s49
	s_lshl_b64 s[44:45], s[40:41], 6
	s_add_u32 s4, s44, s4
	s_addc_u32 s5, s45, s5
	s_lshl_b64 s[4:5], s[4:5], 1
	s_add_u32 s4, s22, s4
	s_addc_u32 s5, s23, s5
	s_add_i32 s39, s21, 0x18000
	v_mov_b32_e32 v141, v1
	s_waitcnt vmcnt(4)
	s_barrier
	s_mov_b32 m0, s39
	v_lshl_add_u64 v[4:5], s[4:5], 0, v[0:1]
	s_add_i32 s40, s21, 0x1a000
	global_load_lds_dwordx4 v[4:5], off
	v_lshl_add_u64 v[4:5], s[4:5], 0, v[140:141]
	s_add_u32 s4, s44, s16
	s_addc_u32 s5, s45, s17
	s_lshl_b64 s[4:5], s[4:5], 1
	s_add_u32 s4, s74, s4
	s_mov_b32 m0, s40
	s_addc_u32 s5, s75, s5
	s_add_i32 s41, s21, 0x8000
	global_load_lds_dwordx4 v[4:5], off
	s_mov_b32 m0, s41
	v_lshl_add_u64 v[4:5], s[4:5], 0, v[0:1]
	s_add_i32 s42, s21, 0xa000
	global_load_lds_dwordx4 v[4:5], off
	v_lshl_add_u64 v[4:5], s[4:5], 0, v[140:141]
	s_add_u32 s4, s44, s18
	s_addc_u32 s5, s45, s19
	s_lshl_b64 s[4:5], s[4:5], 1
	s_add_u32 s4, s22, s4
	s_mov_b32 m0, s42
	s_addc_u32 s5, s23, s5
	s_add_i32 s18, s21, 0x1c000
	global_load_lds_dwordx4 v[4:5], off
	s_mov_b32 m0, s18
	v_lshl_add_u64 v[4:5], s[4:5], 0, v[0:1]
	s_add_i32 s19, s21, 0x1e000
	global_load_lds_dwordx4 v[4:5], off
	v_lshl_add_u64 v[4:5], s[4:5], 0, v[140:141]
	s_mov_b32 m0, s19
	v_and_b32_e32 v3, 15, v2
	global_load_lds_dwordx4 v[4:5], off
	v_and_b32_e32 v6, 48, v2
	v_lshlrev_b32_e32 v2, 2, v2
	v_lshlrev_b32_e32 v4, 6, v3
	v_and_b32_e32 v2, 32, v2
	v_bitop3_b32 v142, v4, v2, v6 bitop3:0x36
	v_or_b32_e32 v2, s33, v3
	v_lshlrev_b32_e32 v4, 6, v2
	v_lshlrev_b32_e32 v2, 2, v2
	s_lshl_b64 s[4:5], s[10:11], 12
	v_and_b32_e32 v4, 0x3c0, v4
	v_and_b32_e32 v2, 32, v2
	v_readlane_b32 s11, v245, 36
	s_add_i32 s43, s20, -2
	v_bitop3_b32 v4, v4, v2, v6 bitop3:0x36
	v_or_b32_e32 v2, s11, v3
	s_add_u32 s55, s74, s4
	v_lshlrev_b32_e32 v5, 6, v2
	v_lshlrev_b32_e32 v2, 2, v2
	s_addc_u32 s57, s75, s5
	v_and_b32_e32 v5, 0x3c0, v5
	v_and_b32_e32 v2, 32, v2
	v_readlane_b32 s11, v245, 37
	s_lshl_b64 s[16:17], s[48:49], 7
	s_lshl_b64 s[44:45], s[14:15], 12
	v_bitop3_b32 v5, v5, v2, v6 bitop3:0x36
	v_or_b32_e32 v2, s11, v3
	s_add_u32 s11, s22, s44
	s_addc_u32 s44, s23, s45
	s_lshl_b64 s[50:51], s[12:13], 12
	s_add_u32 s13, s74, s50
	v_lshlrev_b32_e32 v7, 6, v2
	v_lshlrev_b32_e32 v2, 2, v2
	s_addc_u32 s45, s75, s51
	v_and_b32_e32 v7, 0x3c0, v7
	v_and_b32_e32 v2, 32, v2
	s_add_u32 s50, s55, 0x80
	v_bitop3_b32 v7, v7, v2, v6 bitop3:0x36
	v_or_b32_e32 v2, s85, v3
	s_addc_u32 s51, s57, 0
	v_readlane_b32 s57, v244, 19
	v_lshlrev_b32_e32 v3, 6, v2
	v_lshlrev_b32_e32 v2, 2, v2
	v_add_u32_e32 v133, s57, v4
	v_readlane_b32 s57, v244, 20
	s_waitcnt vmcnt(6)
	v_and_b32_e32 v3, 0x3c0, v3
	v_and_b32_e32 v2, 32, v2
	v_add_u32_e32 v134, s57, v5
	v_readlane_b32 s57, v244, 21
	v_bitop3_b32 v3, v3, v2, v6 bitop3:0x36
	v_mov_b32_e32 v2, 0
	v_add_u32_e32 v137, s57, v7
	v_readlane_b32 s57, v244, 22
	s_mov_b32 s55, 0
	v_mov_b32_e32 v4, v2
	v_add_u32_e32 v139, s57, v3
	v_mov_b32_e32 v3, v2
	v_mov_b32_e32 v5, v2
	v_mov_b32_e32 v6, v2
	v_mov_b32_e32 v7, v2
	v_mov_b32_e32 v8, v2
	v_mov_b32_e32 v9, v2
	v_mov_b32_e32 v10, v2
	v_mov_b32_e32 v11, v2
	v_mov_b32_e32 v12, v2
	v_mov_b32_e32 v13, v2
	v_mov_b32_e32 v14, v2
	v_mov_b32_e32 v15, v2
	v_mov_b32_e32 v16, v2
	v_mov_b32_e32 v17, v2
	v_mov_b32_e32 v18, v2
	v_mov_b32_e32 v19, v2
	v_mov_b32_e32 v20, v2
	v_mov_b32_e32 v21, v2
	v_mov_b32_e32 v22, v2
	v_mov_b32_e32 v23, v2
	v_mov_b32_e32 v24, v2
	v_mov_b32_e32 v25, v2
	v_mov_b32_e32 v26, v2
	v_mov_b32_e32 v27, v2
	v_mov_b32_e32 v28, v2
	v_mov_b32_e32 v29, v2
	v_mov_b32_e32 v30, v2
	v_mov_b32_e32 v31, v2
	v_mov_b32_e32 v32, v2
	v_mov_b32_e32 v33, v2
	v_mov_b32_e32 v34, v2
	v_mov_b32_e32 v35, v2
	v_mov_b32_e32 v36, v2
	v_mov_b32_e32 v37, v2
	v_mov_b32_e32 v38, v2
	v_mov_b32_e32 v39, v2
	v_mov_b32_e32 v40, v2
	v_mov_b32_e32 v41, v2
	v_mov_b32_e32 v42, v2
	v_mov_b32_e32 v43, v2
	v_mov_b32_e32 v44, v2
	v_mov_b32_e32 v45, v2
	v_mov_b32_e32 v46, v2
	v_mov_b32_e32 v47, v2
	v_mov_b32_e32 v48, v2
	v_mov_b32_e32 v49, v2
	v_mov_b32_e32 v50, v2
	v_mov_b32_e32 v51, v2
	v_mov_b32_e32 v52, v2
	v_mov_b32_e32 v53, v2
	v_mov_b32_e32 v54, v2
	v_mov_b32_e32 v55, v2
	v_mov_b32_e32 v56, v2
	v_mov_b32_e32 v57, v2
	v_mov_b32_e32 v58, v2
	v_mov_b32_e32 v59, v2
	v_mov_b32_e32 v60, v2
	v_mov_b32_e32 v61, v2
	v_mov_b32_e32 v62, v2
	v_mov_b32_e32 v63, v2
	v_mov_b32_e32 v64, v2
	v_mov_b32_e32 v65, v2
	v_mov_b32_e32 v66, v2
	v_mov_b32_e32 v67, v2
	v_mov_b32_e32 v68, v2
	v_mov_b32_e32 v69, v2
	v_mov_b32_e32 v70, v2
	v_mov_b32_e32 v71, v2
	v_mov_b32_e32 v72, v2
	v_mov_b32_e32 v73, v2
	v_mov_b32_e32 v74, v2
	v_mov_b32_e32 v75, v2
	v_mov_b32_e32 v76, v2
	v_mov_b32_e32 v77, v2
	v_mov_b32_e32 v78, v2
	v_mov_b32_e32 v79, v2
	v_mov_b32_e32 v80, v2
	v_mov_b32_e32 v81, v2
	v_mov_b32_e32 v82, v2
	v_mov_b32_e32 v83, v2
	v_mov_b32_e32 v84, v2
	v_mov_b32_e32 v85, v2
	v_mov_b32_e32 v86, v2
	v_mov_b32_e32 v87, v2
	v_mov_b32_e32 v88, v2
	v_mov_b32_e32 v89, v2
	v_mov_b32_e32 v90, v2
	v_mov_b32_e32 v91, v2
	v_mov_b32_e32 v92, v2
	v_mov_b32_e32 v93, v2
	v_mov_b32_e32 v94, v2
	v_mov_b32_e32 v95, v2
	v_mov_b32_e32 v96, v2
	v_mov_b32_e32 v97, v2
	v_mov_b32_e32 v98, v2
	v_mov_b32_e32 v99, v2
	v_mov_b32_e32 v100, v2
	v_mov_b32_e32 v101, v2
	v_mov_b32_e32 v102, v2
	v_mov_b32_e32 v103, v2
	v_mov_b32_e32 v104, v2
	v_mov_b32_e32 v105, v2
	v_mov_b32_e32 v106, v2
	v_mov_b32_e32 v107, v2
	v_mov_b32_e32 v108, v2
	v_mov_b32_e32 v109, v2
	v_mov_b32_e32 v110, v2
	v_mov_b32_e32 v111, v2
	v_mov_b32_e32 v112, v2
	v_mov_b32_e32 v113, v2
	v_mov_b32_e32 v114, v2
	v_mov_b32_e32 v115, v2
	v_mov_b32_e32 v116, v2
	v_mov_b32_e32 v117, v2
	v_mov_b32_e32 v118, v2
	v_mov_b32_e32 v119, v2
	v_mov_b32_e32 v120, v2
	v_mov_b32_e32 v121, v2
	v_mov_b32_e32 v122, v2
	v_mov_b32_e32 v123, v2
	v_mov_b32_e32 v124, v2
	v_mov_b32_e32 v125, v2
	v_mov_b32_e32 v126, v2
	v_mov_b32_e32 v127, v2
	v_mov_b32_e32 v128, v2
	v_mov_b32_e32 v129, v2
	v_readlane_b32 vcc_lo, v245, 30
	s_nop 0
	s_cmpk_lt_u32 vcc_lo, 0x1000
	s_cbranch_scc1 .Lgp_202
	s_setprio 1

; #define LDA(dst, b, h) for (int m = 0; m < 4; ++m) for (int k = 0; k < 2; ++k) \
;     dst[m][k] = *reinterpret_cast<const bf16x8*>((char*)SA(b, h) + lds_byte(wr * 64 + m * 16 + fr, k * 32 + fq * 8))
; #define LDB(dst, b, h) for (int n = 0; n < 2; ++n) for (int k = 0; k < 2; ++k) \
;     dst[n][k] = *reinterpret_cast<const bf16x8*>((char*)SB(b, h) + lds_byte(wc * 32 + n * 16 + fr, k * 32 + fq * 8))
; #define MMA(ai, bj, At, Bt_) do { __builtin_amdgcn_s_setprio(1); \
;     for (int m = 0; m < 4; ++m) for (int n = 0; n < 2; ++n) for (int k = 0; k < 2; ++k) \
;       acc[ai][bj][m][n] = __builtin_amdgcn_mfma_f32_16x16x32_bf16(At[m][k], Bt_[n][k], acc[ai][bj][m][n], 0, 0, 0); \
;     __builtin_amdgcn_s_setprio(0); } while (0)
; #define WAIT_L(n) asm volatile("s_waitcnt lgkmcnt(" #n ")" ::: "memory")
; #define BAR __builtin_amdgcn_s_barrier()
; #define SCHED __builtin_amdgcn_sched_barrier(0)
;     ...
;       LDB(B0, 0, 0); SCHED; LDA(At, 0, 0); STAGE(SA(1, 1), A, brow + HALF, t + 1);
;       WAIT_L(8); BAR; WAIT_L(0); MMA(0, 0, At, B0); BAR; SCHED;
;       LDB(B1, 0, 1); STAGE(SB(0, 0), Bt, bcol, t + 2);
;       BAR; WAIT_L(0); MMA(0, 1, At, B1); BAR;
;       LDA(At, 0, 1); STAGE(SA(0, 0), A, brow, t + 2);
;       BAR; WAIT_L(0); MMA(1, 0, At, B0); BAR; SCHED;
.LBB0_202:
	v_add_u32_e32 v143, s2, v142
	ds_read_b128 v[146:149], v143
	ds_read_b128 v[150:153], v143 offset:1024
	ds_read_b128 v[154:157], v143 offset:2048
	ds_read_b128 v[158:161], v143 offset:3072
	s_add_u32 s66, s50, s16
	s_addc_u32 s67, s51, s17
	s_add_i32 s58, s21, 0xc000
	ds_read_b128 v[162:165], v133
	ds_read_b128 v[184:187], v133 offset:1024
	ds_read_b128 v[188:191], v134
	ds_read_b128 v[192:195], v134 offset:1024
	ds_read_b128 v[196:199], v137
	ds_read_b128 v[200:203], v137 offset:1024
	ds_read_b128 v[204:207], v139
	ds_read_b128 v[208:211], v139 offset:1024
	s_mov_b32 m0, s58
	v_lshl_add_u64 v[144:145], s[66:67], 0, v[0:1]
	s_add_i32 s57, s21, 0xe000
	global_load_lds_dwordx4 v[144:145], off
	v_lshl_add_u64 v[144:145], s[66:67], 0, v[140:141]
	s_mov_b32 m0, s57
	s_nop 0
	global_load_lds_dwordx4 v[144:145], off
	s_waitcnt lgkmcnt(8)
	s_barrier
	s_waitcnt lgkmcnt(0)
	s_waitcnt lgkmcnt(0)
	v_mfma_f32_16x16x32_bf16 v[126:129], v[162:165], v[146:149], v[126:129]
	v_mfma_f32_16x16x32_bf16 v[122:125], v[162:165], v[154:157], v[122:125]
	v_mfma_f32_16x16x32_bf16 v[118:121], v[188:191], v[146:149], v[118:121]
	v_mfma_f32_16x16x32_bf16 v[114:117], v[188:191], v[154:157], v[114:117]
	v_mfma_f32_16x16x32_bf16 v[110:113], v[196:199], v[146:149], v[110:113]
	v_mfma_f32_16x16x32_bf16 v[106:109], v[196:199], v[154:157], v[106:109]
	v_mfma_f32_16x16x32_bf16 v[102:105], v[204:207], v[146:149], v[102:105]
	v_mfma_f32_16x16x32_bf16 v[98:101], v[204:207], v[154:157], v[98:101]
	v_mfma_f32_16x16x32_bf16 v[126:129], v[184:187], v[150:153], v[126:129]
	v_mfma_f32_16x16x32_bf16 v[122:125], v[184:187], v[158:161], v[122:125]
	v_mfma_f32_16x16x32_bf16 v[118:121], v[192:195], v[150:153], v[118:121]
	v_mfma_f32_16x16x32_bf16 v[114:117], v[192:195], v[158:161], v[114:117]
	v_mfma_f32_16x16x32_bf16 v[110:113], v[200:203], v[150:153], v[110:113]
	v_mfma_f32_16x16x32_bf16 v[106:109], v[200:203], v[158:161], v[106:109]
	v_mfma_f32_16x16x32_bf16 v[102:105], v[208:211], v[150:153], v[102:105]
	v_mfma_f32_16x16x32_bf16 v[98:101], v[208:211], v[158:161], v[98:101]
	s_barrier
	s_add_i32 s55, s55, 2
	s_add_u32 s59, s11, s16
	s_addc_u32 s63, s44, s17
	s_add_u32 s66, s59, 0x100
	v_add_u32_e32 v144, s76, v142
	s_addc_u32 s67, s63, 0
	s_mov_b32 m0, s29
	ds_read_b128 v[212:215], v144
	ds_read_b128 v[216:219], v144 offset:1024
	ds_read_b128 v[220:223], v144 offset:2048
	ds_read_b128 v[224:227], v144 offset:3072
	s_nop 0
	v_lshl_add_u64 v[166:167], s[66:67], 0, v[0:1]
	global_load_lds_dwordx4 v[166:167], off
	v_lshl_add_u64 v[166:167], s[66:67], 0, v[140:141]
	s_mov_b32 m0, s30
	s_nop 0
	global_load_lds_dwordx4 v[166:167], off
	s_barrier
	s_waitcnt lgkmcnt(0)
	s_waitcnt lgkmcnt(0)
	v_mfma_f32_16x16x32_bf16 v[94:97], v[162:165], v[212:215], v[94:97]
	v_mfma_f32_16x16x32_bf16 v[90:93], v[162:165], v[220:223], v[90:93]
	v_mfma_f32_16x16x32_bf16 v[86:89], v[188:191], v[212:215], v[86:89]
	v_mfma_f32_16x16x32_bf16 v[82:85], v[188:191], v[220:223], v[82:85]
	v_mfma_f32_16x16x32_bf16 v[78:81], v[196:199], v[212:215], v[78:81]
	v_mfma_f32_16x16x32_bf16 v[74:77], v[196:199], v[220:223], v[74:77]
	v_mfma_f32_16x16x32_bf16 v[70:73], v[204:207], v[212:215], v[70:73]
	v_mfma_f32_16x16x32_bf16 v[66:69], v[204:207], v[220:223], v[66:69]
	v_mfma_f32_16x16x32_bf16 v[94:97], v[184:187], v[216:219], v[94:97]
	v_mfma_f32_16x16x32_bf16 v[90:93], v[184:187], v[224:227], v[90:93]
	v_mfma_f32_16x16x32_bf16 v[86:89], v[192:195], v[216:219], v[86:89]
	v_mfma_f32_16x16x32_bf16 v[82:85], v[192:195], v[224:227], v[82:85]
	v_mfma_f32_16x16x32_bf16 v[78:81], v[200:203], v[216:219], v[78:81]
	v_mfma_f32_16x16x32_bf16 v[74:77], v[200:203], v[224:227], v[74:77]
	v_mfma_f32_16x16x32_bf16 v[70:73], v[208:211], v[216:219], v[70:73]
	v_mfma_f32_16x16x32_bf16 v[66:69], v[208:211], v[224:227], v[66:69]
	s_add_u32 s65, s13, s16
	s_addc_u32 s70, s45, s17
	s_add_u32 s66, s65, 0x100
	s_addc_u32 s67, s70, 0
	s_mov_b32 m0, s21
	s_barrier
	ds_read_b128 v[162:165], v133 offset:16384
	ds_read_b128 v[184:187], v133 offset:17408
	ds_read_b128 v[188:191], v134 offset:16384
	ds_read_b128 v[192:195], v134 offset:17408
	ds_read_b128 v[196:199], v137 offset:16384
	ds_read_b128 v[200:203], v137 offset:17408
	ds_read_b128 v[204:207], v139 offset:16384
	ds_read_b128 v[208:211], v139 offset:17408
	s_nop 0
	v_lshl_add_u64 v[166:167], s[66:67], 0, v[0:1]
	global_load_lds_dwordx4 v[166:167], off
	v_lshl_add_u64 v[166:167], s[66:67], 0, v[140:141]
	s_mov_b32 m0, s31
	s_nop 0
	global_load_lds_dwordx4 v[166:167], off
	s_barrier
	s_waitcnt lgkmcnt(0)
	s_waitcnt lgkmcnt(0)
	v_mfma_f32_16x16x32_bf16 v[62:65], v[162:165], v[146:149], v[62:65]
	v_mfma_f32_16x16x32_bf16 v[58:61], v[162:165], v[154:157], v[58:61]
	v_mfma_f32_16x16x32_bf16 v[54:57], v[188:191], v[146:149], v[54:57]
	v_mfma_f32_16x16x32_bf16 v[50:53], v[188:191], v[154:157], v[50:53]
	v_mfma_f32_16x16x32_bf16 v[46:49], v[196:199], v[146:149], v[46:49]
	v_mfma_f32_16x16x32_bf16 v[42:45], v[196:199], v[154:157], v[42:45]
	v_mfma_f32_16x16x32_bf16 v[38:41], v[204:207], v[146:149], v[38:41]
	v_mfma_f32_16x16x32_bf16 v[34:37], v[204:207], v[154:157], v[34:37]
	v_mfma_f32_16x16x32_bf16 v[62:65], v[184:187], v[150:153], v[62:65]
	v_mfma_f32_16x16x32_bf16 v[58:61], v[184:187], v[158:161], v[58:61]
	v_mfma_f32_16x16x32_bf16 v[54:57], v[192:195], v[150:153], v[54:57]
	v_mfma_f32_16x16x32_bf16 v[50:53], v[192:195], v[158:161], v[50:53]
	v_mfma_f32_16x16x32_bf16 v[46:49], v[200:203], v[150:153], v[46:49]
	v_mfma_f32_16x16x32_bf16 v[42:45], v[200:203], v[158:161], v[42:45]
	v_mfma_f32_16x16x32_bf16 v[38:41], v[208:211], v[150:153], v[38:41]
	v_mfma_f32_16x16x32_bf16 v[34:37], v[208:211], v[158:161], v[34:37]
	s_barrier
; #define LDA(dst, b, h) for (int m = 0; m < 4; ++m) for (int k = 0; k < 2; ++k) \
;     dst[m][k] = *reinterpret_cast<const bf16x8*>((char*)SA(b, h) + lds_byte(wr * 64 + m * 16 + fr, k * 32 + fq * 8))
; #define LDB(dst, b, h) for (int n = 0; n < 2; ++n) for (int k = 0; k < 2; ++k) \
;     dst[n][k] = *reinterpret_cast<const bf16x8*>((char*)SB(b, h) + lds_byte(wc * 32 + n * 16 + fr, k * 32 + fq * 8))
; #define MMA(ai, bj, At, Bt_) do { __builtin_amdgcn_s_setprio(1); \
;     for (int m = 0; m < 4; ++m) for (int n = 0; n < 2; ++n) for (int k = 0; k < 2; ++k) \
;       acc[ai][bj][m][n] = __builtin_amdgcn_mfma_f32_16x16x32_bf16(At[m][k], Bt_[n][k], acc[ai][bj][m][n], 0, 0, 0); \
;     __builtin_amdgcn_s_setprio(0); } while (0)
; #define WAIT_V(n) asm volatile("s_waitcnt vmcnt(" #n ")" ::: "memory")
; #define WAIT_L(n) asm volatile("s_waitcnt lgkmcnt(" #n ")" ::: "memory")
; #define BAR __builtin_amdgcn_s_barrier()
; #define SCHED __builtin_amdgcn_sched_barrier(0)
;     ...
;       STAGE(SB(0, 1), Bt, bcol + HALF, t + 2);
;       WAIT_V(6); BAR; MMA(1, 1, At, B1); BAR;
;       LDB(B0, 1, 0); SCHED; LDA(At, 1, 0); STAGE(SA(0, 1), A, brow + HALF, t + 2);
;       WAIT_L(8); BAR; WAIT_L(0); MMA(0, 0, At, B0); BAR; SCHED;
;       LDB(B1, 1, 1); STAGE(SB(1, 0), Bt, bcol, t + 3);
;       BAR; WAIT_L(0); MMA(0, 1, At, B1); BAR;
;       LDA(At, 1, 1); STAGE(SA(1, 0), A, brow, t + 3);
	s_add_u32 s66, s59, 0x80100
	s_addc_u32 s67, s63, 0
	s_mov_b32 m0, s34
	s_nop 0
	v_lshl_add_u64 v[146:147], s[66:67], 0, v[0:1]
	global_load_lds_dwordx4 v[146:147], off
	v_lshl_add_u64 v[146:147], s[66:67], 0, v[140:141]
	s_mov_b32 m0, s35
	s_nop 0
	global_load_lds_dwordx4 v[146:147], off
	s_waitcnt vmcnt(6)
	s_barrier
	v_mfma_f32_16x16x32_bf16 v[30:33], v[162:165], v[212:215], v[30:33]
	v_mfma_f32_16x16x32_bf16 v[26:29], v[162:165], v[220:223], v[26:29]
	v_mfma_f32_16x16x32_bf16 v[22:25], v[188:191], v[212:215], v[22:25]
	v_mfma_f32_16x16x32_bf16 v[18:21], v[188:191], v[220:223], v[18:21]
	v_mfma_f32_16x16x32_bf16 v[14:17], v[196:199], v[212:215], v[14:17]
	v_mfma_f32_16x16x32_bf16 v[10:13], v[196:199], v[220:223], v[10:13]
	v_mfma_f32_16x16x32_bf16 v[6:9], v[204:207], v[212:215], v[6:9]
	v_mfma_f32_16x16x32_bf16 v[2:5], v[204:207], v[220:223], v[2:5]
	v_mfma_f32_16x16x32_bf16 v[30:33], v[184:187], v[216:219], v[30:33]
	v_mfma_f32_16x16x32_bf16 v[26:29], v[184:187], v[224:227], v[26:29]
	v_mfma_f32_16x16x32_bf16 v[22:25], v[192:195], v[216:219], v[22:25]
	v_mfma_f32_16x16x32_bf16 v[18:21], v[192:195], v[224:227], v[18:21]
	v_mfma_f32_16x16x32_bf16 v[14:17], v[200:203], v[216:219], v[14:17]
	v_mfma_f32_16x16x32_bf16 v[10:13], v[200:203], v[224:227], v[10:13]
	v_mfma_f32_16x16x32_bf16 v[6:9], v[208:211], v[216:219], v[6:9]
	v_mfma_f32_16x16x32_bf16 v[2:5], v[208:211], v[224:227], v[2:5]
	v_add_u32_e32 v145, s77, v142
	s_barrier
	ds_read_b128 v[148:151], v145
	ds_read_b128 v[152:155], v145 offset:1024
	ds_read_b128 v[156:159], v145 offset:2048
	ds_read_b128 v[160:163], v145 offset:3072
	s_add_u32 s66, s65, 0x80100
	s_addc_u32 s67, s70, 0
	s_mov_b32 m0, s37
	ds_read_b128 v[164:167], v133 offset:32768
	ds_read_b128 v[184:187], v133 offset:33792
	ds_read_b128 v[188:191], v134 offset:32768
	ds_read_b128 v[192:195], v134 offset:33792
	ds_read_b128 v[196:199], v137 offset:32768
	ds_read_b128 v[200:203], v137 offset:33792
	ds_read_b128 v[204:207], v139 offset:32768
	ds_read_b128 v[208:211], v139 offset:33792
	s_nop 0
	v_lshl_add_u64 v[146:147], s[66:67], 0, v[0:1]
	global_load_lds_dwordx4 v[146:147], off
	v_lshl_add_u64 v[146:147], s[66:67], 0, v[140:141]
	s_mov_b32 m0, s38
	s_nop 0
	global_load_lds_dwordx4 v[146:147], off
	s_waitcnt lgkmcnt(8)
	s_barrier
	s_waitcnt lgkmcnt(0)
	s_waitcnt lgkmcnt(0)
	v_mfma_f32_16x16x32_bf16 v[126:129], v[164:167], v[148:151], v[126:129]
	v_mfma_f32_16x16x32_bf16 v[122:125], v[164:167], v[156:159], v[122:125]
	v_mfma_f32_16x16x32_bf16 v[118:121], v[188:191], v[148:151], v[118:121]
	v_mfma_f32_16x16x32_bf16 v[114:117], v[188:191], v[156:159], v[114:117]
	v_mfma_f32_16x16x32_bf16 v[110:113], v[196:199], v[148:151], v[110:113]
	v_mfma_f32_16x16x32_bf16 v[106:109], v[196:199], v[156:159], v[106:109]
	v_mfma_f32_16x16x32_bf16 v[102:105], v[204:207], v[148:151], v[102:105]
	v_mfma_f32_16x16x32_bf16 v[98:101], v[204:207], v[156:159], v[98:101]
	v_mfma_f32_16x16x32_bf16 v[126:129], v[184:187], v[152:155], v[126:129]
	v_mfma_f32_16x16x32_bf16 v[122:125], v[184:187], v[160:163], v[122:125]
	v_mfma_f32_16x16x32_bf16 v[118:121], v[192:195], v[152:155], v[118:121]
	v_mfma_f32_16x16x32_bf16 v[114:117], v[192:195], v[160:163], v[114:117]
	v_mfma_f32_16x16x32_bf16 v[110:113], v[200:203], v[152:155], v[110:113]
	v_mfma_f32_16x16x32_bf16 v[106:109], v[200:203], v[160:163], v[106:109]
	v_mfma_f32_16x16x32_bf16 v[102:105], v[208:211], v[152:155], v[102:105]
	v_mfma_f32_16x16x32_bf16 v[98:101], v[208:211], v[160:163], v[98:101]
	s_barrier
	s_add_u32 s66, s59, 0x180
	v_add_u32_e32 v146, s78, v142
	s_addc_u32 s67, s63, 0
	s_mov_b32 m0, s39
	ds_read_b128 v[212:215], v146
	ds_read_b128 v[216:219], v146 offset:1024
	ds_read_b128 v[220:223], v146 offset:2048
	ds_read_b128 v[224:227], v146 offset:3072
	s_nop 0
	v_lshl_add_u64 v[228:229], s[66:67], 0, v[0:1]
	global_load_lds_dwordx4 v[228:229], off
	v_lshl_add_u64 v[228:229], s[66:67], 0, v[140:141]
	s_mov_b32 m0, s40
	s_nop 0
	global_load_lds_dwordx4 v[228:229], off
	s_barrier
	s_waitcnt lgkmcnt(0)
	s_waitcnt lgkmcnt(0)
	v_mfma_f32_16x16x32_bf16 v[94:97], v[164:167], v[212:215], v[94:97]
	v_mfma_f32_16x16x32_bf16 v[90:93], v[164:167], v[220:223], v[90:93]
	v_mfma_f32_16x16x32_bf16 v[86:89], v[188:191], v[212:215], v[86:89]
	v_mfma_f32_16x16x32_bf16 v[82:85], v[188:191], v[220:223], v[82:85]
	v_mfma_f32_16x16x32_bf16 v[78:81], v[196:199], v[212:215], v[78:81]
	v_mfma_f32_16x16x32_bf16 v[74:77], v[196:199], v[220:223], v[74:77]
	v_mfma_f32_16x16x32_bf16 v[70:73], v[204:207], v[212:215], v[70:73]
	v_mfma_f32_16x16x32_bf16 v[66:69], v[204:207], v[220:223], v[66:69]
	v_mfma_f32_16x16x32_bf16 v[94:97], v[184:187], v[216:219], v[94:97]
	v_mfma_f32_16x16x32_bf16 v[90:93], v[184:187], v[224:227], v[90:93]
	v_mfma_f32_16x16x32_bf16 v[86:89], v[192:195], v[216:219], v[86:89]
	v_mfma_f32_16x16x32_bf16 v[82:85], v[192:195], v[224:227], v[82:85]
	v_mfma_f32_16x16x32_bf16 v[78:81], v[200:203], v[216:219], v[78:81]
	v_mfma_f32_16x16x32_bf16 v[74:77], v[200:203], v[224:227], v[74:77]
	v_mfma_f32_16x16x32_bf16 v[70:73], v[208:211], v[216:219], v[70:73]
	v_mfma_f32_16x16x32_bf16 v[66:69], v[208:211], v[224:227], v[66:69]
	s_add_u32 s66, s65, 0x180
	s_addc_u32 s67, s70, 0
	s_mov_b32 m0, s41
	s_barrier
	ds_read_b128 v[164:167], v133 offset:49152
	ds_read_b128 v[184:187], v133 offset:50176
	ds_read_b128 v[188:191], v134 offset:49152
	ds_read_b128 v[192:195], v134 offset:50176
	ds_read_b128 v[196:199], v137 offset:49152
	ds_read_b128 v[200:203], v137 offset:50176
	ds_read_b128 v[204:207], v139 offset:49152
	ds_read_b128 v[208:211], v139 offset:50176
	s_nop 0
	v_lshl_add_u64 v[228:229], s[66:67], 0, v[0:1]
	global_load_lds_dwordx4 v[228:229], off
	v_lshl_add_u64 v[228:229], s[66:67], 0, v[140:141]
	s_mov_b32 m0, s42
	s_nop 0
	global_load_lds_dwordx4 v[228:229], off
	s_barrier
; #define LDA(dst, b, h) for (int m = 0; m < 4; ++m) for (int k = 0; k < 2; ++k) \
;     dst[m][k] = *reinterpret_cast<const bf16x8*>((char*)SA(b, h) + lds_byte(wr * 64 + m * 16 + fr, k * 32 + fq * 8))
; #define LDB(dst, b, h) for (int n = 0; n < 2; ++n) for (int k = 0; k < 2; ++k) \
;     dst[n][k] = *reinterpret_cast<const bf16x8*>((char*)SB(b, h) + lds_byte(wc * 32 + n * 16 + fr, k * 32 + fq * 8))
; #define MMA(ai, bj, At, Bt_) do { __builtin_amdgcn_s_setprio(1); \
;     for (int m = 0; m < 4; ++m) for (int n = 0; n < 2; ++n) for (int k = 0; k < 2; ++k) \
;       acc[ai][bj][m][n] = __builtin_amdgcn_mfma_f32_16x16x32_bf16(At[m][k], Bt_[n][k], acc[ai][bj][m][n], 0, 0, 0); \
;     __builtin_amdgcn_s_setprio(0); } while (0)
; #define WAIT_V(n) asm volatile("s_waitcnt vmcnt(" #n ")" ::: "memory")
; #define WAIT_L(n) asm volatile("s_waitcnt lgkmcnt(" #n ")" ::: "memory")
; #define BAR __builtin_amdgcn_s_barrier()
; #define SCHED __builtin_amdgcn_sched_barrier(0)
;     ...
;       BAR; WAIT_L(0); MMA(1, 0, At, B0); BAR; SCHED;
;       STAGE(SB(1, 1), Bt, bcol + HALF, t + 3);
;       WAIT_V(6); BAR; MMA(1, 1, At, B1); BAR;
;     }
;     { LDB(B0, 0, 0); LDA(At, 0, 0); STAGE(SA(1, 1), A, brow + HALF, nt - 1);
;       BAR; WAIT_L(0); MMA(0, 0, At, B0); BAR;
;       LDB(B1, 0, 1); BAR; WAIT_L(0); MMA(0, 1, At, B1); BAR;
	s_waitcnt lgkmcnt(0)
	s_waitcnt lgkmcnt(0)
	v_mfma_f32_16x16x32_bf16 v[62:65], v[164:167], v[148:151], v[62:65]
	v_mfma_f32_16x16x32_bf16 v[58:61], v[164:167], v[156:159], v[58:61]
	v_mfma_f32_16x16x32_bf16 v[54:57], v[188:191], v[148:151], v[54:57]
	v_mfma_f32_16x16x32_bf16 v[50:53], v[188:191], v[156:159], v[50:53]
	v_mfma_f32_16x16x32_bf16 v[46:49], v[196:199], v[148:151], v[46:49]
	v_mfma_f32_16x16x32_bf16 v[42:45], v[196:199], v[156:159], v[42:45]
	v_mfma_f32_16x16x32_bf16 v[38:41], v[204:207], v[148:151], v[38:41]
	v_mfma_f32_16x16x32_bf16 v[34:37], v[204:207], v[156:159], v[34:37]
	v_mfma_f32_16x16x32_bf16 v[62:65], v[184:187], v[152:155], v[62:65]
	v_mfma_f32_16x16x32_bf16 v[58:61], v[184:187], v[160:163], v[58:61]
	v_mfma_f32_16x16x32_bf16 v[54:57], v[192:195], v[152:155], v[54:57]
	v_mfma_f32_16x16x32_bf16 v[50:53], v[192:195], v[160:163], v[50:53]
	v_mfma_f32_16x16x32_bf16 v[46:49], v[200:203], v[152:155], v[46:49]
	v_mfma_f32_16x16x32_bf16 v[42:45], v[200:203], v[160:163], v[42:45]
	v_mfma_f32_16x16x32_bf16 v[38:41], v[208:211], v[152:155], v[38:41]
	v_mfma_f32_16x16x32_bf16 v[34:37], v[208:211], v[160:163], v[34:37]
	s_barrier
	s_add_u32 s66, s59, 0x80180
	s_addc_u32 s67, s63, 0
	s_mov_b32 m0, s18
	s_nop 0
	v_lshl_add_u64 v[148:149], s[66:67], 0, v[0:1]
	global_load_lds_dwordx4 v[148:149], off
	v_lshl_add_u64 v[148:149], s[66:67], 0, v[140:141]
	s_mov_b32 m0, s19
	s_nop 0
	global_load_lds_dwordx4 v[148:149], off
	s_waitcnt vmcnt(6)
	s_barrier
	v_mfma_f32_16x16x32_bf16 v[30:33], v[164:167], v[212:215], v[30:33]
	v_mfma_f32_16x16x32_bf16 v[26:29], v[164:167], v[220:223], v[26:29]
	v_mfma_f32_16x16x32_bf16 v[22:25], v[188:191], v[212:215], v[22:25]
	v_mfma_f32_16x16x32_bf16 v[18:21], v[188:191], v[220:223], v[18:21]
	v_mfma_f32_16x16x32_bf16 v[14:17], v[196:199], v[212:215], v[14:17]
	v_mfma_f32_16x16x32_bf16 v[10:13], v[196:199], v[220:223], v[10:13]
	v_mfma_f32_16x16x32_bf16 v[6:9], v[204:207], v[212:215], v[6:9]
	v_mfma_f32_16x16x32_bf16 v[2:5], v[204:207], v[220:223], v[2:5]
	v_mfma_f32_16x16x32_bf16 v[30:33], v[184:187], v[216:219], v[30:33]
	v_mfma_f32_16x16x32_bf16 v[26:29], v[184:187], v[224:227], v[26:29]
	v_mfma_f32_16x16x32_bf16 v[22:25], v[192:195], v[216:219], v[22:25]
	v_mfma_f32_16x16x32_bf16 v[18:21], v[192:195], v[224:227], v[18:21]
	v_mfma_f32_16x16x32_bf16 v[14:17], v[200:203], v[216:219], v[14:17]
	v_mfma_f32_16x16x32_bf16 v[10:13], v[200:203], v[224:227], v[10:13]
	v_mfma_f32_16x16x32_bf16 v[6:9], v[208:211], v[216:219], v[6:9]
	v_mfma_f32_16x16x32_bf16 v[2:5], v[208:211], v[224:227], v[2:5]
	s_add_u32 s11, s11, 0x100
	s_addc_u32 s44, s44, 0
	s_add_u32 s13, s13, 0x100
	s_addc_u32 s45, s45, 0
	s_add_u32 s50, s50, 0x100
	s_addc_u32 s51, s51, 0
	s_cmp_ge_u32 s55, s43
	s_barrier
	s_cbranch_scc0 .LBB0_202
	s_setprio 0
	s_add_i32 s11, s48, s20
	s_add_i32 s48, s11, -1
	s_lshl_b64 s[16:17], s[48:49], 7
	s_add_u32 s11, s74, s16
	s_addc_u32 s13, s75, s17
	s_add_u32 s4, s11, s4
	s_addc_u32 s5, s13, s5
	s_mov_b32 m0, s58
	ds_read_b128 v[148:151], v143
	ds_read_b128 v[152:155], v143 offset:1024
	ds_read_b128 v[156:159], v143 offset:2048
	ds_read_b128 v[160:163], v143 offset:3072
	ds_read_b128 v[164:167], v133
	ds_read_b128 v[184:187], v133 offset:1024
	ds_read_b128 v[188:191], v134
	ds_read_b128 v[192:195], v134 offset:1024
	ds_read_b128 v[196:199], v137
	ds_read_b128 v[200:203], v137 offset:1024
	ds_read_b128 v[204:207], v139
	ds_read_b128 v[208:211], v139 offset:1024
	s_nop 0
	v_lshl_add_u64 v[142:143], s[4:5], 0, v[0:1]
	global_load_lds_dwordx4 v[142:143], off
	v_lshl_add_u64 v[140:141], s[4:5], 0, v[140:141]
	s_mov_b32 m0, s57
	s_nop 0
	global_load_lds_dwordx4 v[140:141], off
	s_barrier
	s_waitcnt lgkmcnt(0)
	s_setprio 1
	s_waitcnt lgkmcnt(0)
	v_mfma_f32_16x16x32_bf16 v[126:129], v[164:167], v[148:151], v[126:129]
	v_mfma_f32_16x16x32_bf16 v[122:125], v[164:167], v[156:159], v[122:125]
	v_mfma_f32_16x16x32_bf16 v[118:121], v[188:191], v[148:151], v[118:121]
	v_mfma_f32_16x16x32_bf16 v[110:113], v[196:199], v[148:151], v[110:113]
	v_mfma_f32_16x16x32_bf16 v[106:109], v[196:199], v[156:159], v[106:109]
	v_mfma_f32_16x16x32_bf16 v[102:105], v[204:207], v[148:151], v[102:105]
	v_mfma_f32_16x16x32_bf16 v[98:101], v[204:207], v[156:159], v[98:101]
	v_mfma_f32_16x16x32_bf16 v[126:129], v[184:187], v[152:155], v[126:129]
	v_mfma_f32_16x16x32_bf16 v[122:125], v[184:187], v[160:163], v[122:125]
	v_mfma_f32_16x16x32_bf16 v[118:121], v[192:195], v[152:155], v[118:121]
	v_mfma_f32_16x16x32_bf16 v[114:117], v[188:191], v[156:159], v[114:117]
	v_mfma_f32_16x16x32_bf16 v[110:113], v[200:203], v[152:155], v[110:113]
	v_mfma_f32_16x16x32_bf16 v[106:109], v[200:203], v[160:163], v[106:109]
	v_mfma_f32_16x16x32_bf16 v[102:105], v[208:211], v[152:155], v[102:105]
	v_mfma_f32_16x16x32_bf16 v[98:101], v[208:211], v[160:163], v[98:101]
	v_mfma_f32_16x16x32_bf16 v[140:143], v[192:195], v[160:163], v[114:117]
	s_setprio 0
	s_barrier
	s_nop 0
	ds_read_b128 v[114:117], v144
	ds_read_b128 v[212:215], v144 offset:1024
	ds_read_b128 v[216:219], v144 offset:2048
	ds_read_b128 v[220:223], v144 offset:3072
	s_barrier
; #define LDA(dst, b, h) for (int m = 0; m < 4; ++m) for (int k = 0; k < 2; ++k) \
;     dst[m][k] = *reinterpret_cast<const bf16x8*>((char*)SA(b, h) + lds_byte(wr * 64 + m * 16 + fr, k * 32 + fq * 8))
; #define LDB(dst, b, h) for (int n = 0; n < 2; ++n) for (int k = 0; k < 2; ++k) \
;     dst[n][k] = *reinterpret_cast<const bf16x8*>((char*)SB(b, h) + lds_byte(wc * 32 + n * 16 + fr, k * 32 + fq * 8))
; #define MMA(ai, bj, At, Bt_) do { __builtin_amdgcn_s_setprio(1); \
;     for (int m = 0; m < 4; ++m) for (int n = 0; n < 2; ++n) for (int k = 0; k < 2; ++k) \
;       acc[ai][bj][m][n] = __builtin_amdgcn_mfma_f32_16x16x32_bf16(At[m][k], Bt_[n][k], acc[ai][bj][m][n], 0, 0, 0); \
;     __builtin_amdgcn_s_setprio(0); } while (0)
; #define WAIT_V(n) asm volatile("s_waitcnt vmcnt(" #n ")" ::: "memory")
; #define WAIT_L(n) asm volatile("s_waitcnt lgkmcnt(" #n ")" ::: "memory")
; #define BAR __builtin_amdgcn_s_barrier()
;     ...
;       LDB(B1, 0, 1); BAR; WAIT_L(0); MMA(0, 1, At, B1); BAR;
;       LDA(At, 0, 1); WAIT_V(4); BAR; WAIT_L(0); MMA(1, 0, At, B0); MMA(1, 1, At, B1); BAR; }
;     { LDB(B0, 1, 0); LDA(At, 1, 0); WAIT_V(2); BAR; WAIT_L(0); MMA(0, 0, At, B0); BAR;
	s_waitcnt lgkmcnt(0)
	s_setprio 1
	s_waitcnt lgkmcnt(0)
	v_mfma_f32_16x16x32_bf16 v[90:93], v[164:167], v[216:219], v[90:93]
	v_mfma_f32_16x16x32_bf16 v[86:89], v[188:191], v[114:117], v[86:89]
	v_mfma_f32_16x16x32_bf16 v[94:97], v[164:167], v[114:117], v[94:97]
	v_mfma_f32_16x16x32_bf16 v[90:93], v[184:187], v[220:223], v[90:93]
	v_mfma_f32_16x16x32_bf16 v[86:89], v[192:195], v[212:215], v[86:89]
	v_mfma_f32_16x16x32_bf16 v[82:85], v[188:191], v[216:219], v[82:85]
	v_mfma_f32_16x16x32_bf16 v[78:81], v[196:199], v[114:117], v[78:81]
	v_mfma_f32_16x16x32_bf16 v[74:77], v[196:199], v[216:219], v[74:77]
	v_mfma_f32_16x16x32_bf16 v[70:73], v[204:207], v[114:117], v[70:73]
	v_mfma_f32_16x16x32_bf16 v[66:69], v[204:207], v[216:219], v[66:69]
	v_mfma_f32_16x16x32_bf16 v[224:227], v[184:187], v[212:215], v[94:97]
	v_mfma_f32_16x16x32_bf16 v[164:167], v[192:195], v[220:223], v[82:85]
	v_mfma_f32_16x16x32_bf16 v[184:187], v[200:203], v[212:215], v[78:81]
	v_mfma_f32_16x16x32_bf16 v[188:191], v[200:203], v[220:223], v[74:77]
	v_mfma_f32_16x16x32_bf16 v[192:195], v[208:211], v[212:215], v[70:73]
	v_mfma_f32_16x16x32_bf16 v[196:199], v[208:211], v[220:223], v[66:69]
	s_setprio 0
	s_barrier
	s_nop 0
	ds_read_b128 v[66:69], v133 offset:16384
	ds_read_b128 v[70:73], v133 offset:17408
	ds_read_b128 v[74:77], v134 offset:16384
	ds_read_b128 v[78:81], v134 offset:17408
	ds_read_b128 v[82:85], v137 offset:16384
	ds_read_b128 v[94:97], v137 offset:17408
	ds_read_b128 v[200:203], v139 offset:16384
	ds_read_b128 v[204:207], v139 offset:17408
	s_waitcnt vmcnt(4)
	s_barrier
	s_waitcnt lgkmcnt(0)
	s_setprio 1
	s_waitcnt lgkmcnt(0)
	v_mfma_f32_16x16x32_bf16 v[62:65], v[66:69], v[148:151], v[62:65]
	v_mfma_f32_16x16x32_bf16 v[58:61], v[66:69], v[156:159], v[58:61]
	v_mfma_f32_16x16x32_bf16 v[54:57], v[74:77], v[148:151], v[54:57]
	v_mfma_f32_16x16x32_bf16 v[50:53], v[74:77], v[156:159], v[50:53]
	v_mfma_f32_16x16x32_bf16 v[46:49], v[82:85], v[148:151], v[46:49]
	v_mfma_f32_16x16x32_bf16 v[42:45], v[82:85], v[156:159], v[42:45]
	v_mfma_f32_16x16x32_bf16 v[38:41], v[200:203], v[148:151], v[38:41]
	v_mfma_f32_16x16x32_bf16 v[34:37], v[200:203], v[156:159], v[34:37]
	v_mfma_f32_16x16x32_bf16 v[62:65], v[70:73], v[152:155], v[62:65]
	v_mfma_f32_16x16x32_bf16 v[58:61], v[70:73], v[160:163], v[58:61]
	v_mfma_f32_16x16x32_bf16 v[54:57], v[78:81], v[152:155], v[54:57]
	v_mfma_f32_16x16x32_bf16 v[50:53], v[78:81], v[160:163], v[50:53]
	v_mfma_f32_16x16x32_bf16 v[46:49], v[94:97], v[152:155], v[46:49]
	v_mfma_f32_16x16x32_bf16 v[42:45], v[94:97], v[160:163], v[42:45]
	v_mfma_f32_16x16x32_bf16 v[38:41], v[204:207], v[152:155], v[38:41]
	v_mfma_f32_16x16x32_bf16 v[34:37], v[204:207], v[160:163], v[34:37]
	s_setprio 0
	s_setprio 1
	v_mfma_f32_16x16x32_bf16 v[30:33], v[66:69], v[114:117], v[30:33]
	v_mfma_f32_16x16x32_bf16 v[26:29], v[66:69], v[216:219], v[26:29]
	v_mfma_f32_16x16x32_bf16 v[22:25], v[74:77], v[114:117], v[22:25]
	v_mfma_f32_16x16x32_bf16 v[18:21], v[74:77], v[216:219], v[18:21]
	v_mfma_f32_16x16x32_bf16 v[14:17], v[82:85], v[114:117], v[14:17]
	v_mfma_f32_16x16x32_bf16 v[10:13], v[82:85], v[216:219], v[10:13]
	v_mfma_f32_16x16x32_bf16 v[6:9], v[200:203], v[114:117], v[6:9]
	v_mfma_f32_16x16x32_bf16 v[2:5], v[200:203], v[216:219], v[2:5]
	v_mfma_f32_16x16x32_bf16 v[148:151], v[70:73], v[212:215], v[30:33]
	v_mfma_f32_16x16x32_bf16 v[152:155], v[70:73], v[220:223], v[26:29]
	v_mfma_f32_16x16x32_bf16 v[156:159], v[78:81], v[212:215], v[22:25]
	v_mfma_f32_16x16x32_bf16 v[160:163], v[78:81], v[220:223], v[18:21]
	v_mfma_f32_16x16x32_bf16 v[208:211], v[94:97], v[212:215], v[14:17]
	v_mfma_f32_16x16x32_bf16 v[228:231], v[94:97], v[220:223], v[10:13]
	v_mfma_f32_16x16x32_bf16 v[212:215], v[204:207], v[212:215], v[6:9]
	v_mfma_f32_16x16x32_bf16 v[200:203], v[204:207], v[220:223], v[2:5]
	s_setprio 0
	s_barrier
	ds_read_b128 v[14:17], v145
	ds_read_b128 v[30:33], v145 offset:1024
	ds_read_b128 v[204:207], v145 offset:2048
	ds_read_b128 v[216:219], v145 offset:3072
	ds_read_b128 v[2:5], v133 offset:32768
	ds_read_b128 v[6:9], v133 offset:33792
	ds_read_b128 v[10:13], v134 offset:32768
	ds_read_b128 v[18:21], v134 offset:33792
	ds_read_b128 v[22:25], v137 offset:32768
	ds_read_b128 v[26:29], v137 offset:33792
	ds_read_b128 v[220:223], v139 offset:32768
	ds_read_b128 v[232:235], v139 offset:33792
	s_waitcnt vmcnt(2)
	s_barrier
; #define LDA(dst, b, h) for (int m = 0; m < 4; ++m) for (int k = 0; k < 2; ++k) \
;     dst[m][k] = *reinterpret_cast<const bf16x8*>((char*)SA(b, h) + lds_byte(wr * 64 + m * 16 + fr, k * 32 + fq * 8))
; #define LDB(dst, b, h) for (int n = 0; n < 2; ++n) for (int k = 0; k < 2; ++k) \
;     dst[n][k] = *reinterpret_cast<const bf16x8*>((char*)SB(b, h) + lds_byte(wc * 32 + n * 16 + fr, k * 32 + fq * 8))
; #define MMA(ai, bj, At, Bt_) do { __builtin_amdgcn_s_setprio(1); \
;     for (int m = 0; m < 4; ++m) for (int n = 0; n < 2; ++n) for (int k = 0; k < 2; ++k) \
;       acc[ai][bj][m][n] = __builtin_amdgcn_mfma_f32_16x16x32_bf16(At[m][k], Bt_[n][k], acc[ai][bj][m][n], 0, 0, 0); \
;     __builtin_amdgcn_s_setprio(0); } while (0)
; #define WAIT_V(n) asm volatile("s_waitcnt vmcnt(" #n ")" ::: "memory")
; #define WAIT_L(n) asm volatile("s_waitcnt lgkmcnt(" #n ")" ::: "memory")
; #define BAR __builtin_amdgcn_s_barrier()
;     ...
;     { LDB(B0, 1, 0); LDA(At, 1, 0); WAIT_V(2); BAR; WAIT_L(0); MMA(0, 0, At, B0); BAR;
;       LDB(B1, 1, 1); WAIT_V(0); BAR; WAIT_L(0); MMA(0, 1, At, B1); BAR;
;       LDA(At, 1, 1); BAR; WAIT_L(0); MMA(1, 0, At, B0); MMA(1, 1, At, B1); BAR; }
;     if (wr == 0) BAR;
	s_waitcnt lgkmcnt(0)
	s_setprio 1
	s_waitcnt lgkmcnt(0)
	v_mfma_f32_16x16x32_bf16 v[66:69], v[2:5], v[14:17], v[126:129]
	v_mfma_f32_16x16x32_bf16 v[114:117], v[6:9], v[30:33], v[66:69]
	v_mfma_f32_16x16x32_bf16 v[66:69], v[2:5], v[204:207], v[122:125]
	v_mfma_f32_16x16x32_bf16 v[126:129], v[6:9], v[216:219], v[66:69]
	v_mfma_f32_16x16x32_bf16 v[66:69], v[10:13], v[14:17], v[118:121]
	v_mfma_f32_16x16x32_bf16 v[82:85], v[18:21], v[30:33], v[66:69]
	v_mfma_f32_16x16x32_bf16 v[66:69], v[10:13], v[204:207], v[140:143]
	v_mfma_f32_16x16x32_bf16 v[94:97], v[18:21], v[216:219], v[66:69]
	v_mfma_f32_16x16x32_bf16 v[66:69], v[22:25], v[14:17], v[110:113]
	v_mfma_f32_16x16x32_bf16 v[74:77], v[26:29], v[30:33], v[66:69]
	v_mfma_f32_16x16x32_bf16 v[66:69], v[22:25], v[204:207], v[106:109]
	v_mfma_f32_16x16x32_bf16 v[78:81], v[26:29], v[216:219], v[66:69]
	v_mfma_f32_16x16x32_bf16 v[66:69], v[220:223], v[14:17], v[102:105]
	v_mfma_f32_16x16x32_bf16 v[70:73], v[220:223], v[204:207], v[98:101]
	v_mfma_f32_16x16x32_bf16 v[66:69], v[232:235], v[30:33], v[66:69]
	v_mfma_f32_16x16x32_bf16 v[70:73], v[232:235], v[216:219], v[70:73]
	s_setprio 0
	s_barrier
	ds_read_b128 v[140:143], v146
	ds_read_b128 v[236:239], v146 offset:1024
	ds_read_b128 v[240:243], v146 offset:2048
	ds_read_b128 v[144:147], v146 offset:3072
	s_waitcnt vmcnt(0)
	s_barrier
	s_waitcnt lgkmcnt(0)
	s_setprio 1
	s_waitcnt lgkmcnt(0)
	v_mfma_f32_16x16x32_bf16 v[98:101], v[2:5], v[140:143], v[224:227]
	v_mfma_f32_16x16x32_bf16 v[2:5], v[2:5], v[240:243], v[90:93]
	v_mfma_f32_16x16x32_bf16 v[118:121], v[6:9], v[144:147], v[2:5]
	v_mfma_f32_16x16x32_bf16 v[2:5], v[10:13], v[140:143], v[86:89]
	v_mfma_f32_16x16x32_bf16 v[102:105], v[18:21], v[236:239], v[2:5]
	v_mfma_f32_16x16x32_bf16 v[2:5], v[10:13], v[240:243], v[164:167]
	v_mfma_f32_16x16x32_bf16 v[122:125], v[18:21], v[144:147], v[2:5]
	v_mfma_f32_16x16x32_bf16 v[2:5], v[22:25], v[140:143], v[184:187]
	v_mfma_f32_16x16x32_bf16 v[90:93], v[26:29], v[236:239], v[2:5]
	v_mfma_f32_16x16x32_bf16 v[2:5], v[22:25], v[240:243], v[188:191]
	v_mfma_f32_16x16x32_bf16 v[110:113], v[26:29], v[144:147], v[2:5]
	v_mfma_f32_16x16x32_bf16 v[2:5], v[220:223], v[140:143], v[192:195]
	v_mfma_f32_16x16x32_bf16 v[86:89], v[232:235], v[236:239], v[2:5]
	v_mfma_f32_16x16x32_bf16 v[2:5], v[220:223], v[240:243], v[196:199]
	v_mfma_f32_16x16x32_bf16 v[98:101], v[6:9], v[236:239], v[98:101]
	v_mfma_f32_16x16x32_bf16 v[106:109], v[232:235], v[144:147], v[2:5]
	s_setprio 0
	s_barrier
	ds_read_b128 v[164:167], v133 offset:49152
	ds_read_b128 v[184:187], v133 offset:50176
	ds_read_b128 v[188:191], v134 offset:49152
	ds_read_b128 v[192:195], v134 offset:50176
	ds_read_b128 v[196:199], v137 offset:49152
	ds_read_b128 v[220:223], v137 offset:50176
	ds_read_b128 v[224:227], v139 offset:49152
	ds_read_b128 v[232:235], v139 offset:50176
	s_barrier
	s_waitcnt lgkmcnt(0)
	s_setprio 1
	s_waitcnt lgkmcnt(0)
	v_mfma_f32_16x16x32_bf16 v[6:9], v[164:167], v[204:207], v[58:61]
	v_mfma_f32_16x16x32_bf16 v[10:13], v[188:191], v[204:207], v[50:53]
	v_mfma_f32_16x16x32_bf16 v[2:5], v[164:167], v[14:17], v[62:65]
	v_mfma_f32_16x16x32_bf16 v[18:21], v[184:187], v[216:219], v[6:9]
	v_mfma_f32_16x16x32_bf16 v[6:9], v[188:191], v[14:17], v[54:57]
	v_mfma_f32_16x16x32_bf16 v[22:25], v[192:195], v[216:219], v[10:13]
	v_mfma_f32_16x16x32_bf16 v[10:13], v[196:199], v[14:17], v[46:49]
	v_mfma_f32_16x16x32_bf16 v[14:17], v[224:227], v[14:17], v[38:41]
	v_mfma_f32_16x16x32_bf16 v[2:5], v[184:187], v[30:33], v[2:5]
	v_mfma_f32_16x16x32_bf16 v[6:9], v[192:195], v[30:33], v[6:9]
	v_mfma_f32_16x16x32_bf16 v[10:13], v[220:223], v[30:33], v[10:13]
	v_mfma_f32_16x16x32_bf16 v[26:29], v[196:199], v[204:207], v[42:45]
	v_mfma_f32_16x16x32_bf16 v[14:17], v[232:235], v[30:33], v[14:17]
	v_mfma_f32_16x16x32_bf16 v[30:33], v[224:227], v[204:207], v[34:37]
	v_mfma_f32_16x16x32_bf16 v[26:29], v[220:223], v[216:219], v[26:29]
	v_mfma_f32_16x16x32_bf16 v[30:33], v[232:235], v[216:219], v[30:33]
	s_setprio 0
	s_setprio 1
	v_mfma_f32_16x16x32_bf16 v[38:41], v[164:167], v[240:243], v[152:155]
	v_mfma_f32_16x16x32_bf16 v[42:45], v[188:191], v[240:243], v[160:163]
	v_mfma_f32_16x16x32_bf16 v[46:49], v[196:199], v[240:243], v[228:231]
	v_mfma_f32_16x16x32_bf16 v[34:37], v[164:167], v[140:143], v[148:151]
	v_mfma_f32_16x16x32_bf16 v[50:53], v[184:187], v[144:147], v[38:41]
	v_mfma_f32_16x16x32_bf16 v[38:41], v[188:191], v[140:143], v[156:159]
	v_mfma_f32_16x16x32_bf16 v[54:57], v[192:195], v[144:147], v[42:45]
	v_mfma_f32_16x16x32_bf16 v[42:45], v[196:199], v[140:143], v[208:211]
	v_mfma_f32_16x16x32_bf16 v[58:61], v[220:223], v[144:147], v[46:49]
	v_mfma_f32_16x16x32_bf16 v[46:49], v[224:227], v[140:143], v[212:215]
	v_mfma_f32_16x16x32_bf16 v[62:65], v[224:227], v[240:243], v[200:203]
	v_mfma_f32_16x16x32_bf16 v[34:37], v[184:187], v[236:239], v[34:37]
	v_mfma_f32_16x16x32_bf16 v[38:41], v[192:195], v[236:239], v[38:41]
	v_mfma_f32_16x16x32_bf16 v[42:45], v[220:223], v[236:239], v[42:45]
	v_mfma_f32_16x16x32_bf16 v[46:49], v[232:235], v[236:239], v[46:49]
	v_mfma_f32_16x16x32_bf16 v[62:65], v[232:235], v[144:147], v[62:65]
	s_setprio 0
	v_readlane_b32 s4, v245, 33
	v_readlane_b32 s5, v245, 34
	s_and_b64 vcc, exec, s[4:5]
	s_barrier
	s_cbranch_vccz .LBB0_205
	s_barrier

; #define WAIT_V(n) asm volatile("s_waitcnt vmcnt(" #n ")" ::: "memory")
; #define BAR __builtin_amdgcn_s_barrier()
;     ...
;     if (wr == 1) BAR;
;     WAIT_V(4); BAR;
;     STAGE(SB(1, 0), Bt, bcol, 1); STAGE(SA(1, 0), A, brow, 1); STAGE(SB(1, 1), Bt, bcol + HALF, 1);
;     WAIT_V(6); BAR;
;     for (int t = 0; t < nt - 2; t += 2) {
.LBB0_417:
	s_add_u32 s34, s8, 0x80
	s_addc_u32 s35, s9, 0
	s_add_i32 s8, s15, 0x18000
	v_mov_b32_e32 v141, v1
	s_waitcnt vmcnt(4)
	s_barrier
	s_mov_b32 m0, s8
	v_lshl_add_u64 v[4:5], s[34:35], 0, v[0:1]
	s_add_i32 s9, s15, 0x1a000
	global_load_lds_dwordx4 v[4:5], off
	v_lshl_add_u64 v[4:5], s[34:35], 0, v[140:141]
	s_add_u32 s34, s18, 0x80
	s_mov_b32 m0, s9
	s_addc_u32 s35, s19, 0
	s_add_i32 s18, s15, 0x8000
	global_load_lds_dwordx4 v[4:5], off
	s_mov_b32 m0, s18
	v_lshl_add_u64 v[4:5], s[34:35], 0, v[0:1]
	s_add_i32 s19, s15, 0xa000
	global_load_lds_dwordx4 v[4:5], off
	v_lshl_add_u64 v[4:5], s[34:35], 0, v[140:141]
	s_add_u32 s34, s20, 0x80
	s_mov_b32 m0, s19
	s_addc_u32 s35, s21, 0
	s_add_i32 s20, s15, 0x1c000
	global_load_lds_dwordx4 v[4:5], off
	s_mov_b32 m0, s20
	v_lshl_add_u64 v[4:5], s[34:35], 0, v[0:1]
	s_add_i32 s21, s15, 0x1e000
	global_load_lds_dwordx4 v[4:5], off
	v_lshl_add_u64 v[4:5], s[34:35], 0, v[140:141]
	s_mov_b32 m0, s21
	v_and_b32_e32 v3, 15, v2
	global_load_lds_dwordx4 v[4:5], off
	v_and_b32_e32 v6, 48, v2
	v_lshlrev_b32_e32 v2, 2, v2
	v_lshlrev_b32_e32 v4, 6, v3
	v_and_b32_e32 v2, 32, v2
	v_bitop3_b32 v142, v4, v2, v6 bitop3:0x36
	v_or_b32_e32 v2, s33, v3
	v_lshlrev_b32_e32 v4, 6, v2
	v_lshlrev_b32_e32 v2, 2, v2
	v_and_b32_e32 v4, 0x3c0, v4
	v_and_b32_e32 v2, 32, v2
	v_readlane_b32 s34, v245, 36
	v_bitop3_b32 v4, v4, v2, v6 bitop3:0x36
	s_lshl_b32 s30, s30, 11
	v_or_b32_e32 v2, s34, v3
	v_lshlrev_b32_e32 v5, 6, v2
	v_lshlrev_b32_e32 v2, 2, v2
	v_and_b32_e32 v5, 0x3c0, v5
	v_and_b32_e32 v2, 32, v2
	v_readlane_b32 s34, v245, 37
	v_bitop3_b32 v5, v5, v2, v6 bitop3:0x36
	s_lshl_b32 s31, s31, 8
	v_or_b32_e32 v2, s34, v3
	v_lshlrev_b32_e32 v7, 6, v2
	v_lshlrev_b32_e32 v2, 2, v2
	s_add_i32 s30, s30, s31
	v_and_b32_e32 v7, 0x3c0, v7
	v_and_b32_e32 v2, 32, v2
	s_ashr_i32 s31, s30, 31
	v_bitop3_b32 v7, v7, v2, v6 bitop3:0x36
	v_or_b32_e32 v2, s85, v3
	s_lshl_b64 s[30:31], s[30:31], 12
	v_readlane_b32 s37, v244, 19
	v_lshlrev_b32_e32 v3, 6, v2
	v_lshlrev_b32_e32 v2, 2, v2
	s_add_u32 s30, s74, s30
	v_add_u32_e32 v133, s37, v4
	v_readlane_b32 s37, v244, 20
	s_waitcnt vmcnt(6)
	v_and_b32_e32 v3, 0x3c0, v3
	v_and_b32_e32 v2, 32, v2
	s_addc_u32 s31, s75, s31
	v_add_u32_e32 v134, s37, v5
	v_readlane_b32 s37, v244, 21
	v_bitop3_b32 v3, v3, v2, v6 bitop3:0x36
	s_add_u32 s34, s38, s6
	v_mov_b32_e32 v2, 0
	v_add_u32_e32 v137, s37, v7
	v_readlane_b32 s37, v244, 22
	s_addc_u32 s35, s39, s7
	s_mov_b32 s36, -2
	s_mov_b64 s[6:7], 0
	v_add_u32_e32 v139, s37, v3
	v_mov_b32_e32 v3, v2
	v_mov_b32_e32 v4, v2
	v_mov_b32_e32 v5, v2
	v_mov_b32_e32 v6, v2
	v_mov_b32_e32 v7, v2
	v_mov_b32_e32 v8, v2
	v_mov_b32_e32 v9, v2
	v_mov_b32_e32 v10, v2
	v_mov_b32_e32 v11, v2
	v_mov_b32_e32 v12, v2
	v_mov_b32_e32 v13, v2
	v_mov_b32_e32 v14, v2
	v_mov_b32_e32 v15, v2
	v_mov_b32_e32 v16, v2
	v_mov_b32_e32 v17, v2
	v_mov_b32_e32 v18, v2
	v_mov_b32_e32 v19, v2
	v_mov_b32_e32 v20, v2
	v_mov_b32_e32 v21, v2
	v_mov_b32_e32 v22, v2
	v_mov_b32_e32 v23, v2
	v_mov_b32_e32 v24, v2
	v_mov_b32_e32 v25, v2
	v_mov_b32_e32 v26, v2
	v_mov_b32_e32 v27, v2
	v_mov_b32_e32 v28, v2
	v_mov_b32_e32 v29, v2
	v_mov_b32_e32 v30, v2
	v_mov_b32_e32 v31, v2
	v_mov_b32_e32 v32, v2
	v_mov_b32_e32 v33, v2
	v_mov_b32_e32 v34, v2
	v_mov_b32_e32 v35, v2
	v_mov_b32_e32 v36, v2
	v_mov_b32_e32 v37, v2
	v_mov_b32_e32 v38, v2
	v_mov_b32_e32 v39, v2
	v_mov_b32_e32 v40, v2
	v_mov_b32_e32 v41, v2
	v_mov_b32_e32 v42, v2
	v_mov_b32_e32 v43, v2
	v_mov_b32_e32 v44, v2
	v_mov_b32_e32 v45, v2
	v_mov_b32_e32 v46, v2
	v_mov_b32_e32 v47, v2
	v_mov_b32_e32 v48, v2
	v_mov_b32_e32 v49, v2
	v_mov_b32_e32 v50, v2
	v_mov_b32_e32 v51, v2
	v_mov_b32_e32 v52, v2
	v_mov_b32_e32 v53, v2
	v_mov_b32_e32 v54, v2
	v_mov_b32_e32 v55, v2
	v_mov_b32_e32 v56, v2
	v_mov_b32_e32 v57, v2
	v_mov_b32_e32 v58, v2
	v_mov_b32_e32 v59, v2
	v_mov_b32_e32 v60, v2
	v_mov_b32_e32 v61, v2
	v_mov_b32_e32 v62, v2
	v_mov_b32_e32 v63, v2
	v_mov_b32_e32 v64, v2
	v_mov_b32_e32 v65, v2
	v_mov_b32_e32 v66, v2
	v_mov_b32_e32 v67, v2
	v_mov_b32_e32 v68, v2
	v_mov_b32_e32 v69, v2
	v_mov_b32_e32 v70, v2
	v_mov_b32_e32 v71, v2
	v_mov_b32_e32 v72, v2
	v_mov_b32_e32 v73, v2
	v_mov_b32_e32 v74, v2
	v_mov_b32_e32 v75, v2
	v_mov_b32_e32 v76, v2
	v_mov_b32_e32 v77, v2
	v_mov_b32_e32 v78, v2
	v_mov_b32_e32 v79, v2
	v_mov_b32_e32 v80, v2
	v_mov_b32_e32 v81, v2
	v_mov_b32_e32 v82, v2
	v_mov_b32_e32 v83, v2
	v_mov_b32_e32 v84, v2
	v_mov_b32_e32 v85, v2
	v_mov_b32_e32 v86, v2
	v_mov_b32_e32 v87, v2
	v_mov_b32_e32 v88, v2
	v_mov_b32_e32 v89, v2
	v_mov_b32_e32 v90, v2
	v_mov_b32_e32 v91, v2
	v_mov_b32_e32 v92, v2
	v_mov_b32_e32 v93, v2
	v_mov_b32_e32 v94, v2
	v_mov_b32_e32 v95, v2
	v_mov_b32_e32 v96, v2
	v_mov_b32_e32 v97, v2
	v_mov_b32_e32 v98, v2
	v_mov_b32_e32 v99, v2
	v_mov_b32_e32 v100, v2
	v_mov_b32_e32 v101, v2
	v_mov_b32_e32 v102, v2
	v_mov_b32_e32 v103, v2
	v_mov_b32_e32 v104, v2
	v_mov_b32_e32 v105, v2
	v_mov_b32_e32 v106, v2
	v_mov_b32_e32 v107, v2
	v_mov_b32_e32 v108, v2
	v_mov_b32_e32 v109, v2
	v_mov_b32_e32 v110, v2
	v_mov_b32_e32 v111, v2
	v_mov_b32_e32 v112, v2
	v_mov_b32_e32 v113, v2
	v_mov_b32_e32 v114, v2
	v_mov_b32_e32 v115, v2
	v_mov_b32_e32 v116, v2
	v_mov_b32_e32 v117, v2
	v_mov_b32_e32 v118, v2
	v_mov_b32_e32 v119, v2
	v_mov_b32_e32 v120, v2
	v_mov_b32_e32 v121, v2
	v_mov_b32_e32 v122, v2
	v_mov_b32_e32 v123, v2
	v_mov_b32_e32 v124, v2
	v_mov_b32_e32 v125, v2
	v_mov_b32_e32 v126, v2
	v_mov_b32_e32 v127, v2
	v_mov_b32_e32 v128, v2
	v_mov_b32_e32 v129, v2
	v_readlane_b32 vcc_lo, v245, 30
	s_nop 0
	s_cmpk_lt_u32 vcc_lo, 0x1000
	s_cbranch_scc1 .Lgp_418
	s_setprio 1

; #define LDA(dst, b, h) for (int m = 0; m < 4; ++m) for (int k = 0; k < 2; ++k) \
;     dst[m][k] = *reinterpret_cast<const bf16x8*>((char*)SA(b, h) + lds_byte(wr * 64 + m * 16 + fr, k * 32 + fq * 8))
; #define LDB(dst, b, h) for (int n = 0; n < 2; ++n) for (int k = 0; k < 2; ++k) \
;     dst[n][k] = *reinterpret_cast<const bf16x8*>((char*)SB(b, h) + lds_byte(wc * 32 + n * 16 + fr, k * 32 + fq * 8))
; #define MMA(ai, bj, At, Bt_) do { __builtin_amdgcn_s_setprio(1); \
;     for (int m = 0; m < 4; ++m) for (int n = 0; n < 2; ++n) for (int k = 0; k < 2; ++k) \
;       acc[ai][bj][m][n] = __builtin_amdgcn_mfma_f32_16x16x32_bf16(At[m][k], Bt_[n][k], acc[ai][bj][m][n], 0, 0, 0); \
;     __builtin_amdgcn_s_setprio(0); } while (0)
; #define WAIT_L(n) asm volatile("s_waitcnt lgkmcnt(" #n ")" ::: "memory")
; #define BAR __builtin_amdgcn_s_barrier()
; #define SCHED __builtin_amdgcn_sched_barrier(0)
;     ...
;       LDB(B0, 0, 0); SCHED; LDA(At, 0, 0); STAGE(SA(1, 1), A, brow + HALF, t + 1);
;       WAIT_L(8); BAR; WAIT_L(0); MMA(0, 0, At, B0); BAR; SCHED;
;       LDB(B1, 0, 1); STAGE(SB(0, 0), Bt, bcol, t + 2);
;       BAR; WAIT_L(0); MMA(0, 1, At, B1); BAR;
;       LDA(At, 0, 1); STAGE(SA(0, 0), A, brow, t + 2);
;       BAR; WAIT_L(0); MMA(1, 0, At, B0); BAR; SCHED;
.LBB0_418:
	v_add_u32_e32 v143, s2, v142
	ds_read_b128 v[146:149], v143
	ds_read_b128 v[150:153], v143 offset:1024
	ds_read_b128 v[154:157], v143 offset:2048
	ds_read_b128 v[158:161], v143 offset:3072
	s_add_u32 s42, s30, s6
	s_addc_u32 s43, s31, s7
	s_add_u32 s44, s42, 0x80080
	s_addc_u32 s45, s43, 0
	s_add_i32 s41, s15, 0xc000
	ds_read_b128 v[162:165], v133
	ds_read_b128 v[184:187], v133 offset:1024
	ds_read_b128 v[188:191], v134
	ds_read_b128 v[192:195], v134 offset:1024
	ds_read_b128 v[196:199], v137
	ds_read_b128 v[200:203], v137 offset:1024
	ds_read_b128 v[204:207], v139
	ds_read_b128 v[208:211], v139 offset:1024
	s_mov_b32 m0, s41
	v_lshl_add_u64 v[144:145], s[44:45], 0, v[0:1]
	s_add_i32 s37, s15, 0xe000
	global_load_lds_dwordx4 v[144:145], off
	v_lshl_add_u64 v[144:145], s[44:45], 0, v[140:141]
	s_mov_b32 m0, s37
	s_nop 0
	global_load_lds_dwordx4 v[144:145], off
	s_waitcnt lgkmcnt(8)
	s_barrier
	s_waitcnt lgkmcnt(0)
	s_waitcnt lgkmcnt(0)
	v_mfma_f32_16x16x32_bf16 v[126:129], v[162:165], v[146:149], v[126:129]
	v_mfma_f32_16x16x32_bf16 v[122:125], v[162:165], v[154:157], v[122:125]
	v_mfma_f32_16x16x32_bf16 v[118:121], v[188:191], v[146:149], v[118:121]
	v_mfma_f32_16x16x32_bf16 v[114:117], v[188:191], v[154:157], v[114:117]
	v_mfma_f32_16x16x32_bf16 v[110:113], v[196:199], v[146:149], v[110:113]
	v_mfma_f32_16x16x32_bf16 v[106:109], v[196:199], v[154:157], v[106:109]
	v_mfma_f32_16x16x32_bf16 v[102:105], v[204:207], v[146:149], v[102:105]
	v_mfma_f32_16x16x32_bf16 v[98:101], v[204:207], v[154:157], v[98:101]
	v_mfma_f32_16x16x32_bf16 v[126:129], v[184:187], v[150:153], v[126:129]
	v_mfma_f32_16x16x32_bf16 v[122:125], v[184:187], v[158:161], v[122:125]
	v_mfma_f32_16x16x32_bf16 v[118:121], v[192:195], v[150:153], v[118:121]
	v_mfma_f32_16x16x32_bf16 v[114:117], v[192:195], v[158:161], v[114:117]
	v_mfma_f32_16x16x32_bf16 v[110:113], v[200:203], v[150:153], v[110:113]
	v_mfma_f32_16x16x32_bf16 v[106:109], v[200:203], v[158:161], v[106:109]
	v_mfma_f32_16x16x32_bf16 v[102:105], v[208:211], v[150:153], v[102:105]
	v_mfma_f32_16x16x32_bf16 v[98:101], v[208:211], v[158:161], v[98:101]
	s_barrier
	s_add_u32 s44, s34, s6
	s_addc_u32 s45, s35, s7
	s_add_u32 s50, s44, 0x100
	v_add_u32_e32 v144, s76, v142
	s_addc_u32 s51, s45, 0
	s_mov_b32 m0, s23
	ds_read_b128 v[212:215], v144
	ds_read_b128 v[216:219], v144 offset:1024
	ds_read_b128 v[220:223], v144 offset:2048
	ds_read_b128 v[224:227], v144 offset:3072
	s_nop 0
	v_lshl_add_u64 v[166:167], s[50:51], 0, v[0:1]
	global_load_lds_dwordx4 v[166:167], off
	v_lshl_add_u64 v[166:167], s[50:51], 0, v[140:141]
	s_mov_b32 m0, s26
	s_nop 0
	global_load_lds_dwordx4 v[166:167], off
	s_barrier
	s_waitcnt lgkmcnt(0)
	s_waitcnt lgkmcnt(0)
	v_mfma_f32_16x16x32_bf16 v[94:97], v[162:165], v[212:215], v[94:97]
	v_mfma_f32_16x16x32_bf16 v[90:93], v[162:165], v[220:223], v[90:93]
	v_mfma_f32_16x16x32_bf16 v[86:89], v[188:191], v[212:215], v[86:89]
	v_mfma_f32_16x16x32_bf16 v[82:85], v[188:191], v[220:223], v[82:85]
	v_mfma_f32_16x16x32_bf16 v[78:81], v[196:199], v[212:215], v[78:81]
	v_mfma_f32_16x16x32_bf16 v[74:77], v[196:199], v[220:223], v[74:77]
	v_mfma_f32_16x16x32_bf16 v[70:73], v[204:207], v[212:215], v[70:73]
	v_mfma_f32_16x16x32_bf16 v[66:69], v[204:207], v[220:223], v[66:69]
	v_mfma_f32_16x16x32_bf16 v[94:97], v[184:187], v[216:219], v[94:97]
	v_mfma_f32_16x16x32_bf16 v[90:93], v[184:187], v[224:227], v[90:93]
	v_mfma_f32_16x16x32_bf16 v[86:89], v[192:195], v[216:219], v[86:89]
	v_mfma_f32_16x16x32_bf16 v[82:85], v[192:195], v[224:227], v[82:85]
	v_mfma_f32_16x16x32_bf16 v[78:81], v[200:203], v[216:219], v[78:81]
	v_mfma_f32_16x16x32_bf16 v[74:77], v[200:203], v[224:227], v[74:77]
	v_mfma_f32_16x16x32_bf16 v[70:73], v[208:211], v[216:219], v[70:73]
	v_mfma_f32_16x16x32_bf16 v[66:69], v[208:211], v[224:227], v[66:69]
	s_add_u32 s50, s42, 0x100
	s_addc_u32 s51, s43, 0
	s_mov_b32 m0, s15
	s_barrier
	ds_read_b128 v[162:165], v133 offset:16384
	ds_read_b128 v[184:187], v133 offset:17408
	ds_read_b128 v[188:191], v134 offset:16384
	ds_read_b128 v[192:195], v134 offset:17408
	ds_read_b128 v[196:199], v137 offset:16384
	ds_read_b128 v[200:203], v137 offset:17408
	ds_read_b128 v[204:207], v139 offset:16384
	ds_read_b128 v[208:211], v139 offset:17408
	s_nop 0
	v_lshl_add_u64 v[166:167], s[50:51], 0, v[0:1]
	global_load_lds_dwordx4 v[166:167], off
	v_lshl_add_u64 v[166:167], s[50:51], 0, v[140:141]
	s_mov_b32 m0, s25
	s_nop 0
	global_load_lds_dwordx4 v[166:167], off
	s_barrier
	s_waitcnt lgkmcnt(0)
	s_waitcnt lgkmcnt(0)
	v_mfma_f32_16x16x32_bf16 v[62:65], v[162:165], v[146:149], v[62:65]
	v_mfma_f32_16x16x32_bf16 v[58:61], v[162:165], v[154:157], v[58:61]
	v_mfma_f32_16x16x32_bf16 v[54:57], v[188:191], v[146:149], v[54:57]
	v_mfma_f32_16x16x32_bf16 v[50:53], v[188:191], v[154:157], v[50:53]
	v_mfma_f32_16x16x32_bf16 v[46:49], v[196:199], v[146:149], v[46:49]
	v_mfma_f32_16x16x32_bf16 v[42:45], v[196:199], v[154:157], v[42:45]
	v_mfma_f32_16x16x32_bf16 v[38:41], v[204:207], v[146:149], v[38:41]
	v_mfma_f32_16x16x32_bf16 v[34:37], v[204:207], v[154:157], v[34:37]
	v_mfma_f32_16x16x32_bf16 v[62:65], v[184:187], v[150:153], v[62:65]
	v_mfma_f32_16x16x32_bf16 v[58:61], v[184:187], v[158:161], v[58:61]
	v_mfma_f32_16x16x32_bf16 v[54:57], v[192:195], v[150:153], v[54:57]
	v_mfma_f32_16x16x32_bf16 v[50:53], v[192:195], v[158:161], v[50:53]
	v_mfma_f32_16x16x32_bf16 v[46:49], v[200:203], v[150:153], v[46:49]
	v_mfma_f32_16x16x32_bf16 v[42:45], v[200:203], v[158:161], v[42:45]
	v_mfma_f32_16x16x32_bf16 v[38:41], v[208:211], v[150:153], v[38:41]
	v_mfma_f32_16x16x32_bf16 v[34:37], v[208:211], v[158:161], v[34:37]
	s_barrier
; #define LDA(dst, b, h) for (int m = 0; m < 4; ++m) for (int k = 0; k < 2; ++k) \
;     dst[m][k] = *reinterpret_cast<const bf16x8*>((char*)SA(b, h) + lds_byte(wr * 64 + m * 16 + fr, k * 32 + fq * 8))
; #define LDB(dst, b, h) for (int n = 0; n < 2; ++n) for (int k = 0; k < 2; ++k) \
;     dst[n][k] = *reinterpret_cast<const bf16x8*>((char*)SB(b, h) + lds_byte(wc * 32 + n * 16 + fr, k * 32 + fq * 8))
; #define MMA(ai, bj, At, Bt_) do { __builtin_amdgcn_s_setprio(1); \
;     for (int m = 0; m < 4; ++m) for (int n = 0; n < 2; ++n) for (int k = 0; k < 2; ++k) \
;       acc[ai][bj][m][n] = __builtin_amdgcn_mfma_f32_16x16x32_bf16(At[m][k], Bt_[n][k], acc[ai][bj][m][n], 0, 0, 0); \
;     __builtin_amdgcn_s_setprio(0); } while (0)
; #define WAIT_V(n) asm volatile("s_waitcnt vmcnt(" #n ")" ::: "memory")
; #define WAIT_L(n) asm volatile("s_waitcnt lgkmcnt(" #n ")" ::: "memory")
; #define BAR __builtin_amdgcn_s_barrier()
; #define SCHED __builtin_amdgcn_sched_barrier(0)
;     ...
;       STAGE(SB(0, 1), Bt, bcol + HALF, t + 2);
;       WAIT_V(6); BAR; MMA(1, 1, At, B1); BAR;
;       LDB(B0, 1, 0); SCHED; LDA(At, 1, 0); STAGE(SA(0, 1), A, brow + HALF, t + 2);
;       WAIT_L(8); BAR; WAIT_L(0); MMA(0, 0, At, B0); BAR; SCHED;
;       LDB(B1, 1, 1); STAGE(SB(1, 0), Bt, bcol, t + 3);
;       BAR; WAIT_L(0); MMA(0, 1, At, B1); BAR;
;       LDA(At, 1, 1); STAGE(SA(1, 0), A, brow, t + 3);
	s_add_u32 s50, s44, 0x80100
	s_addc_u32 s51, s45, 0
	s_mov_b32 m0, s27
	s_nop 0
	v_lshl_add_u64 v[146:147], s[50:51], 0, v[0:1]
	global_load_lds_dwordx4 v[146:147], off
	v_lshl_add_u64 v[146:147], s[50:51], 0, v[140:141]
	s_mov_b32 m0, s28
	s_nop 0
	global_load_lds_dwordx4 v[146:147], off
	s_waitcnt vmcnt(6)
	s_barrier
	v_mfma_f32_16x16x32_bf16 v[30:33], v[162:165], v[212:215], v[30:33]
	v_mfma_f32_16x16x32_bf16 v[26:29], v[162:165], v[220:223], v[26:29]
	v_mfma_f32_16x16x32_bf16 v[22:25], v[188:191], v[212:215], v[22:25]
	v_mfma_f32_16x16x32_bf16 v[18:21], v[188:191], v[220:223], v[18:21]
	v_mfma_f32_16x16x32_bf16 v[14:17], v[196:199], v[212:215], v[14:17]
	v_mfma_f32_16x16x32_bf16 v[10:13], v[196:199], v[220:223], v[10:13]
	v_mfma_f32_16x16x32_bf16 v[6:9], v[204:207], v[212:215], v[6:9]
	v_mfma_f32_16x16x32_bf16 v[2:5], v[204:207], v[220:223], v[2:5]
	v_mfma_f32_16x16x32_bf16 v[30:33], v[184:187], v[216:219], v[30:33]
	v_mfma_f32_16x16x32_bf16 v[26:29], v[184:187], v[224:227], v[26:29]
	v_mfma_f32_16x16x32_bf16 v[22:25], v[192:195], v[216:219], v[22:25]
	v_mfma_f32_16x16x32_bf16 v[18:21], v[192:195], v[224:227], v[18:21]
	v_mfma_f32_16x16x32_bf16 v[14:17], v[200:203], v[216:219], v[14:17]
	v_mfma_f32_16x16x32_bf16 v[10:13], v[200:203], v[224:227], v[10:13]
	v_mfma_f32_16x16x32_bf16 v[6:9], v[208:211], v[216:219], v[6:9]
	v_mfma_f32_16x16x32_bf16 v[2:5], v[208:211], v[224:227], v[2:5]
	v_add_u32_e32 v145, s77, v142
	s_barrier
	ds_read_b128 v[148:151], v145
	ds_read_b128 v[152:155], v145 offset:1024
	ds_read_b128 v[156:159], v145 offset:2048
	ds_read_b128 v[160:163], v145 offset:3072
	s_add_u32 s50, s42, 0x80100
	s_addc_u32 s51, s43, 0
	s_mov_b32 m0, s17
	ds_read_b128 v[164:167], v133 offset:32768
	ds_read_b128 v[184:187], v133 offset:33792
	ds_read_b128 v[188:191], v134 offset:32768
	ds_read_b128 v[192:195], v134 offset:33792
	ds_read_b128 v[196:199], v137 offset:32768
	ds_read_b128 v[200:203], v137 offset:33792
	ds_read_b128 v[204:207], v139 offset:32768
	ds_read_b128 v[208:211], v139 offset:33792
	s_nop 0
	v_lshl_add_u64 v[146:147], s[50:51], 0, v[0:1]
	global_load_lds_dwordx4 v[146:147], off
	v_lshl_add_u64 v[146:147], s[50:51], 0, v[140:141]
	s_mov_b32 m0, s29
	s_nop 0
	global_load_lds_dwordx4 v[146:147], off
	s_waitcnt lgkmcnt(8)
	s_barrier
	s_waitcnt lgkmcnt(0)
	s_waitcnt lgkmcnt(0)
	v_mfma_f32_16x16x32_bf16 v[126:129], v[164:167], v[148:151], v[126:129]
	v_mfma_f32_16x16x32_bf16 v[122:125], v[164:167], v[156:159], v[122:125]
	v_mfma_f32_16x16x32_bf16 v[118:121], v[188:191], v[148:151], v[118:121]
	v_mfma_f32_16x16x32_bf16 v[114:117], v[188:191], v[156:159], v[114:117]
	v_mfma_f32_16x16x32_bf16 v[110:113], v[196:199], v[148:151], v[110:113]
	v_mfma_f32_16x16x32_bf16 v[106:109], v[196:199], v[156:159], v[106:109]
	v_mfma_f32_16x16x32_bf16 v[102:105], v[204:207], v[148:151], v[102:105]
	v_mfma_f32_16x16x32_bf16 v[98:101], v[204:207], v[156:159], v[98:101]
	v_mfma_f32_16x16x32_bf16 v[126:129], v[184:187], v[152:155], v[126:129]
	v_mfma_f32_16x16x32_bf16 v[122:125], v[184:187], v[160:163], v[122:125]
	v_mfma_f32_16x16x32_bf16 v[118:121], v[192:195], v[152:155], v[118:121]
	v_mfma_f32_16x16x32_bf16 v[114:117], v[192:195], v[160:163], v[114:117]
	v_mfma_f32_16x16x32_bf16 v[110:113], v[200:203], v[152:155], v[110:113]
	v_mfma_f32_16x16x32_bf16 v[106:109], v[200:203], v[160:163], v[106:109]
	v_mfma_f32_16x16x32_bf16 v[102:105], v[208:211], v[152:155], v[102:105]
	v_mfma_f32_16x16x32_bf16 v[98:101], v[208:211], v[160:163], v[98:101]
	s_barrier
	s_add_u32 s50, s44, 0x180
	v_add_u32_e32 v146, s78, v142
	s_addc_u32 s51, s45, 0
	s_mov_b32 m0, s8
	ds_read_b128 v[212:215], v146
	ds_read_b128 v[216:219], v146 offset:1024
	ds_read_b128 v[220:223], v146 offset:2048
	ds_read_b128 v[224:227], v146 offset:3072
	s_nop 0
	v_lshl_add_u64 v[228:229], s[50:51], 0, v[0:1]
	global_load_lds_dwordx4 v[228:229], off
	v_lshl_add_u64 v[228:229], s[50:51], 0, v[140:141]
	s_mov_b32 m0, s9
	s_nop 0
	global_load_lds_dwordx4 v[228:229], off
	s_barrier
	s_waitcnt lgkmcnt(0)
	s_waitcnt lgkmcnt(0)
	v_mfma_f32_16x16x32_bf16 v[94:97], v[164:167], v[212:215], v[94:97]
	v_mfma_f32_16x16x32_bf16 v[90:93], v[164:167], v[220:223], v[90:93]
	v_mfma_f32_16x16x32_bf16 v[86:89], v[188:191], v[212:215], v[86:89]
	v_mfma_f32_16x16x32_bf16 v[82:85], v[188:191], v[220:223], v[82:85]
	v_mfma_f32_16x16x32_bf16 v[78:81], v[196:199], v[212:215], v[78:81]
	v_mfma_f32_16x16x32_bf16 v[74:77], v[196:199], v[220:223], v[74:77]
	v_mfma_f32_16x16x32_bf16 v[70:73], v[204:207], v[212:215], v[70:73]
	v_mfma_f32_16x16x32_bf16 v[66:69], v[204:207], v[220:223], v[66:69]
	v_mfma_f32_16x16x32_bf16 v[94:97], v[184:187], v[216:219], v[94:97]
	v_mfma_f32_16x16x32_bf16 v[90:93], v[184:187], v[224:227], v[90:93]
	v_mfma_f32_16x16x32_bf16 v[86:89], v[192:195], v[216:219], v[86:89]
	v_mfma_f32_16x16x32_bf16 v[82:85], v[192:195], v[224:227], v[82:85]
	v_mfma_f32_16x16x32_bf16 v[78:81], v[200:203], v[216:219], v[78:81]
	v_mfma_f32_16x16x32_bf16 v[74:77], v[200:203], v[224:227], v[74:77]
	v_mfma_f32_16x16x32_bf16 v[70:73], v[208:211], v[216:219], v[70:73]
	v_mfma_f32_16x16x32_bf16 v[66:69], v[208:211], v[224:227], v[66:69]
	s_add_u32 s42, s42, 0x180
	s_addc_u32 s43, s43, 0
	s_mov_b32 m0, s18
	s_barrier
	ds_read_b128 v[164:167], v133 offset:49152
	ds_read_b128 v[184:187], v133 offset:50176
	ds_read_b128 v[188:191], v134 offset:49152
	ds_read_b128 v[192:195], v134 offset:50176
	ds_read_b128 v[196:199], v137 offset:49152
	ds_read_b128 v[200:203], v137 offset:50176
	ds_read_b128 v[204:207], v139 offset:49152
	ds_read_b128 v[208:211], v139 offset:50176
	s_nop 0
	v_lshl_add_u64 v[228:229], s[42:43], 0, v[0:1]
	global_load_lds_dwordx4 v[228:229], off
	v_lshl_add_u64 v[228:229], s[42:43], 0, v[140:141]
	s_mov_b32 m0, s19
	s_nop 0
	global_load_lds_dwordx4 v[228:229], off
	s_barrier
; #define LDA(dst, b, h) for (int m = 0; m < 4; ++m) for (int k = 0; k < 2; ++k) \
;     dst[m][k] = *reinterpret_cast<const bf16x8*>((char*)SA(b, h) + lds_byte(wr * 64 + m * 16 + fr, k * 32 + fq * 8))
; #define LDB(dst, b, h) for (int n = 0; n < 2; ++n) for (int k = 0; k < 2; ++k) \
;     dst[n][k] = *reinterpret_cast<const bf16x8*>((char*)SB(b, h) + lds_byte(wc * 32 + n * 16 + fr, k * 32 + fq * 8))
; #define MMA(ai, bj, At, Bt_) do { __builtin_amdgcn_s_setprio(1); \
;     for (int m = 0; m < 4; ++m) for (int n = 0; n < 2; ++n) for (int k = 0; k < 2; ++k) \
;       acc[ai][bj][m][n] = __builtin_amdgcn_mfma_f32_16x16x32_bf16(At[m][k], Bt_[n][k], acc[ai][bj][m][n], 0, 0, 0); \
;     __builtin_amdgcn_s_setprio(0); } while (0)
; #define WAIT_V(n) asm volatile("s_waitcnt vmcnt(" #n ")" ::: "memory")
; #define WAIT_L(n) asm volatile("s_waitcnt lgkmcnt(" #n ")" ::: "memory")
; #define BAR __builtin_amdgcn_s_barrier()
; #define SCHED __builtin_amdgcn_sched_barrier(0)
;     ...
;       BAR; WAIT_L(0); MMA(1, 0, At, B0); BAR; SCHED;
;       STAGE(SB(1, 1), Bt, bcol + HALF, t + 3);
;       WAIT_V(6); BAR; MMA(1, 1, At, B1); BAR;
;     }
;     { LDB(B0, 0, 0); LDA(At, 0, 0); STAGE(SA(1, 1), A, brow + HALF, nt - 1);
;       BAR; WAIT_L(0); MMA(0, 0, At, B0); BAR;
;       LDB(B1, 0, 1); BAR; WAIT_L(0); MMA(0, 1, At, B1); BAR;
	s_waitcnt lgkmcnt(0)
	s_waitcnt lgkmcnt(0)
	v_mfma_f32_16x16x32_bf16 v[62:65], v[164:167], v[148:151], v[62:65]
	v_mfma_f32_16x16x32_bf16 v[58:61], v[164:167], v[156:159], v[58:61]
	v_mfma_f32_16x16x32_bf16 v[54:57], v[188:191], v[148:151], v[54:57]
	v_mfma_f32_16x16x32_bf16 v[50:53], v[188:191], v[156:159], v[50:53]
	v_mfma_f32_16x16x32_bf16 v[46:49], v[196:199], v[148:151], v[46:49]
	v_mfma_f32_16x16x32_bf16 v[42:45], v[196:199], v[156:159], v[42:45]
	v_mfma_f32_16x16x32_bf16 v[38:41], v[204:207], v[148:151], v[38:41]
	v_mfma_f32_16x16x32_bf16 v[34:37], v[204:207], v[156:159], v[34:37]
	v_mfma_f32_16x16x32_bf16 v[62:65], v[184:187], v[152:155], v[62:65]
	v_mfma_f32_16x16x32_bf16 v[58:61], v[184:187], v[160:163], v[58:61]
	v_mfma_f32_16x16x32_bf16 v[54:57], v[192:195], v[152:155], v[54:57]
	v_mfma_f32_16x16x32_bf16 v[50:53], v[192:195], v[160:163], v[50:53]
	v_mfma_f32_16x16x32_bf16 v[46:49], v[200:203], v[152:155], v[46:49]
	v_mfma_f32_16x16x32_bf16 v[42:45], v[200:203], v[160:163], v[42:45]
	v_mfma_f32_16x16x32_bf16 v[38:41], v[208:211], v[152:155], v[38:41]
	v_mfma_f32_16x16x32_bf16 v[34:37], v[208:211], v[160:163], v[34:37]
	s_barrier
	s_add_u32 s42, s44, 0x80180
	s_addc_u32 s43, s45, 0
	s_mov_b32 m0, s20
	s_nop 0
	v_lshl_add_u64 v[148:149], s[42:43], 0, v[0:1]
	global_load_lds_dwordx4 v[148:149], off
	v_lshl_add_u64 v[148:149], s[42:43], 0, v[140:141]
	s_mov_b32 m0, s21
	s_nop 0
	global_load_lds_dwordx4 v[148:149], off
	s_waitcnt vmcnt(6)
	s_barrier
	v_mfma_f32_16x16x32_bf16 v[30:33], v[164:167], v[212:215], v[30:33]
	v_mfma_f32_16x16x32_bf16 v[26:29], v[164:167], v[220:223], v[26:29]
	v_mfma_f32_16x16x32_bf16 v[22:25], v[188:191], v[212:215], v[22:25]
	v_mfma_f32_16x16x32_bf16 v[18:21], v[188:191], v[220:223], v[18:21]
	v_mfma_f32_16x16x32_bf16 v[14:17], v[196:199], v[212:215], v[14:17]
	v_mfma_f32_16x16x32_bf16 v[10:13], v[196:199], v[220:223], v[10:13]
	v_mfma_f32_16x16x32_bf16 v[6:9], v[204:207], v[212:215], v[6:9]
	v_mfma_f32_16x16x32_bf16 v[2:5], v[204:207], v[220:223], v[2:5]
	v_mfma_f32_16x16x32_bf16 v[30:33], v[184:187], v[216:219], v[30:33]
	v_mfma_f32_16x16x32_bf16 v[26:29], v[184:187], v[224:227], v[26:29]
	v_mfma_f32_16x16x32_bf16 v[22:25], v[192:195], v[216:219], v[22:25]
	v_mfma_f32_16x16x32_bf16 v[18:21], v[192:195], v[224:227], v[18:21]
	v_mfma_f32_16x16x32_bf16 v[14:17], v[200:203], v[216:219], v[14:17]
	v_mfma_f32_16x16x32_bf16 v[10:13], v[200:203], v[224:227], v[10:13]
	v_mfma_f32_16x16x32_bf16 v[6:9], v[208:211], v[216:219], v[6:9]
	v_mfma_f32_16x16x32_bf16 v[2:5], v[208:211], v[224:227], v[2:5]
	s_add_i32 s36, s36, 2
	s_add_u32 s6, s6, 0x100
	s_addc_u32 s7, s7, 0
	s_cmp_gt_u32 s36, 27
	s_barrier
	s_cbranch_scc0 .LBB0_418
	s_setprio 0
	s_add_u32 s4, s4, 0xf80
	s_addc_u32 s5, s5, 0
	s_mov_b32 m0, s41
	ds_read_b128 v[148:151], v143
	ds_read_b128 v[152:155], v143 offset:1024
	ds_read_b128 v[156:159], v143 offset:2048
	ds_read_b128 v[160:163], v143 offset:3072
	ds_read_b128 v[164:167], v133
	ds_read_b128 v[184:187], v133 offset:1024
	ds_read_b128 v[188:191], v134
	ds_read_b128 v[192:195], v134 offset:1024
	ds_read_b128 v[196:199], v137
	ds_read_b128 v[200:203], v137 offset:1024
	ds_read_b128 v[204:207], v139
	ds_read_b128 v[208:211], v139 offset:1024
	s_nop 0
	v_lshl_add_u64 v[142:143], s[4:5], 0, v[0:1]
	global_load_lds_dwordx4 v[142:143], off
	v_lshl_add_u64 v[140:141], s[4:5], 0, v[140:141]
	s_mov_b32 m0, s37
	s_nop 0
	global_load_lds_dwordx4 v[140:141], off
	s_barrier
	s_waitcnt lgkmcnt(0)
	s_setprio 1
	s_waitcnt lgkmcnt(0)
	v_mfma_f32_16x16x32_bf16 v[126:129], v[164:167], v[148:151], v[126:129]
	v_mfma_f32_16x16x32_bf16 v[122:125], v[164:167], v[156:159], v[122:125]
	v_mfma_f32_16x16x32_bf16 v[118:121], v[188:191], v[148:151], v[118:121]
	v_mfma_f32_16x16x32_bf16 v[110:113], v[196:199], v[148:151], v[110:113]
	v_mfma_f32_16x16x32_bf16 v[106:109], v[196:199], v[156:159], v[106:109]
	v_mfma_f32_16x16x32_bf16 v[102:105], v[204:207], v[148:151], v[102:105]
	v_mfma_f32_16x16x32_bf16 v[98:101], v[204:207], v[156:159], v[98:101]
	v_mfma_f32_16x16x32_bf16 v[126:129], v[184:187], v[152:155], v[126:129]
	v_mfma_f32_16x16x32_bf16 v[122:125], v[184:187], v[160:163], v[122:125]
	v_mfma_f32_16x16x32_bf16 v[118:121], v[192:195], v[152:155], v[118:121]
	v_mfma_f32_16x16x32_bf16 v[114:117], v[188:191], v[156:159], v[114:117]
	v_mfma_f32_16x16x32_bf16 v[110:113], v[200:203], v[152:155], v[110:113]
	v_mfma_f32_16x16x32_bf16 v[106:109], v[200:203], v[160:163], v[106:109]
	v_mfma_f32_16x16x32_bf16 v[102:105], v[208:211], v[152:155], v[102:105]
	v_mfma_f32_16x16x32_bf16 v[98:101], v[208:211], v[160:163], v[98:101]
	v_mfma_f32_16x16x32_bf16 v[140:143], v[192:195], v[160:163], v[114:117]
	s_setprio 0
	s_barrier
	s_nop 0
	ds_read_b128 v[114:117], v144
	ds_read_b128 v[212:215], v144 offset:1024
	ds_read_b128 v[216:219], v144 offset:2048
	ds_read_b128 v[220:223], v144 offset:3072
	s_barrier
	s_waitcnt lgkmcnt(0)
	s_setprio 1
	s_waitcnt lgkmcnt(0)
	v_mfma_f32_16x16x32_bf16 v[90:93], v[164:167], v[216:219], v[90:93]
	v_mfma_f32_16x16x32_bf16 v[86:89], v[188:191], v[114:117], v[86:89]
	v_mfma_f32_16x16x32_bf16 v[94:97], v[164:167], v[114:117], v[94:97]
	v_mfma_f32_16x16x32_bf16 v[90:93], v[184:187], v[220:223], v[90:93]
	v_mfma_f32_16x16x32_bf16 v[86:89], v[192:195], v[212:215], v[86:89]
	v_mfma_f32_16x16x32_bf16 v[82:85], v[188:191], v[216:219], v[82:85]
	v_mfma_f32_16x16x32_bf16 v[78:81], v[196:199], v[114:117], v[78:81]
	v_mfma_f32_16x16x32_bf16 v[74:77], v[196:199], v[216:219], v[74:77]
	v_mfma_f32_16x16x32_bf16 v[70:73], v[204:207], v[114:117], v[70:73]
	v_mfma_f32_16x16x32_bf16 v[66:69], v[204:207], v[216:219], v[66:69]
	v_mfma_f32_16x16x32_bf16 v[224:227], v[184:187], v[212:215], v[94:97]
	v_mfma_f32_16x16x32_bf16 v[164:167], v[192:195], v[220:223], v[82:85]
	v_mfma_f32_16x16x32_bf16 v[184:187], v[200:203], v[212:215], v[78:81]
	v_mfma_f32_16x16x32_bf16 v[188:191], v[200:203], v[220:223], v[74:77]
	v_mfma_f32_16x16x32_bf16 v[192:195], v[208:211], v[212:215], v[70:73]
	v_mfma_f32_16x16x32_bf16 v[196:199], v[208:211], v[220:223], v[66:69]
	s_setprio 0
	s_barrier
; #define LDA(dst, b, h) for (int m = 0; m < 4; ++m) for (int k = 0; k < 2; ++k) \
;     dst[m][k] = *reinterpret_cast<const bf16x8*>((char*)SA(b, h) + lds_byte(wr * 64 + m * 16 + fr, k * 32 + fq * 8))
; #define LDB(dst, b, h) for (int n = 0; n < 2; ++n) for (int k = 0; k < 2; ++k) \
;     dst[n][k] = *reinterpret_cast<const bf16x8*>((char*)SB(b, h) + lds_byte(wc * 32 + n * 16 + fr, k * 32 + fq * 8))
; #define MMA(ai, bj, At, Bt_) do { __builtin_amdgcn_s_setprio(1); \
;     for (int m = 0; m < 4; ++m) for (int n = 0; n < 2; ++n) for (int k = 0; k < 2; ++k) \
;       acc[ai][bj][m][n] = __builtin_amdgcn_mfma_f32_16x16x32_bf16(At[m][k], Bt_[n][k], acc[ai][bj][m][n], 0, 0, 0); \
;     __builtin_amdgcn_s_setprio(0); } while (0)
; #define WAIT_V(n) asm volatile("s_waitcnt vmcnt(" #n ")" ::: "memory")
; #define WAIT_L(n) asm volatile("s_waitcnt lgkmcnt(" #n ")" ::: "memory")
; #define BAR __builtin_amdgcn_s_barrier()
;     ...
;       LDA(At, 0, 1); WAIT_V(4); BAR; WAIT_L(0); MMA(1, 0, At, B0); MMA(1, 1, At, B1); BAR; }
;     { LDB(B0, 1, 0); LDA(At, 1, 0); WAIT_V(2); BAR; WAIT_L(0); MMA(0, 0, At, B0); BAR;
	s_nop 0
	ds_read_b128 v[66:69], v133 offset:16384
	ds_read_b128 v[70:73], v133 offset:17408
	ds_read_b128 v[74:77], v134 offset:16384
	ds_read_b128 v[78:81], v134 offset:17408
	ds_read_b128 v[82:85], v137 offset:16384
	ds_read_b128 v[94:97], v137 offset:17408
	ds_read_b128 v[200:203], v139 offset:16384
	ds_read_b128 v[204:207], v139 offset:17408
	s_waitcnt vmcnt(4)
	s_barrier
	s_waitcnt lgkmcnt(0)
	s_setprio 1
	s_waitcnt lgkmcnt(0)
	v_mfma_f32_16x16x32_bf16 v[62:65], v[66:69], v[148:151], v[62:65]
	v_mfma_f32_16x16x32_bf16 v[58:61], v[66:69], v[156:159], v[58:61]
	v_mfma_f32_16x16x32_bf16 v[54:57], v[74:77], v[148:151], v[54:57]
	v_mfma_f32_16x16x32_bf16 v[50:53], v[74:77], v[156:159], v[50:53]
	v_mfma_f32_16x16x32_bf16 v[46:49], v[82:85], v[148:151], v[46:49]
	v_mfma_f32_16x16x32_bf16 v[42:45], v[82:85], v[156:159], v[42:45]
	v_mfma_f32_16x16x32_bf16 v[38:41], v[200:203], v[148:151], v[38:41]
	v_mfma_f32_16x16x32_bf16 v[34:37], v[200:203], v[156:159], v[34:37]
	v_mfma_f32_16x16x32_bf16 v[62:65], v[70:73], v[152:155], v[62:65]
	v_mfma_f32_16x16x32_bf16 v[58:61], v[70:73], v[160:163], v[58:61]
	v_mfma_f32_16x16x32_bf16 v[54:57], v[78:81], v[152:155], v[54:57]
	v_mfma_f32_16x16x32_bf16 v[50:53], v[78:81], v[160:163], v[50:53]
	v_mfma_f32_16x16x32_bf16 v[46:49], v[94:97], v[152:155], v[46:49]
	v_mfma_f32_16x16x32_bf16 v[42:45], v[94:97], v[160:163], v[42:45]
	v_mfma_f32_16x16x32_bf16 v[38:41], v[204:207], v[152:155], v[38:41]
	v_mfma_f32_16x16x32_bf16 v[34:37], v[204:207], v[160:163], v[34:37]
	s_setprio 0
	s_setprio 1
	v_mfma_f32_16x16x32_bf16 v[30:33], v[66:69], v[114:117], v[30:33]
	v_mfma_f32_16x16x32_bf16 v[26:29], v[66:69], v[216:219], v[26:29]
	v_mfma_f32_16x16x32_bf16 v[22:25], v[74:77], v[114:117], v[22:25]
	v_mfma_f32_16x16x32_bf16 v[18:21], v[74:77], v[216:219], v[18:21]
	v_mfma_f32_16x16x32_bf16 v[14:17], v[82:85], v[114:117], v[14:17]
	v_mfma_f32_16x16x32_bf16 v[10:13], v[82:85], v[216:219], v[10:13]
	v_mfma_f32_16x16x32_bf16 v[6:9], v[200:203], v[114:117], v[6:9]
	v_mfma_f32_16x16x32_bf16 v[2:5], v[200:203], v[216:219], v[2:5]
	v_mfma_f32_16x16x32_bf16 v[148:151], v[70:73], v[212:215], v[30:33]
	v_mfma_f32_16x16x32_bf16 v[152:155], v[70:73], v[220:223], v[26:29]
	v_mfma_f32_16x16x32_bf16 v[156:159], v[78:81], v[212:215], v[22:25]
	v_mfma_f32_16x16x32_bf16 v[160:163], v[78:81], v[220:223], v[18:21]
	v_mfma_f32_16x16x32_bf16 v[208:211], v[94:97], v[212:215], v[14:17]
	v_mfma_f32_16x16x32_bf16 v[228:231], v[94:97], v[220:223], v[10:13]
	v_mfma_f32_16x16x32_bf16 v[212:215], v[204:207], v[212:215], v[6:9]
	v_mfma_f32_16x16x32_bf16 v[200:203], v[204:207], v[220:223], v[2:5]
	s_setprio 0
	s_barrier
	ds_read_b128 v[14:17], v145
	ds_read_b128 v[30:33], v145 offset:1024
	ds_read_b128 v[204:207], v145 offset:2048
	ds_read_b128 v[216:219], v145 offset:3072
	ds_read_b128 v[2:5], v133 offset:32768
	ds_read_b128 v[6:9], v133 offset:33792
	ds_read_b128 v[10:13], v134 offset:32768
	ds_read_b128 v[18:21], v134 offset:33792
	ds_read_b128 v[22:25], v137 offset:32768
	ds_read_b128 v[26:29], v137 offset:33792
	ds_read_b128 v[220:223], v139 offset:32768
	ds_read_b128 v[232:235], v139 offset:33792
	s_waitcnt vmcnt(2)
	s_barrier
	s_waitcnt lgkmcnt(0)
	s_setprio 1
	s_waitcnt lgkmcnt(0)
	v_mfma_f32_16x16x32_bf16 v[66:69], v[2:5], v[14:17], v[126:129]
	v_mfma_f32_16x16x32_bf16 v[114:117], v[6:9], v[30:33], v[66:69]
	v_mfma_f32_16x16x32_bf16 v[66:69], v[2:5], v[204:207], v[122:125]
	v_mfma_f32_16x16x32_bf16 v[126:129], v[6:9], v[216:219], v[66:69]
	v_mfma_f32_16x16x32_bf16 v[66:69], v[10:13], v[14:17], v[118:121]
	v_mfma_f32_16x16x32_bf16 v[82:85], v[18:21], v[30:33], v[66:69]
	v_mfma_f32_16x16x32_bf16 v[66:69], v[10:13], v[204:207], v[140:143]
	v_mfma_f32_16x16x32_bf16 v[94:97], v[18:21], v[216:219], v[66:69]
	v_mfma_f32_16x16x32_bf16 v[66:69], v[22:25], v[14:17], v[110:113]
	v_mfma_f32_16x16x32_bf16 v[74:77], v[26:29], v[30:33], v[66:69]
	v_mfma_f32_16x16x32_bf16 v[66:69], v[22:25], v[204:207], v[106:109]
	v_mfma_f32_16x16x32_bf16 v[78:81], v[26:29], v[216:219], v[66:69]
	v_mfma_f32_16x16x32_bf16 v[66:69], v[220:223], v[14:17], v[102:105]
	v_mfma_f32_16x16x32_bf16 v[70:73], v[220:223], v[204:207], v[98:101]
	v_mfma_f32_16x16x32_bf16 v[66:69], v[232:235], v[30:33], v[66:69]
	v_mfma_f32_16x16x32_bf16 v[70:73], v[232:235], v[216:219], v[70:73]
	s_setprio 0
	s_barrier
; #define LDA(dst, b, h) for (int m = 0; m < 4; ++m) for (int k = 0; k < 2; ++k) \
;     dst[m][k] = *reinterpret_cast<const bf16x8*>((char*)SA(b, h) + lds_byte(wr * 64 + m * 16 + fr, k * 32 + fq * 8))
; #define LDB(dst, b, h) for (int n = 0; n < 2; ++n) for (int k = 0; k < 2; ++k) \
;     dst[n][k] = *reinterpret_cast<const bf16x8*>((char*)SB(b, h) + lds_byte(wc * 32 + n * 16 + fr, k * 32 + fq * 8))
; #define MMA(ai, bj, At, Bt_) do { __builtin_amdgcn_s_setprio(1); \
;     for (int m = 0; m < 4; ++m) for (int n = 0; n < 2; ++n) for (int k = 0; k < 2; ++k) \
;       acc[ai][bj][m][n] = __builtin_amdgcn_mfma_f32_16x16x32_bf16(At[m][k], Bt_[n][k], acc[ai][bj][m][n], 0, 0, 0); \
;     __builtin_amdgcn_s_setprio(0); } while (0)
; #define WAIT_V(n) asm volatile("s_waitcnt vmcnt(" #n ")" ::: "memory")
; #define WAIT_L(n) asm volatile("s_waitcnt lgkmcnt(" #n ")" ::: "memory")
; #define BAR __builtin_amdgcn_s_barrier()
;     ...
;       LDB(B1, 1, 1); WAIT_V(0); BAR; WAIT_L(0); MMA(0, 1, At, B1); BAR;
;       LDA(At, 1, 1); BAR; WAIT_L(0); MMA(1, 0, At, B0); MMA(1, 1, At, B1); BAR; }
;     if (wr == 0) BAR;
	ds_read_b128 v[140:143], v146
	ds_read_b128 v[236:239], v146 offset:1024
	ds_read_b128 v[240:243], v146 offset:2048
	ds_read_b128 v[144:147], v146 offset:3072
	s_waitcnt vmcnt(0)
	s_barrier
	s_waitcnt lgkmcnt(0)
	s_setprio 1
	s_waitcnt lgkmcnt(0)
	v_mfma_f32_16x16x32_bf16 v[98:101], v[2:5], v[140:143], v[224:227]
	v_mfma_f32_16x16x32_bf16 v[2:5], v[2:5], v[240:243], v[90:93]
	v_mfma_f32_16x16x32_bf16 v[118:121], v[6:9], v[144:147], v[2:5]
	v_mfma_f32_16x16x32_bf16 v[2:5], v[10:13], v[140:143], v[86:89]
	v_mfma_f32_16x16x32_bf16 v[102:105], v[18:21], v[236:239], v[2:5]
	v_mfma_f32_16x16x32_bf16 v[2:5], v[10:13], v[240:243], v[164:167]
	v_mfma_f32_16x16x32_bf16 v[122:125], v[18:21], v[144:147], v[2:5]
	v_mfma_f32_16x16x32_bf16 v[2:5], v[22:25], v[140:143], v[184:187]
	v_mfma_f32_16x16x32_bf16 v[90:93], v[26:29], v[236:239], v[2:5]
	v_mfma_f32_16x16x32_bf16 v[2:5], v[22:25], v[240:243], v[188:191]
	v_mfma_f32_16x16x32_bf16 v[110:113], v[26:29], v[144:147], v[2:5]
	v_mfma_f32_16x16x32_bf16 v[2:5], v[220:223], v[140:143], v[192:195]
	v_mfma_f32_16x16x32_bf16 v[86:89], v[232:235], v[236:239], v[2:5]
	v_mfma_f32_16x16x32_bf16 v[2:5], v[220:223], v[240:243], v[196:199]
	v_mfma_f32_16x16x32_bf16 v[98:101], v[6:9], v[236:239], v[98:101]
	v_mfma_f32_16x16x32_bf16 v[106:109], v[232:235], v[144:147], v[2:5]
	s_setprio 0
	s_barrier
	ds_read_b128 v[164:167], v133 offset:49152
	ds_read_b128 v[184:187], v133 offset:50176
	ds_read_b128 v[188:191], v134 offset:49152
	ds_read_b128 v[192:195], v134 offset:50176
	ds_read_b128 v[196:199], v137 offset:49152
	ds_read_b128 v[220:223], v137 offset:50176
	ds_read_b128 v[224:227], v139 offset:49152
	ds_read_b128 v[232:235], v139 offset:50176
	s_barrier
	s_waitcnt lgkmcnt(0)
	s_setprio 1
	s_waitcnt lgkmcnt(0)
	v_mfma_f32_16x16x32_bf16 v[6:9], v[164:167], v[204:207], v[58:61]
	v_mfma_f32_16x16x32_bf16 v[10:13], v[188:191], v[204:207], v[50:53]
	v_mfma_f32_16x16x32_bf16 v[2:5], v[164:167], v[14:17], v[62:65]
	v_mfma_f32_16x16x32_bf16 v[18:21], v[184:187], v[216:219], v[6:9]
	v_mfma_f32_16x16x32_bf16 v[6:9], v[188:191], v[14:17], v[54:57]
	v_mfma_f32_16x16x32_bf16 v[22:25], v[192:195], v[216:219], v[10:13]
	v_mfma_f32_16x16x32_bf16 v[10:13], v[196:199], v[14:17], v[46:49]
	v_mfma_f32_16x16x32_bf16 v[14:17], v[224:227], v[14:17], v[38:41]
	v_mfma_f32_16x16x32_bf16 v[2:5], v[184:187], v[30:33], v[2:5]
	v_mfma_f32_16x16x32_bf16 v[6:9], v[192:195], v[30:33], v[6:9]
	v_mfma_f32_16x16x32_bf16 v[10:13], v[220:223], v[30:33], v[10:13]
	v_mfma_f32_16x16x32_bf16 v[26:29], v[196:199], v[204:207], v[42:45]
	v_mfma_f32_16x16x32_bf16 v[14:17], v[232:235], v[30:33], v[14:17]
	v_mfma_f32_16x16x32_bf16 v[30:33], v[224:227], v[204:207], v[34:37]
	v_mfma_f32_16x16x32_bf16 v[26:29], v[220:223], v[216:219], v[26:29]
	v_mfma_f32_16x16x32_bf16 v[30:33], v[232:235], v[216:219], v[30:33]
	s_setprio 0
	s_setprio 1
	v_mfma_f32_16x16x32_bf16 v[38:41], v[164:167], v[240:243], v[152:155]
	v_mfma_f32_16x16x32_bf16 v[42:45], v[188:191], v[240:243], v[160:163]
	v_mfma_f32_16x16x32_bf16 v[46:49], v[196:199], v[240:243], v[228:231]
	v_mfma_f32_16x16x32_bf16 v[34:37], v[164:167], v[140:143], v[148:151]
	v_mfma_f32_16x16x32_bf16 v[50:53], v[184:187], v[144:147], v[38:41]
	v_mfma_f32_16x16x32_bf16 v[38:41], v[188:191], v[140:143], v[156:159]
	v_mfma_f32_16x16x32_bf16 v[54:57], v[192:195], v[144:147], v[42:45]
	v_mfma_f32_16x16x32_bf16 v[42:45], v[196:199], v[140:143], v[208:211]
	v_mfma_f32_16x16x32_bf16 v[58:61], v[220:223], v[144:147], v[46:49]
	v_mfma_f32_16x16x32_bf16 v[46:49], v[224:227], v[140:143], v[212:215]
	v_mfma_f32_16x16x32_bf16 v[62:65], v[224:227], v[240:243], v[200:203]
	v_mfma_f32_16x16x32_bf16 v[34:37], v[184:187], v[236:239], v[34:37]
	v_mfma_f32_16x16x32_bf16 v[38:41], v[192:195], v[236:239], v[38:41]
	v_mfma_f32_16x16x32_bf16 v[42:45], v[220:223], v[236:239], v[42:45]
	v_mfma_f32_16x16x32_bf16 v[46:49], v[232:235], v[236:239], v[46:49]
	v_mfma_f32_16x16x32_bf16 v[62:65], v[232:235], v[144:147], v[62:65]
	s_setprio 0
	v_readlane_b32 s4, v245, 33
	v_readlane_b32 s5, v245, 34
	s_and_b64 vcc, exec, s[4:5]
	s_barrier
	s_cbranch_vccz .LBB0_421
	s_barrier
